# DSA attention core rewritten by hand: K/V gathered straight into a per-wave LDS ring by LDS-DMA (XOR-swizzled), QK via ds_read_b128, PV via ds_read_b64_tr_b16; same arithmetic order, bit-identical out
# speedup vs baseline: 1.0106x; 1.0106x over previous
.LBB0_470:
	s_waitcnt lgkmcnt(0)
	s_barrier
	v_readlane_b32 s20, v254, 30
	v_readlane_b32 s21, v254, 31
	v_readlane_b32 s22, v253, 1
	v_readlane_b32 s2, v254, 17
	v_readlane_b32 s3, v254, 18
	v_readlane_b32 s4, v254, 23
	v_readlane_b32 s5, v254, 24
	v_readlane_b32 s6, v254, 15
	v_readlane_b32 s7, v254, 16
	s_lshl_b32 s23, s20, 19
	s_add_u32 s2, s2, s23
	s_addc_u32 s3, s3, 0
	s_add_u32 s4, s4, s23
	s_addc_u32 s5, s5, 0
	s_lshl_b32 s8, s22, 14
	s_lshl_b32 s12, s22, 1
	s_add_i32 s12, s12, s21
	s_lshl_b32 s14, s22, 10
	s_min_i32 s9, s61, 0x100
	s_lshr_b32 s10, s9, 6
	s_mov_b32 s11, 0
	v_and_b32_e32 v165, 15, v221
	v_bfe_u32 v166, v221, 4, 2
	v_lshlrev_b32_e32 v167, 2, v166
	v_xor_b32_e32 v167, v165, v167
	v_lshlrev_b32_e32 v10, 4, v167
	v_xor_b32_e32 v168, 1, v167
	v_lshlrev_b32_e32 v11, 4, v168
	v_xor_b32_e32 v168, 2, v167
	v_lshlrev_b32_e32 v12, 4, v168
	v_xor_b32_e32 v168, 3, v167
	v_lshlrev_b32_e32 v13, 4, v168
	v_lshlrev_b32_e32 v156, 1, v166
	v_add_u32_e32 v156, 0x20000, v156
	v_and_b32_e32 v167, 7, v165
	v_lshlrev_b32_e32 v167, 8, v167
	v_lshl_add_u32 v157, v166, 4, v167
	v_and_b32_e32 v167, 3, v165
	v_lshlrev_b32_e32 v167, 2, v167
	v_bfe_u32 v168, v165, 2, 2
	v_or_b32_e32 v167, v167, v168
	v_lshlrev_b32_e32 v170, 8, v165
	v_add_u32_e32 v170, s8, v170
	v_mov_b32_e32 v168, v166
	v_xor_b32_e32 v168, v168, v167
	v_lshl_add_u32 v18, v168, 4, v170
	v_or_b32_e32 v168, 4, v166
	v_xor_b32_e32 v168, v168, v167
	v_lshl_add_u32 v19, v168, 4, v170
	v_or_b32_e32 v168, 8, v166
	v_xor_b32_e32 v168, v168, v167
	v_lshl_add_u32 v20, v168, 4, v170
	v_or_b32_e32 v168, 12, v166
	v_xor_b32_e32 v168, v168, v167
	v_lshl_add_u32 v21, v168, 4, v170
	v_lshrrev_b32_e32 v170, 2, v165
	v_and_b32_e32 v171, 3, v165
	v_lshl_add_u32 v172, v166, 2, v170
	v_lshl_add_u32 v173, v170, 2, v166
	v_lshlrev_b32_e32 v172, 8, v172
	v_and_b32_e32 v167, 1, v171
	v_lshl_add_u32 v172, v167, 3, v172
	v_add_u32_e32 v172, s8, v172
	v_lshrrev_b32_e32 v167, 1, v171
	v_xor_b32_e32 v168, v167, v173
	v_lshl_add_u32 v148, v168, 4, v172
	v_or_b32_e32 v168, 2, v167
	v_xor_b32_e32 v168, v168, v173
	v_lshl_add_u32 v149, v168, 4, v172
	v_or_b32_e32 v168, 4, v167
	v_xor_b32_e32 v168, v168, v173
	v_lshl_add_u32 v150, v168, 4, v172
	v_or_b32_e32 v168, 6, v167
	v_xor_b32_e32 v168, v168, v173
	v_lshl_add_u32 v151, v168, 4, v172
	v_or_b32_e32 v168, 8, v167
	v_xor_b32_e32 v168, v168, v173
	v_lshl_add_u32 v152, v168, 4, v172
	v_or_b32_e32 v168, 10, v167
	v_xor_b32_e32 v168, v168, v173
	v_lshl_add_u32 v153, v168, 4, v172
	v_or_b32_e32 v168, 12, v167
	v_xor_b32_e32 v168, v168, v173
	v_lshl_add_u32 v154, v168, 4, v172
	v_or_b32_e32 v168, 14, v167
	v_xor_b32_e32 v168, v168, v173
	v_lshl_add_u32 v155, v168, 4, v172
	v_lshlrev_b32_e32 v158, 10, v166
	v_lshl_add_u32 v158, v165, 1, v158
	v_add_u32_e32 v158, s8, v158
	v_add_u32_e32 v158, 0x2000, v158
	v_lshlrev_b32_e32 v160, 4, v221
	v_add_u32_e32 v159, s8, v160
	v_add_u32_e32 v159, 0x2000, v159
	s_lshl_b32 s13, s12, 12
	v_add_u32_e32 v162, s13, v157
	global_load_dwordx4 v[88:91], v162, s[6:7] offset:0
	global_load_dwordx4 v[92:95], v162, s[6:7] offset:64
	global_load_dwordx4 v[96:99], v162, s[6:7] offset:128
	global_load_dwordx4 v[100:103], v162, s[6:7] offset:192
	s_mov_b32 s18, s14
	s_mov_b64 s[16:17], s[2:3]
	v_add_u32_e32 v161, s18, v156
	ds_read_u16 v0, v161 offset:0
	ds_read_u16 v1, v161 offset:8
	ds_read_u16 v2, v161 offset:16
	ds_read_u16 v3, v161 offset:24
	ds_read_u16 v4, v161 offset:32
	ds_read_u16 v5, v161 offset:40
	ds_read_u16 v6, v161 offset:48
	ds_read_u16 v7, v161 offset:56
	s_waitcnt lgkmcnt(7)
	s_add_i32 m0, s8, 0x0
	v_lshl_add_u32 v8, v0, 8, v10
	global_load_lds_dwordx4 v8, s[16:17]
	s_waitcnt lgkmcnt(6)
	s_add_i32 m0, s8, 0x400
	v_lshl_add_u32 v9, v1, 8, v11
	global_load_lds_dwordx4 v9, s[16:17]
	s_waitcnt lgkmcnt(5)
	s_add_i32 m0, s8, 0x800
	v_lshl_add_u32 v8, v2, 8, v12
	global_load_lds_dwordx4 v8, s[16:17]
	s_waitcnt lgkmcnt(4)
	s_add_i32 m0, s8, 0xc00
	v_lshl_add_u32 v9, v3, 8, v13
	global_load_lds_dwordx4 v9, s[16:17]
	s_waitcnt lgkmcnt(3)
	s_add_i32 m0, s8, 0x1000
	v_lshl_add_u32 v8, v4, 8, v10
	global_load_lds_dwordx4 v8, s[16:17]
	s_waitcnt lgkmcnt(2)
	s_add_i32 m0, s8, 0x1400
	v_lshl_add_u32 v9, v5, 8, v11
	global_load_lds_dwordx4 v9, s[16:17]
	s_waitcnt lgkmcnt(1)
	s_add_i32 m0, s8, 0x1800
	v_lshl_add_u32 v8, v6, 8, v12
	global_load_lds_dwordx4 v8, s[16:17]
	s_waitcnt lgkmcnt(0)
	s_add_i32 m0, s8, 0x1c00
	v_lshl_add_u32 v9, v7, 8, v13
	global_load_lds_dwordx4 v9, s[16:17]
	s_cmp_eq_u32 s10, 1
	s_cbranch_scc1 .Lattn_q2
	s_cmp_eq_u32 s10, 2
	s_cbranch_scc1 .Lattn_q4
	s_cmp_eq_u32 s10, 3
	s_cbranch_scc1 .Lattn_q6
.Lattn_q8:
	s_add_i32 s18, s14, 64
	s_mov_b64 s[16:17], s[2:3]
	v_add_u32_e32 v161, s18, v156
	ds_read_u16 v0, v161 offset:0
	ds_read_u16 v1, v161 offset:8
	ds_read_u16 v2, v161 offset:16
	ds_read_u16 v3, v161 offset:24
	ds_read_u16 v4, v161 offset:32
	ds_read_u16 v5, v161 offset:40
	ds_read_u16 v6, v161 offset:48
	ds_read_u16 v7, v161 offset:56
	s_waitcnt lgkmcnt(7)
	s_add_i32 m0, s8, 0x2000
	v_lshl_add_u32 v8, v0, 8, v10
	global_load_lds_dwordx4 v8, s[16:17]
	s_waitcnt lgkmcnt(6)
	s_add_i32 m0, s8, 0x2400
	v_lshl_add_u32 v9, v1, 8, v11
	global_load_lds_dwordx4 v9, s[16:17]
	s_waitcnt lgkmcnt(5)
	s_add_i32 m0, s8, 0x2800
	v_lshl_add_u32 v8, v2, 8, v12
	global_load_lds_dwordx4 v8, s[16:17]
	s_waitcnt lgkmcnt(4)
	s_add_i32 m0, s8, 0x2c00
	v_lshl_add_u32 v9, v3, 8, v13
	global_load_lds_dwordx4 v9, s[16:17]
	s_waitcnt lgkmcnt(3)
	s_add_i32 m0, s8, 0x3000
	v_lshl_add_u32 v8, v4, 8, v10
	global_load_lds_dwordx4 v8, s[16:17]
	s_waitcnt lgkmcnt(2)
	s_add_i32 m0, s8, 0x3400
	v_lshl_add_u32 v9, v5, 8, v11
	global_load_lds_dwordx4 v9, s[16:17]
	s_waitcnt lgkmcnt(1)
	s_add_i32 m0, s8, 0x3800
	v_lshl_add_u32 v8, v6, 8, v12
	global_load_lds_dwordx4 v8, s[16:17]
	s_waitcnt lgkmcnt(0)
	s_add_i32 m0, s8, 0x3c00
	v_lshl_add_u32 v9, v7, 8, v13
	global_load_lds_dwordx4 v9, s[16:17]
	s_waitcnt vmcnt(8)
	ds_read_b128 v[104:107], v18 offset:0
	ds_read_b128 v[108:111], v19 offset:0
	ds_read_b128 v[112:115], v20 offset:0
	ds_read_b128 v[116:119], v21 offset:0
	ds_read_b128 v[120:123], v18 offset:4096
	ds_read_b128 v[124:127], v19 offset:4096
	ds_read_b128 v[128:131], v20 offset:4096
	ds_read_b128 v[132:135], v21 offset:4096
	s_waitcnt lgkmcnt(7)
	v_mfma_f32_16x16x32_bf16 v[136:139], v[104:107], v[88:91], 0
	s_waitcnt lgkmcnt(6)
	v_mfma_f32_16x16x32_bf16 v[136:139], v[108:111], v[92:95], v[136:139]
	s_waitcnt lgkmcnt(5)
	v_mfma_f32_16x16x32_bf16 v[136:139], v[112:115], v[96:99], v[136:139]
	s_waitcnt lgkmcnt(4)
	v_mfma_f32_16x16x32_bf16 v[136:139], v[116:119], v[100:103], v[136:139]
	s_waitcnt lgkmcnt(3)
	v_mfma_f32_16x16x32_bf16 v[140:143], v[120:123], v[88:91], 0
	s_waitcnt lgkmcnt(2)
	v_mfma_f32_16x16x32_bf16 v[140:143], v[124:127], v[92:95], v[140:143]
	s_waitcnt lgkmcnt(1)
	v_mfma_f32_16x16x32_bf16 v[140:143], v[128:131], v[96:99], v[140:143]
	s_waitcnt lgkmcnt(0)
	v_mfma_f32_16x16x32_bf16 v[140:143], v[132:135], v[100:103], v[140:143]
	v_mul_f32_e32 v24, 0x3db504f3, v136
	v_mul_f32_e32 v25, 0x3db504f3, v137
	v_mul_f32_e32 v26, 0x3db504f3, v138
	v_mul_f32_e32 v27, 0x3db504f3, v139
	s_nop 3
	v_mul_f32_e32 v28, 0x3db504f3, v140
	v_mul_f32_e32 v29, 0x3db504f3, v141
	v_mul_f32_e32 v30, 0x3db504f3, v142
	v_mul_f32_e32 v31, 0x3db504f3, v143
	s_add_i32 s18, s14, 128
	s_mov_b64 s[16:17], s[2:3]
	v_add_u32_e32 v161, s18, v156
	ds_read_u16 v0, v161 offset:0
	ds_read_u16 v1, v161 offset:8
	ds_read_u16 v2, v161 offset:16
	ds_read_u16 v3, v161 offset:24
	ds_read_u16 v4, v161 offset:32
	ds_read_u16 v5, v161 offset:40
	ds_read_u16 v6, v161 offset:48
	ds_read_u16 v7, v161 offset:56
	s_waitcnt lgkmcnt(7)
	s_add_i32 m0, s8, 0x0
	v_lshl_add_u32 v8, v0, 8, v10
	global_load_lds_dwordx4 v8, s[16:17]
	s_waitcnt lgkmcnt(6)
	s_add_i32 m0, s8, 0x400
	v_lshl_add_u32 v9, v1, 8, v11
	global_load_lds_dwordx4 v9, s[16:17]
	s_waitcnt lgkmcnt(5)
	s_add_i32 m0, s8, 0x800
	v_lshl_add_u32 v8, v2, 8, v12
	global_load_lds_dwordx4 v8, s[16:17]
	s_waitcnt lgkmcnt(4)
	s_add_i32 m0, s8, 0xc00
	v_lshl_add_u32 v9, v3, 8, v13
	global_load_lds_dwordx4 v9, s[16:17]
	s_waitcnt lgkmcnt(3)
	s_add_i32 m0, s8, 0x1000
	v_lshl_add_u32 v8, v4, 8, v10
	global_load_lds_dwordx4 v8, s[16:17]
	s_waitcnt lgkmcnt(2)
	s_add_i32 m0, s8, 0x1400
	v_lshl_add_u32 v9, v5, 8, v11
	global_load_lds_dwordx4 v9, s[16:17]
	s_waitcnt lgkmcnt(1)
	s_add_i32 m0, s8, 0x1800
	v_lshl_add_u32 v8, v6, 8, v12
	global_load_lds_dwordx4 v8, s[16:17]
	s_waitcnt lgkmcnt(0)
	s_add_i32 m0, s8, 0x1c00
	v_lshl_add_u32 v9, v7, 8, v13
	global_load_lds_dwordx4 v9, s[16:17]
	s_waitcnt vmcnt(8)
	ds_read_b128 v[104:107], v18 offset:8192
	ds_read_b128 v[108:111], v19 offset:8192
	ds_read_b128 v[112:115], v20 offset:8192
	ds_read_b128 v[116:119], v21 offset:8192
	ds_read_b128 v[120:123], v18 offset:12288
	ds_read_b128 v[124:127], v19 offset:12288
	ds_read_b128 v[128:131], v20 offset:12288
	ds_read_b128 v[132:135], v21 offset:12288
	s_waitcnt lgkmcnt(7)
	v_mfma_f32_16x16x32_bf16 v[136:139], v[104:107], v[88:91], 0
	s_waitcnt lgkmcnt(6)
	v_mfma_f32_16x16x32_bf16 v[136:139], v[108:111], v[92:95], v[136:139]
	s_waitcnt lgkmcnt(5)
	v_mfma_f32_16x16x32_bf16 v[136:139], v[112:115], v[96:99], v[136:139]
	s_waitcnt lgkmcnt(4)
	v_mfma_f32_16x16x32_bf16 v[136:139], v[116:119], v[100:103], v[136:139]
	s_waitcnt lgkmcnt(3)
	v_mfma_f32_16x16x32_bf16 v[140:143], v[120:123], v[88:91], 0
	s_waitcnt lgkmcnt(2)
	v_mfma_f32_16x16x32_bf16 v[140:143], v[124:127], v[92:95], v[140:143]
	s_waitcnt lgkmcnt(1)
	v_mfma_f32_16x16x32_bf16 v[140:143], v[128:131], v[96:99], v[140:143]
	s_waitcnt lgkmcnt(0)
	v_mfma_f32_16x16x32_bf16 v[140:143], v[132:135], v[100:103], v[140:143]
	v_mul_f32_e32 v32, 0x3db504f3, v136
	v_mul_f32_e32 v33, 0x3db504f3, v137
	v_mul_f32_e32 v34, 0x3db504f3, v138
	v_mul_f32_e32 v35, 0x3db504f3, v139
	s_nop 3
	v_mul_f32_e32 v36, 0x3db504f3, v140
	v_mul_f32_e32 v37, 0x3db504f3, v141
	v_mul_f32_e32 v38, 0x3db504f3, v142
	v_mul_f32_e32 v39, 0x3db504f3, v143
	s_add_i32 s18, s14, 192
	s_mov_b64 s[16:17], s[2:3]
	v_add_u32_e32 v161, s18, v156
	ds_read_u16 v0, v161 offset:0
	ds_read_u16 v1, v161 offset:8
	ds_read_u16 v2, v161 offset:16
	ds_read_u16 v3, v161 offset:24
	ds_read_u16 v4, v161 offset:32
	ds_read_u16 v5, v161 offset:40
	ds_read_u16 v6, v161 offset:48
	ds_read_u16 v7, v161 offset:56
	s_waitcnt lgkmcnt(7)
	s_add_i32 m0, s8, 0x2000
	v_lshl_add_u32 v8, v0, 8, v10
	global_load_lds_dwordx4 v8, s[16:17]
	s_waitcnt lgkmcnt(6)
	s_add_i32 m0, s8, 0x2400
	v_lshl_add_u32 v9, v1, 8, v11
	global_load_lds_dwordx4 v9, s[16:17]
	s_waitcnt lgkmcnt(5)
	s_add_i32 m0, s8, 0x2800
	v_lshl_add_u32 v8, v2, 8, v12
	global_load_lds_dwordx4 v8, s[16:17]
	s_waitcnt lgkmcnt(4)
	s_add_i32 m0, s8, 0x2c00
	v_lshl_add_u32 v9, v3, 8, v13
	global_load_lds_dwordx4 v9, s[16:17]
	s_waitcnt lgkmcnt(3)
	s_add_i32 m0, s8, 0x3000
	v_lshl_add_u32 v8, v4, 8, v10
	global_load_lds_dwordx4 v8, s[16:17]
	s_waitcnt lgkmcnt(2)
	s_add_i32 m0, s8, 0x3400
	v_lshl_add_u32 v9, v5, 8, v11
	global_load_lds_dwordx4 v9, s[16:17]
	s_waitcnt lgkmcnt(1)
	s_add_i32 m0, s8, 0x3800
	v_lshl_add_u32 v8, v6, 8, v12
	global_load_lds_dwordx4 v8, s[16:17]
	s_waitcnt lgkmcnt(0)
	s_add_i32 m0, s8, 0x3c00
	v_lshl_add_u32 v9, v7, 8, v13
	global_load_lds_dwordx4 v9, s[16:17]
	s_waitcnt vmcnt(8)
	ds_read_b128 v[104:107], v18 offset:0
	ds_read_b128 v[108:111], v19 offset:0
	ds_read_b128 v[112:115], v20 offset:0
	ds_read_b128 v[116:119], v21 offset:0
	ds_read_b128 v[120:123], v18 offset:4096
	ds_read_b128 v[124:127], v19 offset:4096
	ds_read_b128 v[128:131], v20 offset:4096
	ds_read_b128 v[132:135], v21 offset:4096
	s_waitcnt lgkmcnt(7)
	v_mfma_f32_16x16x32_bf16 v[136:139], v[104:107], v[88:91], 0
	s_waitcnt lgkmcnt(6)
	v_mfma_f32_16x16x32_bf16 v[136:139], v[108:111], v[92:95], v[136:139]
	s_waitcnt lgkmcnt(5)
	v_mfma_f32_16x16x32_bf16 v[136:139], v[112:115], v[96:99], v[136:139]
	s_waitcnt lgkmcnt(4)
	v_mfma_f32_16x16x32_bf16 v[136:139], v[116:119], v[100:103], v[136:139]
	s_waitcnt lgkmcnt(3)
	v_mfma_f32_16x16x32_bf16 v[140:143], v[120:123], v[88:91], 0
	s_waitcnt lgkmcnt(2)
	v_mfma_f32_16x16x32_bf16 v[140:143], v[124:127], v[92:95], v[140:143]
	s_waitcnt lgkmcnt(1)
	v_mfma_f32_16x16x32_bf16 v[140:143], v[128:131], v[96:99], v[140:143]
	s_waitcnt lgkmcnt(0)
	v_mfma_f32_16x16x32_bf16 v[140:143], v[132:135], v[100:103], v[140:143]
	v_mul_f32_e32 v40, 0x3db504f3, v136
	v_mul_f32_e32 v41, 0x3db504f3, v137
	v_mul_f32_e32 v42, 0x3db504f3, v138
	v_mul_f32_e32 v43, 0x3db504f3, v139
	s_nop 3
	v_mul_f32_e32 v44, 0x3db504f3, v140
	v_mul_f32_e32 v45, 0x3db504f3, v141
	v_mul_f32_e32 v46, 0x3db504f3, v142
	v_mul_f32_e32 v47, 0x3db504f3, v143
	s_add_i32 s18, s14, 256
	s_mov_b64 s[16:17], s[2:3]
	v_add_u32_e32 v161, s18, v156
	ds_read_u16 v0, v161 offset:0
	ds_read_u16 v1, v161 offset:8
	ds_read_u16 v2, v161 offset:16
	ds_read_u16 v3, v161 offset:24
	ds_read_u16 v4, v161 offset:32
	ds_read_u16 v5, v161 offset:40
	ds_read_u16 v6, v161 offset:48
	ds_read_u16 v7, v161 offset:56
	s_waitcnt lgkmcnt(7)
	s_add_i32 m0, s8, 0x0
	v_lshl_add_u32 v8, v0, 8, v10
	global_load_lds_dwordx4 v8, s[16:17]
	s_waitcnt lgkmcnt(6)
	s_add_i32 m0, s8, 0x400
	v_lshl_add_u32 v9, v1, 8, v11
	global_load_lds_dwordx4 v9, s[16:17]
	s_waitcnt lgkmcnt(5)
	s_add_i32 m0, s8, 0x800
	v_lshl_add_u32 v8, v2, 8, v12
	global_load_lds_dwordx4 v8, s[16:17]
	s_waitcnt lgkmcnt(4)
	s_add_i32 m0, s8, 0xc00
	v_lshl_add_u32 v9, v3, 8, v13
	global_load_lds_dwordx4 v9, s[16:17]
	s_waitcnt lgkmcnt(3)
	s_add_i32 m0, s8, 0x1000
	v_lshl_add_u32 v8, v4, 8, v10
	global_load_lds_dwordx4 v8, s[16:17]
	s_waitcnt lgkmcnt(2)
	s_add_i32 m0, s8, 0x1400
	v_lshl_add_u32 v9, v5, 8, v11
	global_load_lds_dwordx4 v9, s[16:17]
	s_waitcnt lgkmcnt(1)
	s_add_i32 m0, s8, 0x1800
	v_lshl_add_u32 v8, v6, 8, v12
	global_load_lds_dwordx4 v8, s[16:17]
	s_waitcnt lgkmcnt(0)
	s_add_i32 m0, s8, 0x1c00
	v_lshl_add_u32 v9, v7, 8, v13
	global_load_lds_dwordx4 v9, s[16:17]
	s_waitcnt vmcnt(8)
	ds_read_b128 v[104:107], v18 offset:8192
	ds_read_b128 v[108:111], v19 offset:8192
	ds_read_b128 v[112:115], v20 offset:8192
	ds_read_b128 v[116:119], v21 offset:8192
	ds_read_b128 v[120:123], v18 offset:12288
	ds_read_b128 v[124:127], v19 offset:12288
	ds_read_b128 v[128:131], v20 offset:12288
	ds_read_b128 v[132:135], v21 offset:12288
	s_waitcnt lgkmcnt(7)
	v_mfma_f32_16x16x32_bf16 v[136:139], v[104:107], v[88:91], 0
	s_waitcnt lgkmcnt(6)
	v_mfma_f32_16x16x32_bf16 v[136:139], v[108:111], v[92:95], v[136:139]
	s_waitcnt lgkmcnt(5)
	v_mfma_f32_16x16x32_bf16 v[136:139], v[112:115], v[96:99], v[136:139]
	s_waitcnt lgkmcnt(4)
	v_mfma_f32_16x16x32_bf16 v[136:139], v[116:119], v[100:103], v[136:139]
	s_waitcnt lgkmcnt(3)
	v_mfma_f32_16x16x32_bf16 v[140:143], v[120:123], v[88:91], 0
	s_waitcnt lgkmcnt(2)
	v_mfma_f32_16x16x32_bf16 v[140:143], v[124:127], v[92:95], v[140:143]
	s_waitcnt lgkmcnt(1)
	v_mfma_f32_16x16x32_bf16 v[140:143], v[128:131], v[96:99], v[140:143]
	s_waitcnt lgkmcnt(0)
	v_mfma_f32_16x16x32_bf16 v[140:143], v[132:135], v[100:103], v[140:143]
	v_mul_f32_e32 v48, 0x3db504f3, v136
	v_mul_f32_e32 v49, 0x3db504f3, v137
	v_mul_f32_e32 v50, 0x3db504f3, v138
	v_mul_f32_e32 v51, 0x3db504f3, v139
	s_nop 3
	v_mul_f32_e32 v52, 0x3db504f3, v140
	v_mul_f32_e32 v53, 0x3db504f3, v141
	v_mul_f32_e32 v54, 0x3db504f3, v142
	v_mul_f32_e32 v55, 0x3db504f3, v143
	s_add_i32 s18, s14, 320
	s_mov_b64 s[16:17], s[2:3]
	v_add_u32_e32 v161, s18, v156
	ds_read_u16 v0, v161 offset:0
	ds_read_u16 v1, v161 offset:8
	ds_read_u16 v2, v161 offset:16
	ds_read_u16 v3, v161 offset:24
	ds_read_u16 v4, v161 offset:32
	ds_read_u16 v5, v161 offset:40
	ds_read_u16 v6, v161 offset:48
	ds_read_u16 v7, v161 offset:56
	s_waitcnt lgkmcnt(7)
	s_add_i32 m0, s8, 0x2000
	v_lshl_add_u32 v8, v0, 8, v10
	global_load_lds_dwordx4 v8, s[16:17]
	s_waitcnt lgkmcnt(6)
	s_add_i32 m0, s8, 0x2400
	v_lshl_add_u32 v9, v1, 8, v11
	global_load_lds_dwordx4 v9, s[16:17]
	s_waitcnt lgkmcnt(5)
	s_add_i32 m0, s8, 0x2800
	v_lshl_add_u32 v8, v2, 8, v12
	global_load_lds_dwordx4 v8, s[16:17]
	s_waitcnt lgkmcnt(4)
	s_add_i32 m0, s8, 0x2c00
	v_lshl_add_u32 v9, v3, 8, v13
	global_load_lds_dwordx4 v9, s[16:17]
	s_waitcnt lgkmcnt(3)
	s_add_i32 m0, s8, 0x3000
	v_lshl_add_u32 v8, v4, 8, v10
	global_load_lds_dwordx4 v8, s[16:17]
	s_waitcnt lgkmcnt(2)
	s_add_i32 m0, s8, 0x3400
	v_lshl_add_u32 v9, v5, 8, v11
	global_load_lds_dwordx4 v9, s[16:17]
	s_waitcnt lgkmcnt(1)
	s_add_i32 m0, s8, 0x3800
	v_lshl_add_u32 v8, v6, 8, v12
	global_load_lds_dwordx4 v8, s[16:17]
	s_waitcnt lgkmcnt(0)
	s_add_i32 m0, s8, 0x3c00
	v_lshl_add_u32 v9, v7, 8, v13
	global_load_lds_dwordx4 v9, s[16:17]
	s_waitcnt vmcnt(8)
	ds_read_b128 v[104:107], v18 offset:0
	ds_read_b128 v[108:111], v19 offset:0
	ds_read_b128 v[112:115], v20 offset:0
	ds_read_b128 v[116:119], v21 offset:0
	ds_read_b128 v[120:123], v18 offset:4096
	ds_read_b128 v[124:127], v19 offset:4096
	ds_read_b128 v[128:131], v20 offset:4096
	ds_read_b128 v[132:135], v21 offset:4096
	s_waitcnt lgkmcnt(7)
	v_mfma_f32_16x16x32_bf16 v[136:139], v[104:107], v[88:91], 0
	s_waitcnt lgkmcnt(6)
	v_mfma_f32_16x16x32_bf16 v[136:139], v[108:111], v[92:95], v[136:139]
	s_waitcnt lgkmcnt(5)
	v_mfma_f32_16x16x32_bf16 v[136:139], v[112:115], v[96:99], v[136:139]
	s_waitcnt lgkmcnt(4)
	v_mfma_f32_16x16x32_bf16 v[136:139], v[116:119], v[100:103], v[136:139]
	s_waitcnt lgkmcnt(3)
	v_mfma_f32_16x16x32_bf16 v[140:143], v[120:123], v[88:91], 0
	s_waitcnt lgkmcnt(2)
	v_mfma_f32_16x16x32_bf16 v[140:143], v[124:127], v[92:95], v[140:143]
	s_waitcnt lgkmcnt(1)
	v_mfma_f32_16x16x32_bf16 v[140:143], v[128:131], v[96:99], v[140:143]
	s_waitcnt lgkmcnt(0)
	v_mfma_f32_16x16x32_bf16 v[140:143], v[132:135], v[100:103], v[140:143]
	v_mul_f32_e32 v56, 0x3db504f3, v136
	v_mul_f32_e32 v57, 0x3db504f3, v137
	v_mul_f32_e32 v58, 0x3db504f3, v138
	v_mul_f32_e32 v59, 0x3db504f3, v139
	s_nop 3
	v_mul_f32_e32 v60, 0x3db504f3, v140
	v_mul_f32_e32 v61, 0x3db504f3, v141
	v_mul_f32_e32 v62, 0x3db504f3, v142
	v_mul_f32_e32 v63, 0x3db504f3, v143
	s_add_i32 s18, s14, 384
	s_mov_b64 s[16:17], s[2:3]
	v_add_u32_e32 v161, s18, v156
	ds_read_u16 v0, v161 offset:0
	ds_read_u16 v1, v161 offset:8
	ds_read_u16 v2, v161 offset:16
	ds_read_u16 v3, v161 offset:24
	ds_read_u16 v4, v161 offset:32
	ds_read_u16 v5, v161 offset:40
	ds_read_u16 v6, v161 offset:48
	ds_read_u16 v7, v161 offset:56
	s_waitcnt lgkmcnt(7)
	s_add_i32 m0, s8, 0x0
	v_lshl_add_u32 v8, v0, 8, v10
	global_load_lds_dwordx4 v8, s[16:17]
	s_waitcnt lgkmcnt(6)
	s_add_i32 m0, s8, 0x400
	v_lshl_add_u32 v9, v1, 8, v11
	global_load_lds_dwordx4 v9, s[16:17]
	s_waitcnt lgkmcnt(5)
	s_add_i32 m0, s8, 0x800
	v_lshl_add_u32 v8, v2, 8, v12
	global_load_lds_dwordx4 v8, s[16:17]
	s_waitcnt lgkmcnt(4)
	s_add_i32 m0, s8, 0xc00
	v_lshl_add_u32 v9, v3, 8, v13
	global_load_lds_dwordx4 v9, s[16:17]
	s_waitcnt lgkmcnt(3)
	s_add_i32 m0, s8, 0x1000
	v_lshl_add_u32 v8, v4, 8, v10
	global_load_lds_dwordx4 v8, s[16:17]
	s_waitcnt lgkmcnt(2)
	s_add_i32 m0, s8, 0x1400
	v_lshl_add_u32 v9, v5, 8, v11
	global_load_lds_dwordx4 v9, s[16:17]
	s_waitcnt lgkmcnt(1)
	s_add_i32 m0, s8, 0x1800
	v_lshl_add_u32 v8, v6, 8, v12
	global_load_lds_dwordx4 v8, s[16:17]
	s_waitcnt lgkmcnt(0)
	s_add_i32 m0, s8, 0x1c00
	v_lshl_add_u32 v9, v7, 8, v13
	global_load_lds_dwordx4 v9, s[16:17]
	s_waitcnt vmcnt(8)
	ds_read_b128 v[104:107], v18 offset:8192
	ds_read_b128 v[108:111], v19 offset:8192
	ds_read_b128 v[112:115], v20 offset:8192
	ds_read_b128 v[116:119], v21 offset:8192
	ds_read_b128 v[120:123], v18 offset:12288
	ds_read_b128 v[124:127], v19 offset:12288
	ds_read_b128 v[128:131], v20 offset:12288
	ds_read_b128 v[132:135], v21 offset:12288
	s_waitcnt lgkmcnt(7)
	v_mfma_f32_16x16x32_bf16 v[136:139], v[104:107], v[88:91], 0
	s_waitcnt lgkmcnt(6)
	v_mfma_f32_16x16x32_bf16 v[136:139], v[108:111], v[92:95], v[136:139]
	s_waitcnt lgkmcnt(5)
	v_mfma_f32_16x16x32_bf16 v[136:139], v[112:115], v[96:99], v[136:139]
	s_waitcnt lgkmcnt(4)
	v_mfma_f32_16x16x32_bf16 v[136:139], v[116:119], v[100:103], v[136:139]
	s_waitcnt lgkmcnt(3)
	v_mfma_f32_16x16x32_bf16 v[140:143], v[120:123], v[88:91], 0
	s_waitcnt lgkmcnt(2)
	v_mfma_f32_16x16x32_bf16 v[140:143], v[124:127], v[92:95], v[140:143]
	s_waitcnt lgkmcnt(1)
	v_mfma_f32_16x16x32_bf16 v[140:143], v[128:131], v[96:99], v[140:143]
	s_waitcnt lgkmcnt(0)
	v_mfma_f32_16x16x32_bf16 v[140:143], v[132:135], v[100:103], v[140:143]
	v_mul_f32_e32 v64, 0x3db504f3, v136
	v_mul_f32_e32 v65, 0x3db504f3, v137
	v_mul_f32_e32 v66, 0x3db504f3, v138
	v_mul_f32_e32 v67, 0x3db504f3, v139
	s_nop 3
	v_mul_f32_e32 v68, 0x3db504f3, v140
	v_mul_f32_e32 v69, 0x3db504f3, v141
	v_mul_f32_e32 v70, 0x3db504f3, v142
	v_mul_f32_e32 v71, 0x3db504f3, v143
	s_add_i32 s18, s14, 448
	s_mov_b64 s[16:17], s[2:3]
	v_add_u32_e32 v161, s18, v156
	ds_read_u16 v0, v161 offset:0
	ds_read_u16 v1, v161 offset:8
	ds_read_u16 v2, v161 offset:16
	ds_read_u16 v3, v161 offset:24
	ds_read_u16 v4, v161 offset:32
	ds_read_u16 v5, v161 offset:40
	ds_read_u16 v6, v161 offset:48
	ds_read_u16 v7, v161 offset:56
	s_waitcnt lgkmcnt(7)
	s_add_i32 m0, s8, 0x2000
	v_lshl_add_u32 v8, v0, 8, v10
	global_load_lds_dwordx4 v8, s[16:17]
	s_waitcnt lgkmcnt(6)
	s_add_i32 m0, s8, 0x2400
	v_lshl_add_u32 v9, v1, 8, v11
	global_load_lds_dwordx4 v9, s[16:17]
	s_waitcnt lgkmcnt(5)
	s_add_i32 m0, s8, 0x2800
	v_lshl_add_u32 v8, v2, 8, v12
	global_load_lds_dwordx4 v8, s[16:17]
	s_waitcnt lgkmcnt(4)
	s_add_i32 m0, s8, 0x2c00
	v_lshl_add_u32 v9, v3, 8, v13
	global_load_lds_dwordx4 v9, s[16:17]
	s_waitcnt lgkmcnt(3)
	s_add_i32 m0, s8, 0x3000
	v_lshl_add_u32 v8, v4, 8, v10
	global_load_lds_dwordx4 v8, s[16:17]
	s_waitcnt lgkmcnt(2)
	s_add_i32 m0, s8, 0x3400
	v_lshl_add_u32 v9, v5, 8, v11
	global_load_lds_dwordx4 v9, s[16:17]
	s_waitcnt lgkmcnt(1)
	s_add_i32 m0, s8, 0x3800
	v_lshl_add_u32 v8, v6, 8, v12
	global_load_lds_dwordx4 v8, s[16:17]
	s_waitcnt lgkmcnt(0)
	s_add_i32 m0, s8, 0x3c00
	v_lshl_add_u32 v9, v7, 8, v13
	global_load_lds_dwordx4 v9, s[16:17]
	s_waitcnt vmcnt(8)
	ds_read_b128 v[104:107], v18 offset:0
	ds_read_b128 v[108:111], v19 offset:0
	ds_read_b128 v[112:115], v20 offset:0
	ds_read_b128 v[116:119], v21 offset:0
	ds_read_b128 v[120:123], v18 offset:4096
	ds_read_b128 v[124:127], v19 offset:4096
	ds_read_b128 v[128:131], v20 offset:4096
	ds_read_b128 v[132:135], v21 offset:4096
	s_waitcnt lgkmcnt(7)
	v_mfma_f32_16x16x32_bf16 v[136:139], v[104:107], v[88:91], 0
	s_waitcnt lgkmcnt(6)
	v_mfma_f32_16x16x32_bf16 v[136:139], v[108:111], v[92:95], v[136:139]
	s_waitcnt lgkmcnt(5)
	v_mfma_f32_16x16x32_bf16 v[136:139], v[112:115], v[96:99], v[136:139]
	s_waitcnt lgkmcnt(4)
	v_mfma_f32_16x16x32_bf16 v[136:139], v[116:119], v[100:103], v[136:139]
	s_waitcnt lgkmcnt(3)
	v_mfma_f32_16x16x32_bf16 v[140:143], v[120:123], v[88:91], 0
	s_waitcnt lgkmcnt(2)
	v_mfma_f32_16x16x32_bf16 v[140:143], v[124:127], v[92:95], v[140:143]
	s_waitcnt lgkmcnt(1)
	v_mfma_f32_16x16x32_bf16 v[140:143], v[128:131], v[96:99], v[140:143]
	s_waitcnt lgkmcnt(0)
	v_mfma_f32_16x16x32_bf16 v[140:143], v[132:135], v[100:103], v[140:143]
	v_mul_f32_e32 v72, 0x3db504f3, v136
	v_mul_f32_e32 v73, 0x3db504f3, v137
	v_mul_f32_e32 v74, 0x3db504f3, v138
	v_mul_f32_e32 v75, 0x3db504f3, v139
	s_nop 3
	v_mul_f32_e32 v76, 0x3db504f3, v140
	v_mul_f32_e32 v77, 0x3db504f3, v141
	v_mul_f32_e32 v78, 0x3db504f3, v142
	v_mul_f32_e32 v79, 0x3db504f3, v143
	s_mov_b32 s18, s14
	s_mov_b64 s[16:17], s[4:5]
	v_add_u32_e32 v161, s18, v156
	ds_read_u16 v0, v161 offset:0
	ds_read_u16 v1, v161 offset:8
	ds_read_u16 v2, v161 offset:16
	ds_read_u16 v3, v161 offset:24
	ds_read_u16 v4, v161 offset:32
	ds_read_u16 v5, v161 offset:40
	ds_read_u16 v6, v161 offset:48
	ds_read_u16 v7, v161 offset:56
	s_waitcnt lgkmcnt(7)
	s_add_i32 m0, s8, 0x0
	v_lshl_add_u32 v8, v0, 8, v10
	global_load_lds_dwordx4 v8, s[16:17]
	s_waitcnt lgkmcnt(6)
	s_add_i32 m0, s8, 0x400
	v_lshl_add_u32 v9, v1, 8, v11
	global_load_lds_dwordx4 v9, s[16:17]
	s_waitcnt lgkmcnt(5)
	s_add_i32 m0, s8, 0x800
	v_lshl_add_u32 v8, v2, 8, v12
	global_load_lds_dwordx4 v8, s[16:17]
	s_waitcnt lgkmcnt(4)
	s_add_i32 m0, s8, 0xc00
	v_lshl_add_u32 v9, v3, 8, v13
	global_load_lds_dwordx4 v9, s[16:17]
	s_waitcnt lgkmcnt(3)
	s_add_i32 m0, s8, 0x1000
	v_lshl_add_u32 v8, v4, 8, v10
	global_load_lds_dwordx4 v8, s[16:17]
	s_waitcnt lgkmcnt(2)
	s_add_i32 m0, s8, 0x1400
	v_lshl_add_u32 v9, v5, 8, v11
	global_load_lds_dwordx4 v9, s[16:17]
	s_waitcnt lgkmcnt(1)
	s_add_i32 m0, s8, 0x1800
	v_lshl_add_u32 v8, v6, 8, v12
	global_load_lds_dwordx4 v8, s[16:17]
	s_waitcnt lgkmcnt(0)
	s_add_i32 m0, s8, 0x1c00
	v_lshl_add_u32 v9, v7, 8, v13
	global_load_lds_dwordx4 v9, s[16:17]
	s_waitcnt vmcnt(8)
	ds_read_b128 v[104:107], v18 offset:8192
	ds_read_b128 v[108:111], v19 offset:8192
	ds_read_b128 v[112:115], v20 offset:8192
	ds_read_b128 v[116:119], v21 offset:8192
	ds_read_b128 v[120:123], v18 offset:12288
	ds_read_b128 v[124:127], v19 offset:12288
	ds_read_b128 v[128:131], v20 offset:12288
	ds_read_b128 v[132:135], v21 offset:12288
	s_waitcnt lgkmcnt(7)
	v_mfma_f32_16x16x32_bf16 v[136:139], v[104:107], v[88:91], 0
	s_waitcnt lgkmcnt(6)
	v_mfma_f32_16x16x32_bf16 v[136:139], v[108:111], v[92:95], v[136:139]
	s_waitcnt lgkmcnt(5)
	v_mfma_f32_16x16x32_bf16 v[136:139], v[112:115], v[96:99], v[136:139]
	s_waitcnt lgkmcnt(4)
	v_mfma_f32_16x16x32_bf16 v[136:139], v[116:119], v[100:103], v[136:139]
	s_waitcnt lgkmcnt(3)
	v_mfma_f32_16x16x32_bf16 v[140:143], v[120:123], v[88:91], 0
	s_waitcnt lgkmcnt(2)
	v_mfma_f32_16x16x32_bf16 v[140:143], v[124:127], v[92:95], v[140:143]
	s_waitcnt lgkmcnt(1)
	v_mfma_f32_16x16x32_bf16 v[140:143], v[128:131], v[96:99], v[140:143]
	s_waitcnt lgkmcnt(0)
	v_mfma_f32_16x16x32_bf16 v[140:143], v[132:135], v[100:103], v[140:143]
	v_mul_f32_e32 v80, 0x3db504f3, v136
	v_mul_f32_e32 v81, 0x3db504f3, v137
	v_mul_f32_e32 v82, 0x3db504f3, v138
	v_mul_f32_e32 v83, 0x3db504f3, v139
	s_nop 3
	v_mul_f32_e32 v84, 0x3db504f3, v140
	v_mul_f32_e32 v85, 0x3db504f3, v141
	v_mul_f32_e32 v86, 0x3db504f3, v142
	v_mul_f32_e32 v87, 0x3db504f3, v143
	v_max3_f32 v163, v24, v25, v26
	v_max3_f32 v163, v163, v27, v28
	v_max3_f32 v163, v163, v29, v30
	v_max3_f32 v163, v163, v31, v32
	v_max3_f32 v163, v163, v33, v34
	v_max3_f32 v163, v163, v35, v36
	v_max3_f32 v163, v163, v37, v38
	v_max3_f32 v163, v163, v39, v40
	v_max3_f32 v163, v163, v41, v42
	v_max3_f32 v163, v163, v43, v44
	v_max3_f32 v163, v163, v45, v46
	v_max3_f32 v163, v163, v47, v48
	v_max3_f32 v163, v163, v49, v50
	v_max3_f32 v163, v163, v51, v52
	v_max3_f32 v163, v163, v53, v54
	v_max3_f32 v163, v163, v55, v56
	v_max3_f32 v163, v163, v57, v58
	v_max3_f32 v163, v163, v59, v60
	v_max3_f32 v163, v163, v61, v62
	v_max3_f32 v163, v163, v63, v64
	v_max3_f32 v163, v163, v65, v66
	v_max3_f32 v163, v163, v67, v68
	v_max3_f32 v163, v163, v69, v70
	v_max3_f32 v163, v163, v71, v72
	v_max3_f32 v163, v163, v73, v74
	v_max3_f32 v163, v163, v75, v76
	v_max3_f32 v163, v163, v77, v78
	v_max3_f32 v163, v163, v79, v80
	v_max3_f32 v163, v163, v81, v82
	v_max3_f32 v163, v163, v83, v84
	v_max3_f32 v163, v163, v85, v86
	v_max_f32_e32 v163, v163, v87
	s_nop 0
	ds_bpermute_b32 v165, v147, v163
	s_waitcnt lgkmcnt(0)
	v_max_f32_e32 v163, v163, v165
	s_nop 0
	ds_bpermute_b32 v165, v146, v163
	s_waitcnt lgkmcnt(0)
	v_max_f32_e32 v163, v163, v165
	v_sub_f32_e32 v165, v24, v163
	v_mul_f32_e32 v165, 0x3fb8aa3b, v165
	v_exp_f32_e32 v24, v165
	v_sub_f32_e32 v166, v25, v163
	v_mul_f32_e32 v166, 0x3fb8aa3b, v166
	v_exp_f32_e32 v25, v166
	v_sub_f32_e32 v167, v26, v163
	v_mul_f32_e32 v167, 0x3fb8aa3b, v167
	v_exp_f32_e32 v26, v167
	v_add_f32_e32 v164, 0, v24
	v_sub_f32_e32 v168, v27, v163
	v_mul_f32_e32 v168, 0x3fb8aa3b, v168
	v_exp_f32_e32 v27, v168
	v_add_f32_e32 v164, v164, v25
	v_sub_f32_e32 v165, v28, v163
	v_mul_f32_e32 v165, 0x3fb8aa3b, v165
	v_exp_f32_e32 v28, v165
	v_add_f32_e32 v164, v164, v26
	v_sub_f32_e32 v166, v29, v163
	v_mul_f32_e32 v166, 0x3fb8aa3b, v166
	v_exp_f32_e32 v29, v166
	v_add_f32_e32 v164, v164, v27
	v_sub_f32_e32 v167, v30, v163
	v_mul_f32_e32 v167, 0x3fb8aa3b, v167
	v_exp_f32_e32 v30, v167
	v_add_f32_e32 v164, v164, v28
	v_sub_f32_e32 v168, v31, v163
	v_mul_f32_e32 v168, 0x3fb8aa3b, v168
	v_exp_f32_e32 v31, v168
	v_add_f32_e32 v164, v164, v29
	v_sub_f32_e32 v165, v32, v163
	v_mul_f32_e32 v165, 0x3fb8aa3b, v165
	v_exp_f32_e32 v32, v165
	v_add_f32_e32 v164, v164, v30
	v_sub_f32_e32 v166, v33, v163
	v_mul_f32_e32 v166, 0x3fb8aa3b, v166
	v_exp_f32_e32 v33, v166
	v_add_f32_e32 v164, v164, v31
	v_sub_f32_e32 v167, v34, v163
	v_mul_f32_e32 v167, 0x3fb8aa3b, v167
	v_exp_f32_e32 v34, v167
	v_add_f32_e32 v164, v164, v32
	v_sub_f32_e32 v168, v35, v163
	v_mul_f32_e32 v168, 0x3fb8aa3b, v168
	v_exp_f32_e32 v35, v168
	v_add_f32_e32 v164, v164, v33
	v_sub_f32_e32 v165, v36, v163
	v_mul_f32_e32 v165, 0x3fb8aa3b, v165
	v_exp_f32_e32 v36, v165
	v_add_f32_e32 v164, v164, v34
	v_sub_f32_e32 v166, v37, v163
	v_mul_f32_e32 v166, 0x3fb8aa3b, v166
	v_exp_f32_e32 v37, v166
	v_add_f32_e32 v164, v164, v35
	v_sub_f32_e32 v167, v38, v163
	v_mul_f32_e32 v167, 0x3fb8aa3b, v167
	v_exp_f32_e32 v38, v167
	v_add_f32_e32 v164, v164, v36
	v_sub_f32_e32 v168, v39, v163
	v_mul_f32_e32 v168, 0x3fb8aa3b, v168
	v_exp_f32_e32 v39, v168
	v_add_f32_e32 v164, v164, v37
	v_sub_f32_e32 v165, v40, v163
	v_mul_f32_e32 v165, 0x3fb8aa3b, v165
	v_exp_f32_e32 v40, v165
	v_add_f32_e32 v164, v164, v38
	v_sub_f32_e32 v166, v41, v163
	v_mul_f32_e32 v166, 0x3fb8aa3b, v166
	v_exp_f32_e32 v41, v166
	v_add_f32_e32 v164, v164, v39
	v_sub_f32_e32 v167, v42, v163
	v_mul_f32_e32 v167, 0x3fb8aa3b, v167
	v_exp_f32_e32 v42, v167
	v_add_f32_e32 v164, v164, v40
	v_sub_f32_e32 v168, v43, v163
	v_mul_f32_e32 v168, 0x3fb8aa3b, v168
	v_exp_f32_e32 v43, v168
	v_add_f32_e32 v164, v164, v41
	v_sub_f32_e32 v165, v44, v163
	v_mul_f32_e32 v165, 0x3fb8aa3b, v165
	v_exp_f32_e32 v44, v165
	v_add_f32_e32 v164, v164, v42
	v_sub_f32_e32 v166, v45, v163
	v_mul_f32_e32 v166, 0x3fb8aa3b, v166
	v_exp_f32_e32 v45, v166
	v_add_f32_e32 v164, v164, v43
	v_sub_f32_e32 v167, v46, v163
	v_mul_f32_e32 v167, 0x3fb8aa3b, v167
	v_exp_f32_e32 v46, v167
	v_add_f32_e32 v164, v164, v44
	v_sub_f32_e32 v168, v47, v163
	v_mul_f32_e32 v168, 0x3fb8aa3b, v168
	v_exp_f32_e32 v47, v168
	v_add_f32_e32 v164, v164, v45
	v_sub_f32_e32 v165, v48, v163
	v_mul_f32_e32 v165, 0x3fb8aa3b, v165
	v_exp_f32_e32 v48, v165
	v_add_f32_e32 v164, v164, v46
	v_sub_f32_e32 v166, v49, v163
	v_mul_f32_e32 v166, 0x3fb8aa3b, v166
	v_exp_f32_e32 v49, v166
	v_add_f32_e32 v164, v164, v47
	v_sub_f32_e32 v167, v50, v163
	v_mul_f32_e32 v167, 0x3fb8aa3b, v167
	v_exp_f32_e32 v50, v167
	v_add_f32_e32 v164, v164, v48
	v_sub_f32_e32 v168, v51, v163
	v_mul_f32_e32 v168, 0x3fb8aa3b, v168
	v_exp_f32_e32 v51, v168
	v_add_f32_e32 v164, v164, v49
	v_sub_f32_e32 v165, v52, v163
	v_mul_f32_e32 v165, 0x3fb8aa3b, v165
	v_exp_f32_e32 v52, v165
	v_add_f32_e32 v164, v164, v50
	v_sub_f32_e32 v166, v53, v163
	v_mul_f32_e32 v166, 0x3fb8aa3b, v166
	v_exp_f32_e32 v53, v166
	v_add_f32_e32 v164, v164, v51
	v_sub_f32_e32 v167, v54, v163
	v_mul_f32_e32 v167, 0x3fb8aa3b, v167
	v_exp_f32_e32 v54, v167
	v_add_f32_e32 v164, v164, v52
	v_sub_f32_e32 v168, v55, v163
	v_mul_f32_e32 v168, 0x3fb8aa3b, v168
	v_exp_f32_e32 v55, v168
	v_add_f32_e32 v164, v164, v53
	v_sub_f32_e32 v165, v56, v163
	v_mul_f32_e32 v165, 0x3fb8aa3b, v165
	v_exp_f32_e32 v56, v165
	v_add_f32_e32 v164, v164, v54
	v_sub_f32_e32 v166, v57, v163
	v_mul_f32_e32 v166, 0x3fb8aa3b, v166
	v_exp_f32_e32 v57, v166
	v_add_f32_e32 v164, v164, v55
	v_sub_f32_e32 v167, v58, v163
	v_mul_f32_e32 v167, 0x3fb8aa3b, v167
	v_exp_f32_e32 v58, v167
	v_add_f32_e32 v164, v164, v56
	v_sub_f32_e32 v168, v59, v163
	v_mul_f32_e32 v168, 0x3fb8aa3b, v168
	v_exp_f32_e32 v59, v168
	v_add_f32_e32 v164, v164, v57
	v_sub_f32_e32 v165, v60, v163
	v_mul_f32_e32 v165, 0x3fb8aa3b, v165
	v_exp_f32_e32 v60, v165
	v_add_f32_e32 v164, v164, v58
	v_sub_f32_e32 v166, v61, v163
	v_mul_f32_e32 v166, 0x3fb8aa3b, v166
	v_exp_f32_e32 v61, v166
	v_add_f32_e32 v164, v164, v59
	v_sub_f32_e32 v167, v62, v163
	v_mul_f32_e32 v167, 0x3fb8aa3b, v167
	v_exp_f32_e32 v62, v167
	v_add_f32_e32 v164, v164, v60
	v_sub_f32_e32 v168, v63, v163
	v_mul_f32_e32 v168, 0x3fb8aa3b, v168
	v_exp_f32_e32 v63, v168
	v_add_f32_e32 v164, v164, v61
	v_sub_f32_e32 v165, v64, v163
	v_mul_f32_e32 v165, 0x3fb8aa3b, v165
	v_exp_f32_e32 v64, v165
	v_add_f32_e32 v164, v164, v62
	v_sub_f32_e32 v166, v65, v163
	v_mul_f32_e32 v166, 0x3fb8aa3b, v166
	v_exp_f32_e32 v65, v166
	v_add_f32_e32 v164, v164, v63
	v_sub_f32_e32 v167, v66, v163
	v_mul_f32_e32 v167, 0x3fb8aa3b, v167
	v_exp_f32_e32 v66, v167
	v_add_f32_e32 v164, v164, v64
	v_sub_f32_e32 v168, v67, v163
	v_mul_f32_e32 v168, 0x3fb8aa3b, v168
	v_exp_f32_e32 v67, v168
	v_add_f32_e32 v164, v164, v65
	v_sub_f32_e32 v165, v68, v163
	v_mul_f32_e32 v165, 0x3fb8aa3b, v165
	v_exp_f32_e32 v68, v165
	v_add_f32_e32 v164, v164, v66
	v_sub_f32_e32 v166, v69, v163
	v_mul_f32_e32 v166, 0x3fb8aa3b, v166
	v_exp_f32_e32 v69, v166
	v_add_f32_e32 v164, v164, v67
	v_sub_f32_e32 v167, v70, v163
	v_mul_f32_e32 v167, 0x3fb8aa3b, v167
	v_exp_f32_e32 v70, v167
	v_add_f32_e32 v164, v164, v68
	v_sub_f32_e32 v168, v71, v163
	v_mul_f32_e32 v168, 0x3fb8aa3b, v168
	v_exp_f32_e32 v71, v168
	v_add_f32_e32 v164, v164, v69
	v_sub_f32_e32 v165, v72, v163
	v_mul_f32_e32 v165, 0x3fb8aa3b, v165
	v_exp_f32_e32 v72, v165
	v_add_f32_e32 v164, v164, v70
	v_sub_f32_e32 v166, v73, v163
	v_mul_f32_e32 v166, 0x3fb8aa3b, v166
	v_exp_f32_e32 v73, v166
	v_add_f32_e32 v164, v164, v71
	v_sub_f32_e32 v167, v74, v163
	v_mul_f32_e32 v167, 0x3fb8aa3b, v167
	v_exp_f32_e32 v74, v167
	v_add_f32_e32 v164, v164, v72
	v_sub_f32_e32 v168, v75, v163
	v_mul_f32_e32 v168, 0x3fb8aa3b, v168
	v_exp_f32_e32 v75, v168
	v_add_f32_e32 v164, v164, v73
	v_sub_f32_e32 v165, v76, v163
	v_mul_f32_e32 v165, 0x3fb8aa3b, v165
	v_exp_f32_e32 v76, v165
	v_add_f32_e32 v164, v164, v74
	v_sub_f32_e32 v166, v77, v163
	v_mul_f32_e32 v166, 0x3fb8aa3b, v166
	v_exp_f32_e32 v77, v166
	v_add_f32_e32 v164, v164, v75
	v_sub_f32_e32 v167, v78, v163
	v_mul_f32_e32 v167, 0x3fb8aa3b, v167
	v_exp_f32_e32 v78, v167
	v_add_f32_e32 v164, v164, v76
	v_sub_f32_e32 v168, v79, v163
	v_mul_f32_e32 v168, 0x3fb8aa3b, v168
	v_exp_f32_e32 v79, v168
	v_add_f32_e32 v164, v164, v77
	v_sub_f32_e32 v165, v80, v163
	v_mul_f32_e32 v165, 0x3fb8aa3b, v165
	v_exp_f32_e32 v80, v165
	v_add_f32_e32 v164, v164, v78
	v_sub_f32_e32 v166, v81, v163
	v_mul_f32_e32 v166, 0x3fb8aa3b, v166
	v_exp_f32_e32 v81, v166
	v_add_f32_e32 v164, v164, v79
	v_sub_f32_e32 v167, v82, v163
	v_mul_f32_e32 v167, 0x3fb8aa3b, v167
	v_exp_f32_e32 v82, v167
	v_add_f32_e32 v164, v164, v80
	v_sub_f32_e32 v168, v83, v163
	v_mul_f32_e32 v168, 0x3fb8aa3b, v168
	v_exp_f32_e32 v83, v168
	v_add_f32_e32 v164, v164, v81
	v_sub_f32_e32 v165, v84, v163
	v_mul_f32_e32 v165, 0x3fb8aa3b, v165
	v_exp_f32_e32 v84, v165
	v_add_f32_e32 v164, v164, v82
	v_sub_f32_e32 v166, v85, v163
	v_mul_f32_e32 v166, 0x3fb8aa3b, v166
	v_exp_f32_e32 v85, v166
	v_add_f32_e32 v164, v164, v83
	v_sub_f32_e32 v167, v86, v163
	v_mul_f32_e32 v167, 0x3fb8aa3b, v167
	v_exp_f32_e32 v86, v167
	v_add_f32_e32 v164, v164, v84
	v_sub_f32_e32 v168, v87, v163
	v_mul_f32_e32 v168, 0x3fb8aa3b, v168
	v_exp_f32_e32 v87, v168
	v_add_f32_e32 v164, v164, v85
	s_nop 0
	v_add_f32_e32 v164, v164, v86
	v_add_f32_e32 v164, v164, v87
	s_nop 0
	ds_bpermute_b32 v165, v147, v164
	s_waitcnt lgkmcnt(0)
	v_add_f32_e32 v164, v164, v165
	s_nop 0
	ds_bpermute_b32 v165, v146, v164
	s_waitcnt lgkmcnt(0)
	v_add_f32_e32 v164, v164, v165
	v_div_scale_f32 v170, s[74:75], v164, v164, 1.0
	v_rcp_f32_e32 v171, v170
	s_nop 0
	v_fma_f32 v172, -v170, v171, 1.0
	v_fmac_f32_e32 v171, v172, v171
	v_div_scale_f32 v172, vcc, 1.0, v164, 1.0
	v_mul_f32_e32 v173, v172, v171
	v_fma_f32 v169, -v170, v173, v172
	v_fmac_f32_e32 v173, v169, v171
	v_fma_f32 v170, -v170, v173, v172
	v_div_fmas_f32 v170, v170, v171, v173
	v_div_fixup_f32 v169, v170, v164, 1.0
	v_mul_f32_e32 v165, v24, v169
	v_mul_f32_e32 v166, v25, v169
	v_cvt_pk_bf16_f32 v24, v165, v166
	v_mul_f32_e32 v167, v26, v169
	v_mul_f32_e32 v168, v27, v169
	v_cvt_pk_bf16_f32 v25, v167, v168
	v_mul_f32_e32 v165, v28, v169
	v_mul_f32_e32 v166, v29, v169
	v_cvt_pk_bf16_f32 v26, v165, v166
	v_mul_f32_e32 v167, v30, v169
	v_mul_f32_e32 v168, v31, v169
	v_cvt_pk_bf16_f32 v27, v167, v168
	v_mul_f32_e32 v165, v32, v169
	v_mul_f32_e32 v166, v33, v169
	v_cvt_pk_bf16_f32 v32, v165, v166
	v_mul_f32_e32 v167, v34, v169
	v_mul_f32_e32 v168, v35, v169
	v_cvt_pk_bf16_f32 v33, v167, v168
	v_mul_f32_e32 v165, v36, v169
	v_mul_f32_e32 v166, v37, v169
	v_cvt_pk_bf16_f32 v34, v165, v166
	v_mul_f32_e32 v167, v38, v169
	v_mul_f32_e32 v168, v39, v169
	v_cvt_pk_bf16_f32 v35, v167, v168
	v_mul_f32_e32 v165, v40, v169
	v_mul_f32_e32 v166, v41, v169
	v_cvt_pk_bf16_f32 v40, v165, v166
	v_mul_f32_e32 v167, v42, v169
	v_mul_f32_e32 v168, v43, v169
	v_cvt_pk_bf16_f32 v41, v167, v168
	v_mul_f32_e32 v165, v44, v169
	v_mul_f32_e32 v166, v45, v169
	v_cvt_pk_bf16_f32 v42, v165, v166
	v_mul_f32_e32 v167, v46, v169
	v_mul_f32_e32 v168, v47, v169
	v_cvt_pk_bf16_f32 v43, v167, v168
	v_mul_f32_e32 v165, v48, v169
	v_mul_f32_e32 v166, v49, v169
	v_cvt_pk_bf16_f32 v48, v165, v166
	v_mul_f32_e32 v167, v50, v169
	v_mul_f32_e32 v168, v51, v169
	v_cvt_pk_bf16_f32 v49, v167, v168
	v_mul_f32_e32 v165, v52, v169
	v_mul_f32_e32 v166, v53, v169
	v_cvt_pk_bf16_f32 v50, v165, v166
	v_mul_f32_e32 v167, v54, v169
	v_mul_f32_e32 v168, v55, v169
	v_cvt_pk_bf16_f32 v51, v167, v168
	v_mul_f32_e32 v165, v56, v169
	v_mul_f32_e32 v166, v57, v169
	v_cvt_pk_bf16_f32 v56, v165, v166
	v_mul_f32_e32 v167, v58, v169
	v_mul_f32_e32 v168, v59, v169
	v_cvt_pk_bf16_f32 v57, v167, v168
	v_mul_f32_e32 v165, v60, v169
	v_mul_f32_e32 v166, v61, v169
	v_cvt_pk_bf16_f32 v58, v165, v166
	v_mul_f32_e32 v167, v62, v169
	v_mul_f32_e32 v168, v63, v169
	v_cvt_pk_bf16_f32 v59, v167, v168
	v_mul_f32_e32 v165, v64, v169
	v_mul_f32_e32 v166, v65, v169
	v_cvt_pk_bf16_f32 v64, v165, v166
	v_mul_f32_e32 v167, v66, v169
	v_mul_f32_e32 v168, v67, v169
	v_cvt_pk_bf16_f32 v65, v167, v168
	v_mul_f32_e32 v165, v68, v169
	v_mul_f32_e32 v166, v69, v169
	v_cvt_pk_bf16_f32 v66, v165, v166
	v_mul_f32_e32 v167, v70, v169
	v_mul_f32_e32 v168, v71, v169
	v_cvt_pk_bf16_f32 v67, v167, v168
	v_mul_f32_e32 v165, v72, v169
	v_mul_f32_e32 v166, v73, v169
	v_cvt_pk_bf16_f32 v72, v165, v166
	v_mul_f32_e32 v167, v74, v169
	v_mul_f32_e32 v168, v75, v169
	v_cvt_pk_bf16_f32 v73, v167, v168
	v_mul_f32_e32 v165, v76, v169
	v_mul_f32_e32 v166, v77, v169
	v_cvt_pk_bf16_f32 v74, v165, v166
	v_mul_f32_e32 v167, v78, v169
	v_mul_f32_e32 v168, v79, v169
	v_cvt_pk_bf16_f32 v75, v167, v168
	v_mul_f32_e32 v165, v80, v169
	v_mul_f32_e32 v166, v81, v169
	v_cvt_pk_bf16_f32 v80, v165, v166
	v_mul_f32_e32 v167, v82, v169
	v_mul_f32_e32 v168, v83, v169
	v_cvt_pk_bf16_f32 v81, v167, v168
	v_mul_f32_e32 v165, v84, v169
	v_mul_f32_e32 v166, v85, v169
	v_cvt_pk_bf16_f32 v82, v165, v166
	v_mul_f32_e32 v167, v86, v169
	v_mul_f32_e32 v168, v87, v169
	v_cvt_pk_bf16_f32 v83, v167, v168
	s_cmp_eq_u32 s11, 0
	s_cselect_b32 s15, 1, 0
	s_add_i32 s15, s15, s12
	s_lshl_b32 s13, s15, 12
	v_add_u32_e32 v162, s13, v157
	global_load_dwordx4 v[88:91], v162, s[6:7] offset:0
	global_load_dwordx4 v[92:95], v162, s[6:7] offset:64
	global_load_dwordx4 v[96:99], v162, s[6:7] offset:128
	global_load_dwordx4 v[100:103], v162, s[6:7] offset:192
	s_add_i32 s18, s14, 64
	s_mov_b64 s[16:17], s[4:5]
	v_add_u32_e32 v161, s18, v156
	ds_read_u16 v0, v161 offset:0
	ds_read_u16 v1, v161 offset:8
	ds_read_u16 v2, v161 offset:16
	ds_read_u16 v3, v161 offset:24
	ds_read_u16 v4, v161 offset:32
	ds_read_u16 v5, v161 offset:40
	ds_read_u16 v6, v161 offset:48
	ds_read_u16 v7, v161 offset:56
	s_waitcnt lgkmcnt(7)
	s_add_i32 m0, s8, 0x2000
	v_lshl_add_u32 v8, v0, 8, v10
	global_load_lds_dwordx4 v8, s[16:17]
	s_waitcnt lgkmcnt(6)
	s_add_i32 m0, s8, 0x2400
	v_lshl_add_u32 v9, v1, 8, v11
	global_load_lds_dwordx4 v9, s[16:17]
	s_waitcnt lgkmcnt(5)
	s_add_i32 m0, s8, 0x2800
	v_lshl_add_u32 v8, v2, 8, v12
	global_load_lds_dwordx4 v8, s[16:17]
	s_waitcnt lgkmcnt(4)
	s_add_i32 m0, s8, 0x2c00
	v_lshl_add_u32 v9, v3, 8, v13
	global_load_lds_dwordx4 v9, s[16:17]
	s_waitcnt lgkmcnt(3)
	s_add_i32 m0, s8, 0x3000
	v_lshl_add_u32 v8, v4, 8, v10
	global_load_lds_dwordx4 v8, s[16:17]
	s_waitcnt lgkmcnt(2)
	s_add_i32 m0, s8, 0x3400
	v_lshl_add_u32 v9, v5, 8, v11
	global_load_lds_dwordx4 v9, s[16:17]
	s_waitcnt lgkmcnt(1)
	s_add_i32 m0, s8, 0x3800
	v_lshl_add_u32 v8, v6, 8, v12
	global_load_lds_dwordx4 v8, s[16:17]
	s_waitcnt lgkmcnt(0)
	s_add_i32 m0, s8, 0x3c00
	v_lshl_add_u32 v9, v7, 8, v13
	global_load_lds_dwordx4 v9, s[16:17]
	s_waitcnt vmcnt(8)
	ds_read_b64_tr_b16 v[104:105], v148 offset:0
	ds_read_b64_tr_b16 v[106:107], v148 offset:4096
	ds_read_b64_tr_b16 v[108:109], v149 offset:0
	ds_read_b64_tr_b16 v[110:111], v149 offset:4096
	ds_read_b64_tr_b16 v[112:113], v150 offset:0
	ds_read_b64_tr_b16 v[114:115], v150 offset:4096
	ds_read_b64_tr_b16 v[116:117], v151 offset:0
	ds_read_b64_tr_b16 v[118:119], v151 offset:4096
	ds_read_b64_tr_b16 v[120:121], v152 offset:0
	ds_read_b64_tr_b16 v[122:123], v152 offset:4096
	ds_read_b64_tr_b16 v[124:125], v153 offset:0
	ds_read_b64_tr_b16 v[126:127], v153 offset:4096
	ds_read_b64_tr_b16 v[128:129], v154 offset:0
	ds_read_b64_tr_b16 v[130:131], v154 offset:4096
	s_waitcnt lgkmcnt(12)
	v_mfma_f32_16x16x32_bf16 v[176:179], v[24:27], v[104:107], 0
	ds_read_b64_tr_b16 v[132:133], v155 offset:0
	ds_read_b64_tr_b16 v[134:135], v155 offset:4096
	s_waitcnt lgkmcnt(12)
	v_mfma_f32_16x16x32_bf16 v[180:183], v[24:27], v[108:111], 0
	s_waitcnt lgkmcnt(10)
	v_mfma_f32_16x16x32_bf16 v[184:187], v[24:27], v[112:115], 0
	s_waitcnt lgkmcnt(8)
	v_mfma_f32_16x16x32_bf16 v[188:191], v[24:27], v[116:119], 0
	s_waitcnt lgkmcnt(6)
	v_mfma_f32_16x16x32_bf16 v[192:195], v[24:27], v[120:123], 0
	s_waitcnt lgkmcnt(4)
	v_mfma_f32_16x16x32_bf16 v[196:199], v[24:27], v[124:127], 0
	s_waitcnt lgkmcnt(2)
	v_mfma_f32_16x16x32_bf16 v[200:203], v[24:27], v[128:131], 0
	s_waitcnt lgkmcnt(0)
	v_mfma_f32_16x16x32_bf16 v[204:207], v[24:27], v[132:135], 0
	s_add_i32 s18, s14, 128
	s_mov_b64 s[16:17], s[4:5]
	v_add_u32_e32 v161, s18, v156
	ds_read_u16 v0, v161 offset:0
	ds_read_u16 v1, v161 offset:8
	ds_read_u16 v2, v161 offset:16
	ds_read_u16 v3, v161 offset:24
	ds_read_u16 v4, v161 offset:32
	ds_read_u16 v5, v161 offset:40
	ds_read_u16 v6, v161 offset:48
	ds_read_u16 v7, v161 offset:56
	s_waitcnt lgkmcnt(7)
	s_add_i32 m0, s8, 0x0
	v_lshl_add_u32 v8, v0, 8, v10
	global_load_lds_dwordx4 v8, s[16:17]
	s_waitcnt lgkmcnt(6)
	s_add_i32 m0, s8, 0x400
	v_lshl_add_u32 v9, v1, 8, v11
	global_load_lds_dwordx4 v9, s[16:17]
	s_waitcnt lgkmcnt(5)
	s_add_i32 m0, s8, 0x800
	v_lshl_add_u32 v8, v2, 8, v12
	global_load_lds_dwordx4 v8, s[16:17]
	s_waitcnt lgkmcnt(4)
	s_add_i32 m0, s8, 0xc00
	v_lshl_add_u32 v9, v3, 8, v13
	global_load_lds_dwordx4 v9, s[16:17]
	s_waitcnt lgkmcnt(3)
	s_add_i32 m0, s8, 0x1000
	v_lshl_add_u32 v8, v4, 8, v10
	global_load_lds_dwordx4 v8, s[16:17]
	s_waitcnt lgkmcnt(2)
	s_add_i32 m0, s8, 0x1400
	v_lshl_add_u32 v9, v5, 8, v11
	global_load_lds_dwordx4 v9, s[16:17]
	s_waitcnt lgkmcnt(1)
	s_add_i32 m0, s8, 0x1800
	v_lshl_add_u32 v8, v6, 8, v12
	global_load_lds_dwordx4 v8, s[16:17]
	s_waitcnt lgkmcnt(0)
	s_add_i32 m0, s8, 0x1c00
	v_lshl_add_u32 v9, v7, 8, v13
	global_load_lds_dwordx4 v9, s[16:17]
	s_waitcnt vmcnt(8)
	ds_read_b64_tr_b16 v[104:105], v148 offset:8192
	ds_read_b64_tr_b16 v[106:107], v148 offset:12288
	ds_read_b64_tr_b16 v[108:109], v149 offset:8192
	ds_read_b64_tr_b16 v[110:111], v149 offset:12288
	ds_read_b64_tr_b16 v[112:113], v150 offset:8192
	ds_read_b64_tr_b16 v[114:115], v150 offset:12288
	ds_read_b64_tr_b16 v[116:117], v151 offset:8192
	ds_read_b64_tr_b16 v[118:119], v151 offset:12288
	ds_read_b64_tr_b16 v[120:121], v152 offset:8192
	ds_read_b64_tr_b16 v[122:123], v152 offset:12288
	ds_read_b64_tr_b16 v[124:125], v153 offset:8192
	ds_read_b64_tr_b16 v[126:127], v153 offset:12288
	ds_read_b64_tr_b16 v[128:129], v154 offset:8192
	ds_read_b64_tr_b16 v[130:131], v154 offset:12288
	s_waitcnt lgkmcnt(12)
	v_mfma_f32_16x16x32_bf16 v[176:179], v[32:35], v[104:107], v[176:179]
	ds_read_b64_tr_b16 v[132:133], v155 offset:8192
	ds_read_b64_tr_b16 v[134:135], v155 offset:12288
	s_waitcnt lgkmcnt(12)
	v_mfma_f32_16x16x32_bf16 v[180:183], v[32:35], v[108:111], v[180:183]
	s_waitcnt lgkmcnt(10)
	v_mfma_f32_16x16x32_bf16 v[184:187], v[32:35], v[112:115], v[184:187]
	s_waitcnt lgkmcnt(8)
	v_mfma_f32_16x16x32_bf16 v[188:191], v[32:35], v[116:119], v[188:191]
	s_waitcnt lgkmcnt(6)
	v_mfma_f32_16x16x32_bf16 v[192:195], v[32:35], v[120:123], v[192:195]
	s_waitcnt lgkmcnt(4)
	v_mfma_f32_16x16x32_bf16 v[196:199], v[32:35], v[124:127], v[196:199]
	s_waitcnt lgkmcnt(2)
	v_mfma_f32_16x16x32_bf16 v[200:203], v[32:35], v[128:131], v[200:203]
	s_waitcnt lgkmcnt(0)
	v_mfma_f32_16x16x32_bf16 v[204:207], v[32:35], v[132:135], v[204:207]
	s_add_i32 s18, s14, 192
	s_mov_b64 s[16:17], s[4:5]
	v_add_u32_e32 v161, s18, v156
	ds_read_u16 v0, v161 offset:0
	ds_read_u16 v1, v161 offset:8
	ds_read_u16 v2, v161 offset:16
	ds_read_u16 v3, v161 offset:24
	ds_read_u16 v4, v161 offset:32
	ds_read_u16 v5, v161 offset:40
	ds_read_u16 v6, v161 offset:48
	ds_read_u16 v7, v161 offset:56
	s_waitcnt lgkmcnt(7)
	s_add_i32 m0, s8, 0x2000
	v_lshl_add_u32 v8, v0, 8, v10
	global_load_lds_dwordx4 v8, s[16:17]
	s_waitcnt lgkmcnt(6)
	s_add_i32 m0, s8, 0x2400
	v_lshl_add_u32 v9, v1, 8, v11
	global_load_lds_dwordx4 v9, s[16:17]
	s_waitcnt lgkmcnt(5)
	s_add_i32 m0, s8, 0x2800
	v_lshl_add_u32 v8, v2, 8, v12
	global_load_lds_dwordx4 v8, s[16:17]
	s_waitcnt lgkmcnt(4)
	s_add_i32 m0, s8, 0x2c00
	v_lshl_add_u32 v9, v3, 8, v13
	global_load_lds_dwordx4 v9, s[16:17]
	s_waitcnt lgkmcnt(3)
	s_add_i32 m0, s8, 0x3000
	v_lshl_add_u32 v8, v4, 8, v10
	global_load_lds_dwordx4 v8, s[16:17]
	s_waitcnt lgkmcnt(2)
	s_add_i32 m0, s8, 0x3400
	v_lshl_add_u32 v9, v5, 8, v11
	global_load_lds_dwordx4 v9, s[16:17]
	s_waitcnt lgkmcnt(1)
	s_add_i32 m0, s8, 0x3800
	v_lshl_add_u32 v8, v6, 8, v12
	global_load_lds_dwordx4 v8, s[16:17]
	s_waitcnt lgkmcnt(0)
	s_add_i32 m0, s8, 0x3c00
	v_lshl_add_u32 v9, v7, 8, v13
	global_load_lds_dwordx4 v9, s[16:17]
	s_waitcnt vmcnt(8)
	ds_read_b64_tr_b16 v[104:105], v148 offset:0
	ds_read_b64_tr_b16 v[106:107], v148 offset:4096
	ds_read_b64_tr_b16 v[108:109], v149 offset:0
	ds_read_b64_tr_b16 v[110:111], v149 offset:4096
	ds_read_b64_tr_b16 v[112:113], v150 offset:0
	ds_read_b64_tr_b16 v[114:115], v150 offset:4096
	ds_read_b64_tr_b16 v[116:117], v151 offset:0
	ds_read_b64_tr_b16 v[118:119], v151 offset:4096
	ds_read_b64_tr_b16 v[120:121], v152 offset:0
	ds_read_b64_tr_b16 v[122:123], v152 offset:4096
	ds_read_b64_tr_b16 v[124:125], v153 offset:0
	ds_read_b64_tr_b16 v[126:127], v153 offset:4096
	ds_read_b64_tr_b16 v[128:129], v154 offset:0
	ds_read_b64_tr_b16 v[130:131], v154 offset:4096
	s_waitcnt lgkmcnt(12)
	v_mfma_f32_16x16x32_bf16 v[176:179], v[40:43], v[104:107], v[176:179]
	ds_read_b64_tr_b16 v[132:133], v155 offset:0
	ds_read_b64_tr_b16 v[134:135], v155 offset:4096
	s_waitcnt lgkmcnt(12)
	v_mfma_f32_16x16x32_bf16 v[180:183], v[40:43], v[108:111], v[180:183]
	s_waitcnt lgkmcnt(10)
	v_mfma_f32_16x16x32_bf16 v[184:187], v[40:43], v[112:115], v[184:187]
	s_waitcnt lgkmcnt(8)
	v_mfma_f32_16x16x32_bf16 v[188:191], v[40:43], v[116:119], v[188:191]
	s_waitcnt lgkmcnt(6)
	v_mfma_f32_16x16x32_bf16 v[192:195], v[40:43], v[120:123], v[192:195]
	s_waitcnt lgkmcnt(4)
	v_mfma_f32_16x16x32_bf16 v[196:199], v[40:43], v[124:127], v[196:199]
	s_waitcnt lgkmcnt(2)
	v_mfma_f32_16x16x32_bf16 v[200:203], v[40:43], v[128:131], v[200:203]
	s_waitcnt lgkmcnt(0)
	v_mfma_f32_16x16x32_bf16 v[204:207], v[40:43], v[132:135], v[204:207]
	s_add_i32 s18, s14, 256
	s_mov_b64 s[16:17], s[4:5]
	v_add_u32_e32 v161, s18, v156
	ds_read_u16 v0, v161 offset:0
	ds_read_u16 v1, v161 offset:8
	ds_read_u16 v2, v161 offset:16
	ds_read_u16 v3, v161 offset:24
	ds_read_u16 v4, v161 offset:32
	ds_read_u16 v5, v161 offset:40
	ds_read_u16 v6, v161 offset:48
	ds_read_u16 v7, v161 offset:56
	s_waitcnt lgkmcnt(7)
	s_add_i32 m0, s8, 0x0
	v_lshl_add_u32 v8, v0, 8, v10
	global_load_lds_dwordx4 v8, s[16:17]
	s_waitcnt lgkmcnt(6)
	s_add_i32 m0, s8, 0x400
	v_lshl_add_u32 v9, v1, 8, v11
	global_load_lds_dwordx4 v9, s[16:17]
	s_waitcnt lgkmcnt(5)
	s_add_i32 m0, s8, 0x800
	v_lshl_add_u32 v8, v2, 8, v12
	global_load_lds_dwordx4 v8, s[16:17]
	s_waitcnt lgkmcnt(4)
	s_add_i32 m0, s8, 0xc00
	v_lshl_add_u32 v9, v3, 8, v13
	global_load_lds_dwordx4 v9, s[16:17]
	s_waitcnt lgkmcnt(3)
	s_add_i32 m0, s8, 0x1000
	v_lshl_add_u32 v8, v4, 8, v10
	global_load_lds_dwordx4 v8, s[16:17]
	s_waitcnt lgkmcnt(2)
	s_add_i32 m0, s8, 0x1400
	v_lshl_add_u32 v9, v5, 8, v11
	global_load_lds_dwordx4 v9, s[16:17]
	s_waitcnt lgkmcnt(1)
	s_add_i32 m0, s8, 0x1800
	v_lshl_add_u32 v8, v6, 8, v12
	global_load_lds_dwordx4 v8, s[16:17]
	s_waitcnt lgkmcnt(0)
	s_add_i32 m0, s8, 0x1c00
	v_lshl_add_u32 v9, v7, 8, v13
	global_load_lds_dwordx4 v9, s[16:17]
	s_waitcnt vmcnt(8)
	ds_read_b64_tr_b16 v[104:105], v148 offset:8192
	ds_read_b64_tr_b16 v[106:107], v148 offset:12288
	ds_read_b64_tr_b16 v[108:109], v149 offset:8192
	ds_read_b64_tr_b16 v[110:111], v149 offset:12288
	ds_read_b64_tr_b16 v[112:113], v150 offset:8192
	ds_read_b64_tr_b16 v[114:115], v150 offset:12288
	ds_read_b64_tr_b16 v[116:117], v151 offset:8192
	ds_read_b64_tr_b16 v[118:119], v151 offset:12288
	ds_read_b64_tr_b16 v[120:121], v152 offset:8192
	ds_read_b64_tr_b16 v[122:123], v152 offset:12288
	ds_read_b64_tr_b16 v[124:125], v153 offset:8192
	ds_read_b64_tr_b16 v[126:127], v153 offset:12288
	ds_read_b64_tr_b16 v[128:129], v154 offset:8192
	ds_read_b64_tr_b16 v[130:131], v154 offset:12288
	s_waitcnt lgkmcnt(12)
	v_mfma_f32_16x16x32_bf16 v[176:179], v[48:51], v[104:107], v[176:179]
	ds_read_b64_tr_b16 v[132:133], v155 offset:8192
	ds_read_b64_tr_b16 v[134:135], v155 offset:12288
	s_waitcnt lgkmcnt(12)
	v_mfma_f32_16x16x32_bf16 v[180:183], v[48:51], v[108:111], v[180:183]
	s_waitcnt lgkmcnt(10)
	v_mfma_f32_16x16x32_bf16 v[184:187], v[48:51], v[112:115], v[184:187]
	s_waitcnt lgkmcnt(8)
	v_mfma_f32_16x16x32_bf16 v[188:191], v[48:51], v[116:119], v[188:191]
	s_waitcnt lgkmcnt(6)
	v_mfma_f32_16x16x32_bf16 v[192:195], v[48:51], v[120:123], v[192:195]
	s_waitcnt lgkmcnt(4)
	v_mfma_f32_16x16x32_bf16 v[196:199], v[48:51], v[124:127], v[196:199]
	s_waitcnt lgkmcnt(2)
	v_mfma_f32_16x16x32_bf16 v[200:203], v[48:51], v[128:131], v[200:203]
	s_waitcnt lgkmcnt(0)
	v_mfma_f32_16x16x32_bf16 v[204:207], v[48:51], v[132:135], v[204:207]
	s_add_i32 s18, s14, 320
	s_mov_b64 s[16:17], s[4:5]
	v_add_u32_e32 v161, s18, v156
	ds_read_u16 v0, v161 offset:0
	ds_read_u16 v1, v161 offset:8
	ds_read_u16 v2, v161 offset:16
	ds_read_u16 v3, v161 offset:24
	ds_read_u16 v4, v161 offset:32
	ds_read_u16 v5, v161 offset:40
	ds_read_u16 v6, v161 offset:48
	ds_read_u16 v7, v161 offset:56
	s_waitcnt lgkmcnt(7)
	s_add_i32 m0, s8, 0x2000
	v_lshl_add_u32 v8, v0, 8, v10
	global_load_lds_dwordx4 v8, s[16:17]
	s_waitcnt lgkmcnt(6)
	s_add_i32 m0, s8, 0x2400
	v_lshl_add_u32 v9, v1, 8, v11
	global_load_lds_dwordx4 v9, s[16:17]
	s_waitcnt lgkmcnt(5)
	s_add_i32 m0, s8, 0x2800
	v_lshl_add_u32 v8, v2, 8, v12
	global_load_lds_dwordx4 v8, s[16:17]
	s_waitcnt lgkmcnt(4)
	s_add_i32 m0, s8, 0x2c00
	v_lshl_add_u32 v9, v3, 8, v13
	global_load_lds_dwordx4 v9, s[16:17]
	s_waitcnt lgkmcnt(3)
	s_add_i32 m0, s8, 0x3000
	v_lshl_add_u32 v8, v4, 8, v10
	global_load_lds_dwordx4 v8, s[16:17]
	s_waitcnt lgkmcnt(2)
	s_add_i32 m0, s8, 0x3400
	v_lshl_add_u32 v9, v5, 8, v11
	global_load_lds_dwordx4 v9, s[16:17]
	s_waitcnt lgkmcnt(1)
	s_add_i32 m0, s8, 0x3800
	v_lshl_add_u32 v8, v6, 8, v12
	global_load_lds_dwordx4 v8, s[16:17]
	s_waitcnt lgkmcnt(0)
	s_add_i32 m0, s8, 0x3c00
	v_lshl_add_u32 v9, v7, 8, v13
	global_load_lds_dwordx4 v9, s[16:17]
	s_waitcnt vmcnt(8)
	ds_read_b64_tr_b16 v[104:105], v148 offset:0
	ds_read_b64_tr_b16 v[106:107], v148 offset:4096
	ds_read_b64_tr_b16 v[108:109], v149 offset:0
	ds_read_b64_tr_b16 v[110:111], v149 offset:4096
	ds_read_b64_tr_b16 v[112:113], v150 offset:0
	ds_read_b64_tr_b16 v[114:115], v150 offset:4096
	ds_read_b64_tr_b16 v[116:117], v151 offset:0
	ds_read_b64_tr_b16 v[118:119], v151 offset:4096
	ds_read_b64_tr_b16 v[120:121], v152 offset:0
	ds_read_b64_tr_b16 v[122:123], v152 offset:4096
	ds_read_b64_tr_b16 v[124:125], v153 offset:0
	ds_read_b64_tr_b16 v[126:127], v153 offset:4096
	ds_read_b64_tr_b16 v[128:129], v154 offset:0
	ds_read_b64_tr_b16 v[130:131], v154 offset:4096
	s_waitcnt lgkmcnt(12)
	v_mfma_f32_16x16x32_bf16 v[176:179], v[56:59], v[104:107], v[176:179]
	ds_read_b64_tr_b16 v[132:133], v155 offset:0
	ds_read_b64_tr_b16 v[134:135], v155 offset:4096
	s_waitcnt lgkmcnt(12)
	v_mfma_f32_16x16x32_bf16 v[180:183], v[56:59], v[108:111], v[180:183]
	s_waitcnt lgkmcnt(10)
	v_mfma_f32_16x16x32_bf16 v[184:187], v[56:59], v[112:115], v[184:187]
	s_waitcnt lgkmcnt(8)
	v_mfma_f32_16x16x32_bf16 v[188:191], v[56:59], v[116:119], v[188:191]
	s_waitcnt lgkmcnt(6)
	v_mfma_f32_16x16x32_bf16 v[192:195], v[56:59], v[120:123], v[192:195]
	s_waitcnt lgkmcnt(4)
	v_mfma_f32_16x16x32_bf16 v[196:199], v[56:59], v[124:127], v[196:199]
	s_waitcnt lgkmcnt(2)
	v_mfma_f32_16x16x32_bf16 v[200:203], v[56:59], v[128:131], v[200:203]
	s_waitcnt lgkmcnt(0)
	v_mfma_f32_16x16x32_bf16 v[204:207], v[56:59], v[132:135], v[204:207]
	s_add_i32 s18, s14, 384
	s_mov_b64 s[16:17], s[4:5]
	v_add_u32_e32 v161, s18, v156
	ds_read_u16 v0, v161 offset:0
	ds_read_u16 v1, v161 offset:8
	ds_read_u16 v2, v161 offset:16
	ds_read_u16 v3, v161 offset:24
	ds_read_u16 v4, v161 offset:32
	ds_read_u16 v5, v161 offset:40
	ds_read_u16 v6, v161 offset:48
	ds_read_u16 v7, v161 offset:56
	s_waitcnt lgkmcnt(7)
	s_add_i32 m0, s8, 0x0
	v_lshl_add_u32 v8, v0, 8, v10
	global_load_lds_dwordx4 v8, s[16:17]
	s_waitcnt lgkmcnt(6)
	s_add_i32 m0, s8, 0x400
	v_lshl_add_u32 v9, v1, 8, v11
	global_load_lds_dwordx4 v9, s[16:17]
	s_waitcnt lgkmcnt(5)
	s_add_i32 m0, s8, 0x800
	v_lshl_add_u32 v8, v2, 8, v12
	global_load_lds_dwordx4 v8, s[16:17]
	s_waitcnt lgkmcnt(4)
	s_add_i32 m0, s8, 0xc00
	v_lshl_add_u32 v9, v3, 8, v13
	global_load_lds_dwordx4 v9, s[16:17]
	s_waitcnt lgkmcnt(3)
	s_add_i32 m0, s8, 0x1000
	v_lshl_add_u32 v8, v4, 8, v10
	global_load_lds_dwordx4 v8, s[16:17]
	s_waitcnt lgkmcnt(2)
	s_add_i32 m0, s8, 0x1400
	v_lshl_add_u32 v9, v5, 8, v11
	global_load_lds_dwordx4 v9, s[16:17]
	s_waitcnt lgkmcnt(1)
	s_add_i32 m0, s8, 0x1800
	v_lshl_add_u32 v8, v6, 8, v12
	global_load_lds_dwordx4 v8, s[16:17]
	s_waitcnt lgkmcnt(0)
	s_add_i32 m0, s8, 0x1c00
	v_lshl_add_u32 v9, v7, 8, v13
	global_load_lds_dwordx4 v9, s[16:17]
	s_waitcnt vmcnt(8)
	ds_read_b64_tr_b16 v[104:105], v148 offset:8192
	ds_read_b64_tr_b16 v[106:107], v148 offset:12288
	ds_read_b64_tr_b16 v[108:109], v149 offset:8192
	ds_read_b64_tr_b16 v[110:111], v149 offset:12288
	ds_read_b64_tr_b16 v[112:113], v150 offset:8192
	ds_read_b64_tr_b16 v[114:115], v150 offset:12288
	ds_read_b64_tr_b16 v[116:117], v151 offset:8192
	ds_read_b64_tr_b16 v[118:119], v151 offset:12288
	ds_read_b64_tr_b16 v[120:121], v152 offset:8192
	ds_read_b64_tr_b16 v[122:123], v152 offset:12288
	ds_read_b64_tr_b16 v[124:125], v153 offset:8192
	ds_read_b64_tr_b16 v[126:127], v153 offset:12288
	ds_read_b64_tr_b16 v[128:129], v154 offset:8192
	ds_read_b64_tr_b16 v[130:131], v154 offset:12288
	s_waitcnt lgkmcnt(12)
	v_mfma_f32_16x16x32_bf16 v[176:179], v[64:67], v[104:107], v[176:179]
	ds_read_b64_tr_b16 v[132:133], v155 offset:8192
	ds_read_b64_tr_b16 v[134:135], v155 offset:12288
	s_waitcnt lgkmcnt(12)
	v_mfma_f32_16x16x32_bf16 v[180:183], v[64:67], v[108:111], v[180:183]
	s_waitcnt lgkmcnt(10)
	v_mfma_f32_16x16x32_bf16 v[184:187], v[64:67], v[112:115], v[184:187]
	s_waitcnt lgkmcnt(8)
	v_mfma_f32_16x16x32_bf16 v[188:191], v[64:67], v[116:119], v[188:191]
	s_waitcnt lgkmcnt(6)
	v_mfma_f32_16x16x32_bf16 v[192:195], v[64:67], v[120:123], v[192:195]
	s_waitcnt lgkmcnt(4)
	v_mfma_f32_16x16x32_bf16 v[196:199], v[64:67], v[124:127], v[196:199]
	s_waitcnt lgkmcnt(2)
	v_mfma_f32_16x16x32_bf16 v[200:203], v[64:67], v[128:131], v[200:203]
	s_waitcnt lgkmcnt(0)
	v_mfma_f32_16x16x32_bf16 v[204:207], v[64:67], v[132:135], v[204:207]
	s_add_i32 s18, s14, 448
	s_mov_b64 s[16:17], s[4:5]
	v_add_u32_e32 v161, s18, v156
	ds_read_u16 v0, v161 offset:0
	ds_read_u16 v1, v161 offset:8
	ds_read_u16 v2, v161 offset:16
	ds_read_u16 v3, v161 offset:24
	ds_read_u16 v4, v161 offset:32
	ds_read_u16 v5, v161 offset:40
	ds_read_u16 v6, v161 offset:48
	ds_read_u16 v7, v161 offset:56
	s_waitcnt lgkmcnt(7)
	s_add_i32 m0, s8, 0x2000
	v_lshl_add_u32 v8, v0, 8, v10
	global_load_lds_dwordx4 v8, s[16:17]
	s_waitcnt lgkmcnt(6)
	s_add_i32 m0, s8, 0x2400
	v_lshl_add_u32 v9, v1, 8, v11
	global_load_lds_dwordx4 v9, s[16:17]
	s_waitcnt lgkmcnt(5)
	s_add_i32 m0, s8, 0x2800
	v_lshl_add_u32 v8, v2, 8, v12
	global_load_lds_dwordx4 v8, s[16:17]
	s_waitcnt lgkmcnt(4)
	s_add_i32 m0, s8, 0x2c00
	v_lshl_add_u32 v9, v3, 8, v13
	global_load_lds_dwordx4 v9, s[16:17]
	s_waitcnt lgkmcnt(3)
	s_add_i32 m0, s8, 0x3000
	v_lshl_add_u32 v8, v4, 8, v10
	global_load_lds_dwordx4 v8, s[16:17]
	s_waitcnt lgkmcnt(2)
	s_add_i32 m0, s8, 0x3400
	v_lshl_add_u32 v9, v5, 8, v11
	global_load_lds_dwordx4 v9, s[16:17]
	s_waitcnt lgkmcnt(1)
	s_add_i32 m0, s8, 0x3800
	v_lshl_add_u32 v8, v6, 8, v12
	global_load_lds_dwordx4 v8, s[16:17]
	s_waitcnt lgkmcnt(0)
	s_add_i32 m0, s8, 0x3c00
	v_lshl_add_u32 v9, v7, 8, v13
	global_load_lds_dwordx4 v9, s[16:17]
	s_waitcnt vmcnt(8)
	ds_read_b64_tr_b16 v[104:105], v148 offset:0
	ds_read_b64_tr_b16 v[106:107], v148 offset:4096
	ds_read_b64_tr_b16 v[108:109], v149 offset:0
	ds_read_b64_tr_b16 v[110:111], v149 offset:4096
	ds_read_b64_tr_b16 v[112:113], v150 offset:0
	ds_read_b64_tr_b16 v[114:115], v150 offset:4096
	ds_read_b64_tr_b16 v[116:117], v151 offset:0
	ds_read_b64_tr_b16 v[118:119], v151 offset:4096
	ds_read_b64_tr_b16 v[120:121], v152 offset:0
	ds_read_b64_tr_b16 v[122:123], v152 offset:4096
	ds_read_b64_tr_b16 v[124:125], v153 offset:0
	ds_read_b64_tr_b16 v[126:127], v153 offset:4096
	ds_read_b64_tr_b16 v[128:129], v154 offset:0
	ds_read_b64_tr_b16 v[130:131], v154 offset:4096
	s_waitcnt lgkmcnt(12)
	v_mfma_f32_16x16x32_bf16 v[176:179], v[72:75], v[104:107], v[176:179]
	ds_read_b64_tr_b16 v[132:133], v155 offset:0
	ds_read_b64_tr_b16 v[134:135], v155 offset:4096
	s_waitcnt lgkmcnt(12)
	v_mfma_f32_16x16x32_bf16 v[180:183], v[72:75], v[108:111], v[180:183]
	s_waitcnt lgkmcnt(10)
	v_mfma_f32_16x16x32_bf16 v[184:187], v[72:75], v[112:115], v[184:187]
	s_waitcnt lgkmcnt(8)
	v_mfma_f32_16x16x32_bf16 v[188:191], v[72:75], v[116:119], v[188:191]
	s_waitcnt lgkmcnt(6)
	v_mfma_f32_16x16x32_bf16 v[192:195], v[72:75], v[120:123], v[192:195]
	s_waitcnt lgkmcnt(4)
	v_mfma_f32_16x16x32_bf16 v[196:199], v[72:75], v[124:127], v[196:199]
	s_waitcnt lgkmcnt(2)
	v_mfma_f32_16x16x32_bf16 v[200:203], v[72:75], v[128:131], v[200:203]
	s_waitcnt lgkmcnt(0)
	v_mfma_f32_16x16x32_bf16 v[204:207], v[72:75], v[132:135], v[204:207]
	s_cmp_eq_u32 s11, 0
	s_cselect_b32 s18, 512, 0
	s_add_i32 s18, s18, s14
	s_mov_b64 s[16:17], s[2:3]
	v_add_u32_e32 v161, s18, v156
	ds_read_u16 v0, v161 offset:0
	ds_read_u16 v1, v161 offset:8
	ds_read_u16 v2, v161 offset:16
	ds_read_u16 v3, v161 offset:24
	ds_read_u16 v4, v161 offset:32
	ds_read_u16 v5, v161 offset:40
	ds_read_u16 v6, v161 offset:48
	ds_read_u16 v7, v161 offset:56
	s_waitcnt lgkmcnt(7)
	s_add_i32 m0, s8, 0x0
	v_lshl_add_u32 v8, v0, 8, v10
	global_load_lds_dwordx4 v8, s[16:17]
	s_waitcnt lgkmcnt(6)
	s_add_i32 m0, s8, 0x400
	v_lshl_add_u32 v9, v1, 8, v11
	global_load_lds_dwordx4 v9, s[16:17]
	s_waitcnt lgkmcnt(5)
	s_add_i32 m0, s8, 0x800
	v_lshl_add_u32 v8, v2, 8, v12
	global_load_lds_dwordx4 v8, s[16:17]
	s_waitcnt lgkmcnt(4)
	s_add_i32 m0, s8, 0xc00
	v_lshl_add_u32 v9, v3, 8, v13
	global_load_lds_dwordx4 v9, s[16:17]
	s_waitcnt lgkmcnt(3)
	s_add_i32 m0, s8, 0x1000
	v_lshl_add_u32 v8, v4, 8, v10
	global_load_lds_dwordx4 v8, s[16:17]
	s_waitcnt lgkmcnt(2)
	s_add_i32 m0, s8, 0x1400
	v_lshl_add_u32 v9, v5, 8, v11
	global_load_lds_dwordx4 v9, s[16:17]
	s_waitcnt lgkmcnt(1)
	s_add_i32 m0, s8, 0x1800
	v_lshl_add_u32 v8, v6, 8, v12
	global_load_lds_dwordx4 v8, s[16:17]
	s_waitcnt lgkmcnt(0)
	s_add_i32 m0, s8, 0x1c00
	v_lshl_add_u32 v9, v7, 8, v13
	global_load_lds_dwordx4 v9, s[16:17]
	s_waitcnt vmcnt(8)
	ds_read_b64_tr_b16 v[104:105], v148 offset:8192
	ds_read_b64_tr_b16 v[106:107], v148 offset:12288
	ds_read_b64_tr_b16 v[108:109], v149 offset:8192
	ds_read_b64_tr_b16 v[110:111], v149 offset:12288
	ds_read_b64_tr_b16 v[112:113], v150 offset:8192
	ds_read_b64_tr_b16 v[114:115], v150 offset:12288
	ds_read_b64_tr_b16 v[116:117], v151 offset:8192
	ds_read_b64_tr_b16 v[118:119], v151 offset:12288
	ds_read_b64_tr_b16 v[120:121], v152 offset:8192
	ds_read_b64_tr_b16 v[122:123], v152 offset:12288
	ds_read_b64_tr_b16 v[124:125], v153 offset:8192
	ds_read_b64_tr_b16 v[126:127], v153 offset:12288
	ds_read_b64_tr_b16 v[128:129], v154 offset:8192
	ds_read_b64_tr_b16 v[130:131], v154 offset:12288
	s_waitcnt lgkmcnt(12)
	v_mfma_f32_16x16x32_bf16 v[176:179], v[80:83], v[104:107], v[176:179]
	ds_read_b64_tr_b16 v[132:133], v155 offset:8192
	ds_read_b64_tr_b16 v[134:135], v155 offset:12288
	s_waitcnt lgkmcnt(12)
	v_mfma_f32_16x16x32_bf16 v[180:183], v[80:83], v[108:111], v[180:183]
	s_waitcnt lgkmcnt(10)
	v_mfma_f32_16x16x32_bf16 v[184:187], v[80:83], v[112:115], v[184:187]
	s_waitcnt lgkmcnt(8)
	v_mfma_f32_16x16x32_bf16 v[188:191], v[80:83], v[116:119], v[188:191]
	s_waitcnt lgkmcnt(6)
	v_mfma_f32_16x16x32_bf16 v[192:195], v[80:83], v[120:123], v[192:195]
	s_waitcnt lgkmcnt(4)
	v_mfma_f32_16x16x32_bf16 v[196:199], v[80:83], v[124:127], v[196:199]
	s_waitcnt lgkmcnt(2)
	v_mfma_f32_16x16x32_bf16 v[200:203], v[80:83], v[128:131], v[200:203]
	s_waitcnt lgkmcnt(0)
	v_mfma_f32_16x16x32_bf16 v[204:207], v[80:83], v[132:135], v[204:207]
	s_nop 7
	s_mov_b32 exec_lo, -1
	s_mov_b32 exec_hi, 0
	v_cvt_pk_bf16_f32 v165, v176, 0
	ds_write_b16 v158, v165 offset:0
	v_cvt_pk_bf16_f32 v166, v177, 0
	ds_write_b16 v158, v166 offset:256
	v_cvt_pk_bf16_f32 v167, v178, 0
	ds_write_b16 v158, v167 offset:512
	v_cvt_pk_bf16_f32 v168, v179, 0
	ds_write_b16 v158, v168 offset:768
	v_cvt_pk_bf16_f32 v165, v180, 0
	ds_write_b16 v158, v165 offset:32
	v_cvt_pk_bf16_f32 v166, v181, 0
	ds_write_b16 v158, v166 offset:288
	v_cvt_pk_bf16_f32 v167, v182, 0
	ds_write_b16 v158, v167 offset:544
	v_cvt_pk_bf16_f32 v168, v183, 0
	ds_write_b16 v158, v168 offset:800
	v_cvt_pk_bf16_f32 v165, v184, 0
	ds_write_b16 v158, v165 offset:64
	v_cvt_pk_bf16_f32 v166, v185, 0
	ds_write_b16 v158, v166 offset:320
	v_cvt_pk_bf16_f32 v167, v186, 0
	ds_write_b16 v158, v167 offset:576
	v_cvt_pk_bf16_f32 v168, v187, 0
	ds_write_b16 v158, v168 offset:832
	v_cvt_pk_bf16_f32 v165, v188, 0
	ds_write_b16 v158, v165 offset:96
	v_cvt_pk_bf16_f32 v166, v189, 0
	ds_write_b16 v158, v166 offset:352
	v_cvt_pk_bf16_f32 v167, v190, 0
	ds_write_b16 v158, v167 offset:608
	v_cvt_pk_bf16_f32 v168, v191, 0
	ds_write_b16 v158, v168 offset:864
	v_cvt_pk_bf16_f32 v165, v192, 0
	ds_write_b16 v158, v165 offset:128
	v_cvt_pk_bf16_f32 v166, v193, 0
	ds_write_b16 v158, v166 offset:384
	v_cvt_pk_bf16_f32 v167, v194, 0
	ds_write_b16 v158, v167 offset:640
	v_cvt_pk_bf16_f32 v168, v195, 0
	ds_write_b16 v158, v168 offset:896
	v_cvt_pk_bf16_f32 v165, v196, 0
	ds_write_b16 v158, v165 offset:160
	v_cvt_pk_bf16_f32 v166, v197, 0
	ds_write_b16 v158, v166 offset:416
	v_cvt_pk_bf16_f32 v167, v198, 0
	ds_write_b16 v158, v167 offset:672
	v_cvt_pk_bf16_f32 v168, v199, 0
	ds_write_b16 v158, v168 offset:928
	v_cvt_pk_bf16_f32 v165, v200, 0
	ds_write_b16 v158, v165 offset:192
	v_cvt_pk_bf16_f32 v166, v201, 0
	ds_write_b16 v158, v166 offset:448
	v_cvt_pk_bf16_f32 v167, v202, 0
	ds_write_b16 v158, v167 offset:704
	v_cvt_pk_bf16_f32 v168, v203, 0
	ds_write_b16 v158, v168 offset:960
	v_cvt_pk_bf16_f32 v165, v204, 0
	ds_write_b16 v158, v165 offset:224
	v_cvt_pk_bf16_f32 v166, v205, 0
	ds_write_b16 v158, v166 offset:480
	v_cvt_pk_bf16_f32 v167, v206, 0
	ds_write_b16 v158, v167 offset:736
	v_cvt_pk_bf16_f32 v168, v207, 0
	ds_write_b16 v158, v168 offset:992
	s_mov_b64 exec, -1
	s_waitcnt lgkmcnt(0)
	ds_read_b128 v[104:107], v159
	ds_read_b128 v[108:111], v159 offset:1024
	s_lshl_b32 s13, s12, 12
	v_add_u32_e32 v162, s13, v160
	s_waitcnt lgkmcnt(1)
	global_store_dwordx4 v162, v[104:107], s[6:7]
	s_waitcnt lgkmcnt(0)
	global_store_dwordx4 v162, v[108:111], s[6:7] offset:1024
	s_add_i32 s11, s11, 1
	s_add_i32 s12, s12, 1
	s_addk_i32 s14, 0x200
	s_cmp_lt_u32 s11, 2
	s_cbranch_scc1 .Lattn_q8
	s_branch .Lattn_done

.Lattn_q6:
	s_add_i32 s18, s14, 64
	s_mov_b64 s[16:17], s[2:3]
	v_add_u32_e32 v161, s18, v156
	ds_read_u16 v0, v161 offset:0
	ds_read_u16 v1, v161 offset:8
	ds_read_u16 v2, v161 offset:16
	ds_read_u16 v3, v161 offset:24
	ds_read_u16 v4, v161 offset:32
	ds_read_u16 v5, v161 offset:40
	ds_read_u16 v6, v161 offset:48
	ds_read_u16 v7, v161 offset:56
	s_waitcnt lgkmcnt(7)
	s_add_i32 m0, s8, 0x2000
	v_lshl_add_u32 v8, v0, 8, v10
	global_load_lds_dwordx4 v8, s[16:17]
	s_waitcnt lgkmcnt(6)
	s_add_i32 m0, s8, 0x2400
	v_lshl_add_u32 v9, v1, 8, v11
	global_load_lds_dwordx4 v9, s[16:17]
	s_waitcnt lgkmcnt(5)
	s_add_i32 m0, s8, 0x2800
	v_lshl_add_u32 v8, v2, 8, v12
	global_load_lds_dwordx4 v8, s[16:17]
	s_waitcnt lgkmcnt(4)
	s_add_i32 m0, s8, 0x2c00
	v_lshl_add_u32 v9, v3, 8, v13
	global_load_lds_dwordx4 v9, s[16:17]
	s_waitcnt lgkmcnt(3)
	s_add_i32 m0, s8, 0x3000
	v_lshl_add_u32 v8, v4, 8, v10
	global_load_lds_dwordx4 v8, s[16:17]
	s_waitcnt lgkmcnt(2)
	s_add_i32 m0, s8, 0x3400
	v_lshl_add_u32 v9, v5, 8, v11
	global_load_lds_dwordx4 v9, s[16:17]
	s_waitcnt lgkmcnt(1)
	s_add_i32 m0, s8, 0x3800
	v_lshl_add_u32 v8, v6, 8, v12
	global_load_lds_dwordx4 v8, s[16:17]
	s_waitcnt lgkmcnt(0)
	s_add_i32 m0, s8, 0x3c00
	v_lshl_add_u32 v9, v7, 8, v13
	global_load_lds_dwordx4 v9, s[16:17]
	s_waitcnt vmcnt(8)
	ds_read_b128 v[104:107], v18 offset:0
	ds_read_b128 v[108:111], v19 offset:0
	ds_read_b128 v[112:115], v20 offset:0
	ds_read_b128 v[116:119], v21 offset:0
	ds_read_b128 v[120:123], v18 offset:4096
	ds_read_b128 v[124:127], v19 offset:4096
	ds_read_b128 v[128:131], v20 offset:4096
	ds_read_b128 v[132:135], v21 offset:4096
	s_waitcnt lgkmcnt(7)
	v_mfma_f32_16x16x32_bf16 v[136:139], v[104:107], v[88:91], 0
	s_waitcnt lgkmcnt(6)
	v_mfma_f32_16x16x32_bf16 v[136:139], v[108:111], v[92:95], v[136:139]
	s_waitcnt lgkmcnt(5)
	v_mfma_f32_16x16x32_bf16 v[136:139], v[112:115], v[96:99], v[136:139]
	s_waitcnt lgkmcnt(4)
	v_mfma_f32_16x16x32_bf16 v[136:139], v[116:119], v[100:103], v[136:139]
	s_waitcnt lgkmcnt(3)
	v_mfma_f32_16x16x32_bf16 v[140:143], v[120:123], v[88:91], 0
	s_waitcnt lgkmcnt(2)
	v_mfma_f32_16x16x32_bf16 v[140:143], v[124:127], v[92:95], v[140:143]
	s_waitcnt lgkmcnt(1)
	v_mfma_f32_16x16x32_bf16 v[140:143], v[128:131], v[96:99], v[140:143]
	s_waitcnt lgkmcnt(0)
	v_mfma_f32_16x16x32_bf16 v[140:143], v[132:135], v[100:103], v[140:143]
	v_mul_f32_e32 v24, 0x3db504f3, v136
	v_mul_f32_e32 v25, 0x3db504f3, v137
	v_mul_f32_e32 v26, 0x3db504f3, v138
	v_mul_f32_e32 v27, 0x3db504f3, v139
	s_nop 3
	v_mul_f32_e32 v28, 0x3db504f3, v140
	v_mul_f32_e32 v29, 0x3db504f3, v141
	v_mul_f32_e32 v30, 0x3db504f3, v142
	v_mul_f32_e32 v31, 0x3db504f3, v143
	s_add_i32 s18, s14, 128
	s_mov_b64 s[16:17], s[2:3]
	v_add_u32_e32 v161, s18, v156
	ds_read_u16 v0, v161 offset:0
	ds_read_u16 v1, v161 offset:8
	ds_read_u16 v2, v161 offset:16
	ds_read_u16 v3, v161 offset:24
	ds_read_u16 v4, v161 offset:32
	ds_read_u16 v5, v161 offset:40
	ds_read_u16 v6, v161 offset:48
	ds_read_u16 v7, v161 offset:56
	s_waitcnt lgkmcnt(7)
	s_add_i32 m0, s8, 0x0
	v_lshl_add_u32 v8, v0, 8, v10
	global_load_lds_dwordx4 v8, s[16:17]
	s_waitcnt lgkmcnt(6)
	s_add_i32 m0, s8, 0x400
	v_lshl_add_u32 v9, v1, 8, v11
	global_load_lds_dwordx4 v9, s[16:17]
	s_waitcnt lgkmcnt(5)
	s_add_i32 m0, s8, 0x800
	v_lshl_add_u32 v8, v2, 8, v12
	global_load_lds_dwordx4 v8, s[16:17]
	s_waitcnt lgkmcnt(4)
	s_add_i32 m0, s8, 0xc00
	v_lshl_add_u32 v9, v3, 8, v13
	global_load_lds_dwordx4 v9, s[16:17]
	s_waitcnt lgkmcnt(3)
	s_add_i32 m0, s8, 0x1000
	v_lshl_add_u32 v8, v4, 8, v10
	global_load_lds_dwordx4 v8, s[16:17]
	s_waitcnt lgkmcnt(2)
	s_add_i32 m0, s8, 0x1400
	v_lshl_add_u32 v9, v5, 8, v11
	global_load_lds_dwordx4 v9, s[16:17]
	s_waitcnt lgkmcnt(1)
	s_add_i32 m0, s8, 0x1800
	v_lshl_add_u32 v8, v6, 8, v12
	global_load_lds_dwordx4 v8, s[16:17]
	s_waitcnt lgkmcnt(0)
	s_add_i32 m0, s8, 0x1c00
	v_lshl_add_u32 v9, v7, 8, v13
	global_load_lds_dwordx4 v9, s[16:17]
	s_waitcnt vmcnt(8)
	ds_read_b128 v[104:107], v18 offset:8192
	ds_read_b128 v[108:111], v19 offset:8192
	ds_read_b128 v[112:115], v20 offset:8192
	ds_read_b128 v[116:119], v21 offset:8192
	ds_read_b128 v[120:123], v18 offset:12288
	ds_read_b128 v[124:127], v19 offset:12288
	ds_read_b128 v[128:131], v20 offset:12288
	ds_read_b128 v[132:135], v21 offset:12288
	s_waitcnt lgkmcnt(7)
	v_mfma_f32_16x16x32_bf16 v[136:139], v[104:107], v[88:91], 0
	s_waitcnt lgkmcnt(6)
	v_mfma_f32_16x16x32_bf16 v[136:139], v[108:111], v[92:95], v[136:139]
	s_waitcnt lgkmcnt(5)
	v_mfma_f32_16x16x32_bf16 v[136:139], v[112:115], v[96:99], v[136:139]
	s_waitcnt lgkmcnt(4)
	v_mfma_f32_16x16x32_bf16 v[136:139], v[116:119], v[100:103], v[136:139]
	s_waitcnt lgkmcnt(3)
	v_mfma_f32_16x16x32_bf16 v[140:143], v[120:123], v[88:91], 0
	s_waitcnt lgkmcnt(2)
	v_mfma_f32_16x16x32_bf16 v[140:143], v[124:127], v[92:95], v[140:143]
	s_waitcnt lgkmcnt(1)
	v_mfma_f32_16x16x32_bf16 v[140:143], v[128:131], v[96:99], v[140:143]
	s_waitcnt lgkmcnt(0)
	v_mfma_f32_16x16x32_bf16 v[140:143], v[132:135], v[100:103], v[140:143]
	v_mul_f32_e32 v32, 0x3db504f3, v136
	v_mul_f32_e32 v33, 0x3db504f3, v137
	v_mul_f32_e32 v34, 0x3db504f3, v138
	v_mul_f32_e32 v35, 0x3db504f3, v139
	s_nop 3
	v_mul_f32_e32 v36, 0x3db504f3, v140
	v_mul_f32_e32 v37, 0x3db504f3, v141
	v_mul_f32_e32 v38, 0x3db504f3, v142
	v_mul_f32_e32 v39, 0x3db504f3, v143
	s_add_i32 s18, s14, 192
	s_mov_b64 s[16:17], s[2:3]
	v_add_u32_e32 v161, s18, v156
	ds_read_u16 v0, v161 offset:0
	ds_read_u16 v1, v161 offset:8
	ds_read_u16 v2, v161 offset:16
	ds_read_u16 v3, v161 offset:24
	ds_read_u16 v4, v161 offset:32
	ds_read_u16 v5, v161 offset:40
	ds_read_u16 v6, v161 offset:48
	ds_read_u16 v7, v161 offset:56
	s_waitcnt lgkmcnt(7)
	s_add_i32 m0, s8, 0x2000
	v_lshl_add_u32 v8, v0, 8, v10
	global_load_lds_dwordx4 v8, s[16:17]
	s_waitcnt lgkmcnt(6)
	s_add_i32 m0, s8, 0x2400
	v_lshl_add_u32 v9, v1, 8, v11
	global_load_lds_dwordx4 v9, s[16:17]
	s_waitcnt lgkmcnt(5)
	s_add_i32 m0, s8, 0x2800
	v_lshl_add_u32 v8, v2, 8, v12
	global_load_lds_dwordx4 v8, s[16:17]
	s_waitcnt lgkmcnt(4)
	s_add_i32 m0, s8, 0x2c00
	v_lshl_add_u32 v9, v3, 8, v13
	global_load_lds_dwordx4 v9, s[16:17]
	s_waitcnt lgkmcnt(3)
	s_add_i32 m0, s8, 0x3000
	v_lshl_add_u32 v8, v4, 8, v10
	global_load_lds_dwordx4 v8, s[16:17]
	s_waitcnt lgkmcnt(2)
	s_add_i32 m0, s8, 0x3400
	v_lshl_add_u32 v9, v5, 8, v11
	global_load_lds_dwordx4 v9, s[16:17]
	s_waitcnt lgkmcnt(1)
	s_add_i32 m0, s8, 0x3800
	v_lshl_add_u32 v8, v6, 8, v12
	global_load_lds_dwordx4 v8, s[16:17]
	s_waitcnt lgkmcnt(0)
	s_add_i32 m0, s8, 0x3c00
	v_lshl_add_u32 v9, v7, 8, v13
	global_load_lds_dwordx4 v9, s[16:17]
	s_waitcnt vmcnt(8)
	ds_read_b128 v[104:107], v18 offset:0
	ds_read_b128 v[108:111], v19 offset:0
	ds_read_b128 v[112:115], v20 offset:0
	ds_read_b128 v[116:119], v21 offset:0
	ds_read_b128 v[120:123], v18 offset:4096
	ds_read_b128 v[124:127], v19 offset:4096
	ds_read_b128 v[128:131], v20 offset:4096
	ds_read_b128 v[132:135], v21 offset:4096
	s_waitcnt lgkmcnt(7)
	v_mfma_f32_16x16x32_bf16 v[136:139], v[104:107], v[88:91], 0
	s_waitcnt lgkmcnt(6)
	v_mfma_f32_16x16x32_bf16 v[136:139], v[108:111], v[92:95], v[136:139]
	s_waitcnt lgkmcnt(5)
	v_mfma_f32_16x16x32_bf16 v[136:139], v[112:115], v[96:99], v[136:139]
	s_waitcnt lgkmcnt(4)
	v_mfma_f32_16x16x32_bf16 v[136:139], v[116:119], v[100:103], v[136:139]
	s_waitcnt lgkmcnt(3)
	v_mfma_f32_16x16x32_bf16 v[140:143], v[120:123], v[88:91], 0
	s_waitcnt lgkmcnt(2)
	v_mfma_f32_16x16x32_bf16 v[140:143], v[124:127], v[92:95], v[140:143]
	s_waitcnt lgkmcnt(1)
	v_mfma_f32_16x16x32_bf16 v[140:143], v[128:131], v[96:99], v[140:143]
	s_waitcnt lgkmcnt(0)
	v_mfma_f32_16x16x32_bf16 v[140:143], v[132:135], v[100:103], v[140:143]
	v_mul_f32_e32 v40, 0x3db504f3, v136
	v_mul_f32_e32 v41, 0x3db504f3, v137
	v_mul_f32_e32 v42, 0x3db504f3, v138
	v_mul_f32_e32 v43, 0x3db504f3, v139
	s_nop 3
	v_mul_f32_e32 v44, 0x3db504f3, v140
	v_mul_f32_e32 v45, 0x3db504f3, v141
	v_mul_f32_e32 v46, 0x3db504f3, v142
	v_mul_f32_e32 v47, 0x3db504f3, v143
	s_add_i32 s18, s14, 256
	s_mov_b64 s[16:17], s[2:3]
	v_add_u32_e32 v161, s18, v156
	ds_read_u16 v0, v161 offset:0
	ds_read_u16 v1, v161 offset:8
	ds_read_u16 v2, v161 offset:16
	ds_read_u16 v3, v161 offset:24
	ds_read_u16 v4, v161 offset:32
	ds_read_u16 v5, v161 offset:40
	ds_read_u16 v6, v161 offset:48
	ds_read_u16 v7, v161 offset:56
	s_waitcnt lgkmcnt(7)
	s_add_i32 m0, s8, 0x0
	v_lshl_add_u32 v8, v0, 8, v10
	global_load_lds_dwordx4 v8, s[16:17]
	s_waitcnt lgkmcnt(6)
	s_add_i32 m0, s8, 0x400
	v_lshl_add_u32 v9, v1, 8, v11
	global_load_lds_dwordx4 v9, s[16:17]
	s_waitcnt lgkmcnt(5)
	s_add_i32 m0, s8, 0x800
	v_lshl_add_u32 v8, v2, 8, v12
	global_load_lds_dwordx4 v8, s[16:17]
	s_waitcnt lgkmcnt(4)
	s_add_i32 m0, s8, 0xc00
	v_lshl_add_u32 v9, v3, 8, v13
	global_load_lds_dwordx4 v9, s[16:17]
	s_waitcnt lgkmcnt(3)
	s_add_i32 m0, s8, 0x1000
	v_lshl_add_u32 v8, v4, 8, v10
	global_load_lds_dwordx4 v8, s[16:17]
	s_waitcnt lgkmcnt(2)
	s_add_i32 m0, s8, 0x1400
	v_lshl_add_u32 v9, v5, 8, v11
	global_load_lds_dwordx4 v9, s[16:17]
	s_waitcnt lgkmcnt(1)
	s_add_i32 m0, s8, 0x1800
	v_lshl_add_u32 v8, v6, 8, v12
	global_load_lds_dwordx4 v8, s[16:17]
	s_waitcnt lgkmcnt(0)
	s_add_i32 m0, s8, 0x1c00
	v_lshl_add_u32 v9, v7, 8, v13
	global_load_lds_dwordx4 v9, s[16:17]
	s_waitcnt vmcnt(8)
	ds_read_b128 v[104:107], v18 offset:8192
	ds_read_b128 v[108:111], v19 offset:8192
	ds_read_b128 v[112:115], v20 offset:8192
	ds_read_b128 v[116:119], v21 offset:8192
	ds_read_b128 v[120:123], v18 offset:12288
	ds_read_b128 v[124:127], v19 offset:12288
	ds_read_b128 v[128:131], v20 offset:12288
	ds_read_b128 v[132:135], v21 offset:12288
	s_waitcnt lgkmcnt(7)
	v_mfma_f32_16x16x32_bf16 v[136:139], v[104:107], v[88:91], 0
	s_waitcnt lgkmcnt(6)
	v_mfma_f32_16x16x32_bf16 v[136:139], v[108:111], v[92:95], v[136:139]
	s_waitcnt lgkmcnt(5)
	v_mfma_f32_16x16x32_bf16 v[136:139], v[112:115], v[96:99], v[136:139]
	s_waitcnt lgkmcnt(4)
	v_mfma_f32_16x16x32_bf16 v[136:139], v[116:119], v[100:103], v[136:139]
	s_waitcnt lgkmcnt(3)
	v_mfma_f32_16x16x32_bf16 v[140:143], v[120:123], v[88:91], 0
	s_waitcnt lgkmcnt(2)
	v_mfma_f32_16x16x32_bf16 v[140:143], v[124:127], v[92:95], v[140:143]
	s_waitcnt lgkmcnt(1)
	v_mfma_f32_16x16x32_bf16 v[140:143], v[128:131], v[96:99], v[140:143]
	s_waitcnt lgkmcnt(0)
	v_mfma_f32_16x16x32_bf16 v[140:143], v[132:135], v[100:103], v[140:143]
	v_mul_f32_e32 v48, 0x3db504f3, v136
	v_mul_f32_e32 v49, 0x3db504f3, v137
	v_mul_f32_e32 v50, 0x3db504f3, v138
	v_mul_f32_e32 v51, 0x3db504f3, v139
	s_nop 3
	v_mul_f32_e32 v52, 0x3db504f3, v140
	v_mul_f32_e32 v53, 0x3db504f3, v141
	v_mul_f32_e32 v54, 0x3db504f3, v142
	v_mul_f32_e32 v55, 0x3db504f3, v143
	s_add_i32 s18, s14, 320
	s_mov_b64 s[16:17], s[2:3]
	v_add_u32_e32 v161, s18, v156
	ds_read_u16 v0, v161 offset:0
	ds_read_u16 v1, v161 offset:8
	ds_read_u16 v2, v161 offset:16
	ds_read_u16 v3, v161 offset:24
	ds_read_u16 v4, v161 offset:32
	ds_read_u16 v5, v161 offset:40
	ds_read_u16 v6, v161 offset:48
	ds_read_u16 v7, v161 offset:56
	s_waitcnt lgkmcnt(7)
	s_add_i32 m0, s8, 0x2000
	v_lshl_add_u32 v8, v0, 8, v10
	global_load_lds_dwordx4 v8, s[16:17]
	s_waitcnt lgkmcnt(6)
	s_add_i32 m0, s8, 0x2400
	v_lshl_add_u32 v9, v1, 8, v11
	global_load_lds_dwordx4 v9, s[16:17]
	s_waitcnt lgkmcnt(5)
	s_add_i32 m0, s8, 0x2800
	v_lshl_add_u32 v8, v2, 8, v12
	global_load_lds_dwordx4 v8, s[16:17]
	s_waitcnt lgkmcnt(4)
	s_add_i32 m0, s8, 0x2c00
	v_lshl_add_u32 v9, v3, 8, v13
	global_load_lds_dwordx4 v9, s[16:17]
	s_waitcnt lgkmcnt(3)
	s_add_i32 m0, s8, 0x3000
	v_lshl_add_u32 v8, v4, 8, v10
	global_load_lds_dwordx4 v8, s[16:17]
	s_waitcnt lgkmcnt(2)
	s_add_i32 m0, s8, 0x3400
	v_lshl_add_u32 v9, v5, 8, v11
	global_load_lds_dwordx4 v9, s[16:17]
	s_waitcnt lgkmcnt(1)
	s_add_i32 m0, s8, 0x3800
	v_lshl_add_u32 v8, v6, 8, v12
	global_load_lds_dwordx4 v8, s[16:17]
	s_waitcnt lgkmcnt(0)
	s_add_i32 m0, s8, 0x3c00
	v_lshl_add_u32 v9, v7, 8, v13
	global_load_lds_dwordx4 v9, s[16:17]
	s_waitcnt vmcnt(8)
	ds_read_b128 v[104:107], v18 offset:0
	ds_read_b128 v[108:111], v19 offset:0
	ds_read_b128 v[112:115], v20 offset:0
	ds_read_b128 v[116:119], v21 offset:0
	ds_read_b128 v[120:123], v18 offset:4096
	ds_read_b128 v[124:127], v19 offset:4096
	ds_read_b128 v[128:131], v20 offset:4096
	ds_read_b128 v[132:135], v21 offset:4096
	s_waitcnt lgkmcnt(7)
	v_mfma_f32_16x16x32_bf16 v[136:139], v[104:107], v[88:91], 0
	s_waitcnt lgkmcnt(6)
	v_mfma_f32_16x16x32_bf16 v[136:139], v[108:111], v[92:95], v[136:139]
	s_waitcnt lgkmcnt(5)
	v_mfma_f32_16x16x32_bf16 v[136:139], v[112:115], v[96:99], v[136:139]
	s_waitcnt lgkmcnt(4)
	v_mfma_f32_16x16x32_bf16 v[136:139], v[116:119], v[100:103], v[136:139]
	s_waitcnt lgkmcnt(3)
	v_mfma_f32_16x16x32_bf16 v[140:143], v[120:123], v[88:91], 0
	s_waitcnt lgkmcnt(2)
	v_mfma_f32_16x16x32_bf16 v[140:143], v[124:127], v[92:95], v[140:143]
	s_waitcnt lgkmcnt(1)
	v_mfma_f32_16x16x32_bf16 v[140:143], v[128:131], v[96:99], v[140:143]
	s_waitcnt lgkmcnt(0)
	v_mfma_f32_16x16x32_bf16 v[140:143], v[132:135], v[100:103], v[140:143]
	v_mul_f32_e32 v56, 0x3db504f3, v136
	v_mul_f32_e32 v57, 0x3db504f3, v137
	v_mul_f32_e32 v58, 0x3db504f3, v138
	v_mul_f32_e32 v59, 0x3db504f3, v139
	s_nop 3
	v_mul_f32_e32 v60, 0x3db504f3, v140
	v_mul_f32_e32 v61, 0x3db504f3, v141
	v_mul_f32_e32 v62, 0x3db504f3, v142
	v_mul_f32_e32 v63, 0x3db504f3, v143
	s_mov_b32 s18, s14
	s_mov_b64 s[16:17], s[4:5]
	v_add_u32_e32 v161, s18, v156
	ds_read_u16 v0, v161 offset:0
	ds_read_u16 v1, v161 offset:8
	ds_read_u16 v2, v161 offset:16
	ds_read_u16 v3, v161 offset:24
	ds_read_u16 v4, v161 offset:32
	ds_read_u16 v5, v161 offset:40
	ds_read_u16 v6, v161 offset:48
	ds_read_u16 v7, v161 offset:56
	s_waitcnt lgkmcnt(7)
	s_add_i32 m0, s8, 0x0
	v_lshl_add_u32 v8, v0, 8, v10
	global_load_lds_dwordx4 v8, s[16:17]
	s_waitcnt lgkmcnt(6)
	s_add_i32 m0, s8, 0x400
	v_lshl_add_u32 v9, v1, 8, v11
	global_load_lds_dwordx4 v9, s[16:17]
	s_waitcnt lgkmcnt(5)
	s_add_i32 m0, s8, 0x800
	v_lshl_add_u32 v8, v2, 8, v12
	global_load_lds_dwordx4 v8, s[16:17]
	s_waitcnt lgkmcnt(4)
	s_add_i32 m0, s8, 0xc00
	v_lshl_add_u32 v9, v3, 8, v13
	global_load_lds_dwordx4 v9, s[16:17]
	s_waitcnt lgkmcnt(3)
	s_add_i32 m0, s8, 0x1000
	v_lshl_add_u32 v8, v4, 8, v10
	global_load_lds_dwordx4 v8, s[16:17]
	s_waitcnt lgkmcnt(2)
	s_add_i32 m0, s8, 0x1400
	v_lshl_add_u32 v9, v5, 8, v11
	global_load_lds_dwordx4 v9, s[16:17]
	s_waitcnt lgkmcnt(1)
	s_add_i32 m0, s8, 0x1800
	v_lshl_add_u32 v8, v6, 8, v12
	global_load_lds_dwordx4 v8, s[16:17]
	s_waitcnt lgkmcnt(0)
	s_add_i32 m0, s8, 0x1c00
	v_lshl_add_u32 v9, v7, 8, v13
	global_load_lds_dwordx4 v9, s[16:17]
	s_waitcnt vmcnt(8)
	ds_read_b128 v[104:107], v18 offset:8192
	ds_read_b128 v[108:111], v19 offset:8192
	ds_read_b128 v[112:115], v20 offset:8192
	ds_read_b128 v[116:119], v21 offset:8192
	ds_read_b128 v[120:123], v18 offset:12288
	ds_read_b128 v[124:127], v19 offset:12288
	ds_read_b128 v[128:131], v20 offset:12288
	ds_read_b128 v[132:135], v21 offset:12288
	s_waitcnt lgkmcnt(7)
	v_mfma_f32_16x16x32_bf16 v[136:139], v[104:107], v[88:91], 0
	s_waitcnt lgkmcnt(6)
	v_mfma_f32_16x16x32_bf16 v[136:139], v[108:111], v[92:95], v[136:139]
	s_waitcnt lgkmcnt(5)
	v_mfma_f32_16x16x32_bf16 v[136:139], v[112:115], v[96:99], v[136:139]
	s_waitcnt lgkmcnt(4)
	v_mfma_f32_16x16x32_bf16 v[136:139], v[116:119], v[100:103], v[136:139]
	s_waitcnt lgkmcnt(3)
	v_mfma_f32_16x16x32_bf16 v[140:143], v[120:123], v[88:91], 0
	s_waitcnt lgkmcnt(2)
	v_mfma_f32_16x16x32_bf16 v[140:143], v[124:127], v[92:95], v[140:143]
	s_waitcnt lgkmcnt(1)
	v_mfma_f32_16x16x32_bf16 v[140:143], v[128:131], v[96:99], v[140:143]
	s_waitcnt lgkmcnt(0)
	v_mfma_f32_16x16x32_bf16 v[140:143], v[132:135], v[100:103], v[140:143]
	v_mul_f32_e32 v64, 0x3db504f3, v136
	v_mul_f32_e32 v65, 0x3db504f3, v137
	v_mul_f32_e32 v66, 0x3db504f3, v138
	v_mul_f32_e32 v67, 0x3db504f3, v139
	s_nop 3
	v_mul_f32_e32 v68, 0x3db504f3, v140
	v_mul_f32_e32 v69, 0x3db504f3, v141
	v_mul_f32_e32 v70, 0x3db504f3, v142
	v_mul_f32_e32 v71, 0x3db504f3, v143
	v_max3_f32 v163, v24, v25, v26
	v_max3_f32 v163, v163, v27, v28
	v_max3_f32 v163, v163, v29, v30
	v_max3_f32 v163, v163, v31, v32
	v_max3_f32 v163, v163, v33, v34
	v_max3_f32 v163, v163, v35, v36
	v_max3_f32 v163, v163, v37, v38
	v_max3_f32 v163, v163, v39, v40
	v_max3_f32 v163, v163, v41, v42
	v_max3_f32 v163, v163, v43, v44
	v_max3_f32 v163, v163, v45, v46
	v_max3_f32 v163, v163, v47, v48
	v_max3_f32 v163, v163, v49, v50
	v_max3_f32 v163, v163, v51, v52
	v_max3_f32 v163, v163, v53, v54
	v_max3_f32 v163, v163, v55, v56
	v_max3_f32 v163, v163, v57, v58
	v_max3_f32 v163, v163, v59, v60
	v_max3_f32 v163, v163, v61, v62
	v_max3_f32 v163, v163, v63, v64
	v_max3_f32 v163, v163, v65, v66
	v_max3_f32 v163, v163, v67, v68
	v_max3_f32 v163, v163, v69, v70
	v_max_f32_e32 v163, v163, v71
	s_nop 0
	ds_bpermute_b32 v165, v147, v163
	s_waitcnt lgkmcnt(0)
	v_max_f32_e32 v163, v163, v165
	s_nop 0
	ds_bpermute_b32 v165, v146, v163
	s_waitcnt lgkmcnt(0)
	v_max_f32_e32 v163, v163, v165
	v_sub_f32_e32 v165, v24, v163
	v_mul_f32_e32 v165, 0x3fb8aa3b, v165
	v_exp_f32_e32 v24, v165
	v_sub_f32_e32 v166, v25, v163
	v_mul_f32_e32 v166, 0x3fb8aa3b, v166
	v_exp_f32_e32 v25, v166
	v_sub_f32_e32 v167, v26, v163
	v_mul_f32_e32 v167, 0x3fb8aa3b, v167
	v_exp_f32_e32 v26, v167
	v_add_f32_e32 v164, 0, v24
	v_sub_f32_e32 v168, v27, v163
	v_mul_f32_e32 v168, 0x3fb8aa3b, v168
	v_exp_f32_e32 v27, v168
	v_add_f32_e32 v164, v164, v25
	v_sub_f32_e32 v165, v28, v163
	v_mul_f32_e32 v165, 0x3fb8aa3b, v165
	v_exp_f32_e32 v28, v165
	v_add_f32_e32 v164, v164, v26
	v_sub_f32_e32 v166, v29, v163
	v_mul_f32_e32 v166, 0x3fb8aa3b, v166
	v_exp_f32_e32 v29, v166
	v_add_f32_e32 v164, v164, v27
	v_sub_f32_e32 v167, v30, v163
	v_mul_f32_e32 v167, 0x3fb8aa3b, v167
	v_exp_f32_e32 v30, v167
	v_add_f32_e32 v164, v164, v28
	v_sub_f32_e32 v168, v31, v163
	v_mul_f32_e32 v168, 0x3fb8aa3b, v168
	v_exp_f32_e32 v31, v168
	v_add_f32_e32 v164, v164, v29
	v_sub_f32_e32 v165, v32, v163
	v_mul_f32_e32 v165, 0x3fb8aa3b, v165
	v_exp_f32_e32 v32, v165
	v_add_f32_e32 v164, v164, v30
	v_sub_f32_e32 v166, v33, v163
	v_mul_f32_e32 v166, 0x3fb8aa3b, v166
	v_exp_f32_e32 v33, v166
	v_add_f32_e32 v164, v164, v31
	v_sub_f32_e32 v167, v34, v163
	v_mul_f32_e32 v167, 0x3fb8aa3b, v167
	v_exp_f32_e32 v34, v167
	v_add_f32_e32 v164, v164, v32
	v_sub_f32_e32 v168, v35, v163
	v_mul_f32_e32 v168, 0x3fb8aa3b, v168
	v_exp_f32_e32 v35, v168
	v_add_f32_e32 v164, v164, v33
	v_sub_f32_e32 v165, v36, v163
	v_mul_f32_e32 v165, 0x3fb8aa3b, v165
	v_exp_f32_e32 v36, v165
	v_add_f32_e32 v164, v164, v34
	v_sub_f32_e32 v166, v37, v163
	v_mul_f32_e32 v166, 0x3fb8aa3b, v166
	v_exp_f32_e32 v37, v166
	v_add_f32_e32 v164, v164, v35
	v_sub_f32_e32 v167, v38, v163
	v_mul_f32_e32 v167, 0x3fb8aa3b, v167
	v_exp_f32_e32 v38, v167
	v_add_f32_e32 v164, v164, v36
	v_sub_f32_e32 v168, v39, v163
	v_mul_f32_e32 v168, 0x3fb8aa3b, v168
	v_exp_f32_e32 v39, v168
	v_add_f32_e32 v164, v164, v37
	v_sub_f32_e32 v165, v40, v163
	v_mul_f32_e32 v165, 0x3fb8aa3b, v165
	v_exp_f32_e32 v40, v165
	v_add_f32_e32 v164, v164, v38
	v_sub_f32_e32 v166, v41, v163
	v_mul_f32_e32 v166, 0x3fb8aa3b, v166
	v_exp_f32_e32 v41, v166
	v_add_f32_e32 v164, v164, v39
	v_sub_f32_e32 v167, v42, v163
	v_mul_f32_e32 v167, 0x3fb8aa3b, v167
	v_exp_f32_e32 v42, v167
	v_add_f32_e32 v164, v164, v40
	v_sub_f32_e32 v168, v43, v163
	v_mul_f32_e32 v168, 0x3fb8aa3b, v168
	v_exp_f32_e32 v43, v168
	v_add_f32_e32 v164, v164, v41
	v_sub_f32_e32 v165, v44, v163
	v_mul_f32_e32 v165, 0x3fb8aa3b, v165
	v_exp_f32_e32 v44, v165
	v_add_f32_e32 v164, v164, v42
	v_sub_f32_e32 v166, v45, v163
	v_mul_f32_e32 v166, 0x3fb8aa3b, v166
	v_exp_f32_e32 v45, v166
	v_add_f32_e32 v164, v164, v43
	v_sub_f32_e32 v167, v46, v163
	v_mul_f32_e32 v167, 0x3fb8aa3b, v167
	v_exp_f32_e32 v46, v167
	v_add_f32_e32 v164, v164, v44
	v_sub_f32_e32 v168, v47, v163
	v_mul_f32_e32 v168, 0x3fb8aa3b, v168
	v_exp_f32_e32 v47, v168
	v_add_f32_e32 v164, v164, v45
	v_sub_f32_e32 v165, v48, v163
	v_mul_f32_e32 v165, 0x3fb8aa3b, v165
	v_exp_f32_e32 v48, v165
	v_add_f32_e32 v164, v164, v46
	v_sub_f32_e32 v166, v49, v163
	v_mul_f32_e32 v166, 0x3fb8aa3b, v166
	v_exp_f32_e32 v49, v166
	v_add_f32_e32 v164, v164, v47
	v_sub_f32_e32 v167, v50, v163
	v_mul_f32_e32 v167, 0x3fb8aa3b, v167
	v_exp_f32_e32 v50, v167
	v_add_f32_e32 v164, v164, v48
	v_sub_f32_e32 v168, v51, v163
	v_mul_f32_e32 v168, 0x3fb8aa3b, v168
	v_exp_f32_e32 v51, v168
	v_add_f32_e32 v164, v164, v49
	v_sub_f32_e32 v165, v52, v163
	v_mul_f32_e32 v165, 0x3fb8aa3b, v165
	v_exp_f32_e32 v52, v165
	v_add_f32_e32 v164, v164, v50
	v_sub_f32_e32 v166, v53, v163
	v_mul_f32_e32 v166, 0x3fb8aa3b, v166
	v_exp_f32_e32 v53, v166
	v_add_f32_e32 v164, v164, v51
	v_sub_f32_e32 v167, v54, v163
	v_mul_f32_e32 v167, 0x3fb8aa3b, v167
	v_exp_f32_e32 v54, v167
	v_add_f32_e32 v164, v164, v52
	v_sub_f32_e32 v168, v55, v163
	v_mul_f32_e32 v168, 0x3fb8aa3b, v168
	v_exp_f32_e32 v55, v168
	v_add_f32_e32 v164, v164, v53
	v_sub_f32_e32 v165, v56, v163
	v_mul_f32_e32 v165, 0x3fb8aa3b, v165
	v_exp_f32_e32 v56, v165
	v_add_f32_e32 v164, v164, v54
	v_sub_f32_e32 v166, v57, v163
	v_mul_f32_e32 v166, 0x3fb8aa3b, v166
	v_exp_f32_e32 v57, v166
	v_add_f32_e32 v164, v164, v55
	v_sub_f32_e32 v167, v58, v163
	v_mul_f32_e32 v167, 0x3fb8aa3b, v167
	v_exp_f32_e32 v58, v167
	v_add_f32_e32 v164, v164, v56
	v_sub_f32_e32 v168, v59, v163
	v_mul_f32_e32 v168, 0x3fb8aa3b, v168
	v_exp_f32_e32 v59, v168
	v_add_f32_e32 v164, v164, v57
	v_sub_f32_e32 v165, v60, v163
	v_mul_f32_e32 v165, 0x3fb8aa3b, v165
	v_exp_f32_e32 v60, v165
	v_add_f32_e32 v164, v164, v58
	v_sub_f32_e32 v166, v61, v163
	v_mul_f32_e32 v166, 0x3fb8aa3b, v166
	v_exp_f32_e32 v61, v166
	v_add_f32_e32 v164, v164, v59
	v_sub_f32_e32 v167, v62, v163
	v_mul_f32_e32 v167, 0x3fb8aa3b, v167
	v_exp_f32_e32 v62, v167
	v_add_f32_e32 v164, v164, v60
	v_sub_f32_e32 v168, v63, v163
	v_mul_f32_e32 v168, 0x3fb8aa3b, v168
	v_exp_f32_e32 v63, v168
	v_add_f32_e32 v164, v164, v61
	v_sub_f32_e32 v165, v64, v163
	v_mul_f32_e32 v165, 0x3fb8aa3b, v165
	v_exp_f32_e32 v64, v165
	v_add_f32_e32 v164, v164, v62
	v_sub_f32_e32 v166, v65, v163
	v_mul_f32_e32 v166, 0x3fb8aa3b, v166
	v_exp_f32_e32 v65, v166
	v_add_f32_e32 v164, v164, v63
	v_sub_f32_e32 v167, v66, v163
	v_mul_f32_e32 v167, 0x3fb8aa3b, v167
	v_exp_f32_e32 v66, v167
	v_add_f32_e32 v164, v164, v64
	v_sub_f32_e32 v168, v67, v163
	v_mul_f32_e32 v168, 0x3fb8aa3b, v168
	v_exp_f32_e32 v67, v168
	v_add_f32_e32 v164, v164, v65
	v_sub_f32_e32 v165, v68, v163
	v_mul_f32_e32 v165, 0x3fb8aa3b, v165
	v_exp_f32_e32 v68, v165
	v_add_f32_e32 v164, v164, v66
	v_sub_f32_e32 v166, v69, v163
	v_mul_f32_e32 v166, 0x3fb8aa3b, v166
	v_exp_f32_e32 v69, v166
	v_add_f32_e32 v164, v164, v67
	v_sub_f32_e32 v167, v70, v163
	v_mul_f32_e32 v167, 0x3fb8aa3b, v167
	v_exp_f32_e32 v70, v167
	v_add_f32_e32 v164, v164, v68
	v_sub_f32_e32 v168, v71, v163
	v_mul_f32_e32 v168, 0x3fb8aa3b, v168
	v_exp_f32_e32 v71, v168
	v_add_f32_e32 v164, v164, v69
	s_nop 0
	v_add_f32_e32 v164, v164, v70
	v_add_f32_e32 v164, v164, v71
	s_nop 0
	ds_bpermute_b32 v165, v147, v164
	s_waitcnt lgkmcnt(0)
	v_add_f32_e32 v164, v164, v165
	s_nop 0
	ds_bpermute_b32 v165, v146, v164
	s_waitcnt lgkmcnt(0)
	v_add_f32_e32 v164, v164, v165
	v_div_scale_f32 v170, s[74:75], v164, v164, 1.0
	v_rcp_f32_e32 v171, v170
	s_nop 0
	v_fma_f32 v172, -v170, v171, 1.0
	v_fmac_f32_e32 v171, v172, v171
	v_div_scale_f32 v172, vcc, 1.0, v164, 1.0
	v_mul_f32_e32 v173, v172, v171
	v_fma_f32 v169, -v170, v173, v172
	v_fmac_f32_e32 v173, v169, v171
	v_fma_f32 v170, -v170, v173, v172
	v_div_fmas_f32 v170, v170, v171, v173
	v_div_fixup_f32 v169, v170, v164, 1.0
	v_mul_f32_e32 v165, v24, v169
	v_mul_f32_e32 v166, v25, v169
	v_cvt_pk_bf16_f32 v24, v165, v166
	v_mul_f32_e32 v167, v26, v169
	v_mul_f32_e32 v168, v27, v169
	v_cvt_pk_bf16_f32 v25, v167, v168
	v_mul_f32_e32 v165, v28, v169
	v_mul_f32_e32 v166, v29, v169
	v_cvt_pk_bf16_f32 v26, v165, v166
	v_mul_f32_e32 v167, v30, v169
	v_mul_f32_e32 v168, v31, v169
	v_cvt_pk_bf16_f32 v27, v167, v168
	v_mul_f32_e32 v165, v32, v169
	v_mul_f32_e32 v166, v33, v169
	v_cvt_pk_bf16_f32 v32, v165, v166
	v_mul_f32_e32 v167, v34, v169
	v_mul_f32_e32 v168, v35, v169
	v_cvt_pk_bf16_f32 v33, v167, v168
	v_mul_f32_e32 v165, v36, v169
	v_mul_f32_e32 v166, v37, v169
	v_cvt_pk_bf16_f32 v34, v165, v166
	v_mul_f32_e32 v167, v38, v169
	v_mul_f32_e32 v168, v39, v169
	v_cvt_pk_bf16_f32 v35, v167, v168
	v_mul_f32_e32 v165, v40, v169
	v_mul_f32_e32 v166, v41, v169
	v_cvt_pk_bf16_f32 v40, v165, v166
	v_mul_f32_e32 v167, v42, v169
	v_mul_f32_e32 v168, v43, v169
	v_cvt_pk_bf16_f32 v41, v167, v168
	v_mul_f32_e32 v165, v44, v169
	v_mul_f32_e32 v166, v45, v169
	v_cvt_pk_bf16_f32 v42, v165, v166
	v_mul_f32_e32 v167, v46, v169
	v_mul_f32_e32 v168, v47, v169
	v_cvt_pk_bf16_f32 v43, v167, v168
	v_mul_f32_e32 v165, v48, v169
	v_mul_f32_e32 v166, v49, v169
	v_cvt_pk_bf16_f32 v48, v165, v166
	v_mul_f32_e32 v167, v50, v169
	v_mul_f32_e32 v168, v51, v169
	v_cvt_pk_bf16_f32 v49, v167, v168
	v_mul_f32_e32 v165, v52, v169
	v_mul_f32_e32 v166, v53, v169
	v_cvt_pk_bf16_f32 v50, v165, v166
	v_mul_f32_e32 v167, v54, v169
	v_mul_f32_e32 v168, v55, v169
	v_cvt_pk_bf16_f32 v51, v167, v168
	v_mul_f32_e32 v165, v56, v169
	v_mul_f32_e32 v166, v57, v169
	v_cvt_pk_bf16_f32 v56, v165, v166
	v_mul_f32_e32 v167, v58, v169
	v_mul_f32_e32 v168, v59, v169
	v_cvt_pk_bf16_f32 v57, v167, v168
	v_mul_f32_e32 v165, v60, v169
	v_mul_f32_e32 v166, v61, v169
	v_cvt_pk_bf16_f32 v58, v165, v166
	v_mul_f32_e32 v167, v62, v169
	v_mul_f32_e32 v168, v63, v169
	v_cvt_pk_bf16_f32 v59, v167, v168
	v_mul_f32_e32 v165, v64, v169
	v_mul_f32_e32 v166, v65, v169
	v_cvt_pk_bf16_f32 v64, v165, v166
	v_mul_f32_e32 v167, v66, v169
	v_mul_f32_e32 v168, v67, v169
	v_cvt_pk_bf16_f32 v65, v167, v168
	v_mul_f32_e32 v165, v68, v169
	v_mul_f32_e32 v166, v69, v169
	v_cvt_pk_bf16_f32 v66, v165, v166
	v_mul_f32_e32 v167, v70, v169
	v_mul_f32_e32 v168, v71, v169
	v_cvt_pk_bf16_f32 v67, v167, v168
	s_cmp_eq_u32 s11, 0
	s_cselect_b32 s15, 1, 0
	s_add_i32 s15, s15, s12
	s_lshl_b32 s13, s15, 12
	v_add_u32_e32 v162, s13, v157
	global_load_dwordx4 v[88:91], v162, s[6:7] offset:0
	global_load_dwordx4 v[92:95], v162, s[6:7] offset:64
	global_load_dwordx4 v[96:99], v162, s[6:7] offset:128
	global_load_dwordx4 v[100:103], v162, s[6:7] offset:192
	s_add_i32 s18, s14, 64
	s_mov_b64 s[16:17], s[4:5]
	v_add_u32_e32 v161, s18, v156
	ds_read_u16 v0, v161 offset:0
	ds_read_u16 v1, v161 offset:8
	ds_read_u16 v2, v161 offset:16
	ds_read_u16 v3, v161 offset:24
	ds_read_u16 v4, v161 offset:32
	ds_read_u16 v5, v161 offset:40
	ds_read_u16 v6, v161 offset:48
	ds_read_u16 v7, v161 offset:56
	s_waitcnt lgkmcnt(7)
	s_add_i32 m0, s8, 0x2000
	v_lshl_add_u32 v8, v0, 8, v10
	global_load_lds_dwordx4 v8, s[16:17]
	s_waitcnt lgkmcnt(6)
	s_add_i32 m0, s8, 0x2400
	v_lshl_add_u32 v9, v1, 8, v11
	global_load_lds_dwordx4 v9, s[16:17]
	s_waitcnt lgkmcnt(5)
	s_add_i32 m0, s8, 0x2800
	v_lshl_add_u32 v8, v2, 8, v12
	global_load_lds_dwordx4 v8, s[16:17]
	s_waitcnt lgkmcnt(4)
	s_add_i32 m0, s8, 0x2c00
	v_lshl_add_u32 v9, v3, 8, v13
	global_load_lds_dwordx4 v9, s[16:17]
	s_waitcnt lgkmcnt(3)
	s_add_i32 m0, s8, 0x3000
	v_lshl_add_u32 v8, v4, 8, v10
	global_load_lds_dwordx4 v8, s[16:17]
	s_waitcnt lgkmcnt(2)
	s_add_i32 m0, s8, 0x3400
	v_lshl_add_u32 v9, v5, 8, v11
	global_load_lds_dwordx4 v9, s[16:17]
	s_waitcnt lgkmcnt(1)
	s_add_i32 m0, s8, 0x3800
	v_lshl_add_u32 v8, v6, 8, v12
	global_load_lds_dwordx4 v8, s[16:17]
	s_waitcnt lgkmcnt(0)
	s_add_i32 m0, s8, 0x3c00
	v_lshl_add_u32 v9, v7, 8, v13
	global_load_lds_dwordx4 v9, s[16:17]
	s_waitcnt vmcnt(8)
	ds_read_b64_tr_b16 v[104:105], v148 offset:0
	ds_read_b64_tr_b16 v[106:107], v148 offset:4096
	ds_read_b64_tr_b16 v[108:109], v149 offset:0
	ds_read_b64_tr_b16 v[110:111], v149 offset:4096
	ds_read_b64_tr_b16 v[112:113], v150 offset:0
	ds_read_b64_tr_b16 v[114:115], v150 offset:4096
	ds_read_b64_tr_b16 v[116:117], v151 offset:0
	ds_read_b64_tr_b16 v[118:119], v151 offset:4096
	ds_read_b64_tr_b16 v[120:121], v152 offset:0
	ds_read_b64_tr_b16 v[122:123], v152 offset:4096
	ds_read_b64_tr_b16 v[124:125], v153 offset:0
	ds_read_b64_tr_b16 v[126:127], v153 offset:4096
	ds_read_b64_tr_b16 v[128:129], v154 offset:0
	ds_read_b64_tr_b16 v[130:131], v154 offset:4096
	s_waitcnt lgkmcnt(12)
	v_mfma_f32_16x16x32_bf16 v[176:179], v[24:27], v[104:107], 0
	ds_read_b64_tr_b16 v[132:133], v155 offset:0
	ds_read_b64_tr_b16 v[134:135], v155 offset:4096
	s_waitcnt lgkmcnt(12)
	v_mfma_f32_16x16x32_bf16 v[180:183], v[24:27], v[108:111], 0
	s_waitcnt lgkmcnt(10)
	v_mfma_f32_16x16x32_bf16 v[184:187], v[24:27], v[112:115], 0
	s_waitcnt lgkmcnt(8)
	v_mfma_f32_16x16x32_bf16 v[188:191], v[24:27], v[116:119], 0
	s_waitcnt lgkmcnt(6)
	v_mfma_f32_16x16x32_bf16 v[192:195], v[24:27], v[120:123], 0
	s_waitcnt lgkmcnt(4)
	v_mfma_f32_16x16x32_bf16 v[196:199], v[24:27], v[124:127], 0
	s_waitcnt lgkmcnt(2)
	v_mfma_f32_16x16x32_bf16 v[200:203], v[24:27], v[128:131], 0
	s_waitcnt lgkmcnt(0)
	v_mfma_f32_16x16x32_bf16 v[204:207], v[24:27], v[132:135], 0
	s_add_i32 s18, s14, 128
	s_mov_b64 s[16:17], s[4:5]
	v_add_u32_e32 v161, s18, v156
	ds_read_u16 v0, v161 offset:0
	ds_read_u16 v1, v161 offset:8
	ds_read_u16 v2, v161 offset:16
	ds_read_u16 v3, v161 offset:24
	ds_read_u16 v4, v161 offset:32
	ds_read_u16 v5, v161 offset:40
	ds_read_u16 v6, v161 offset:48
	ds_read_u16 v7, v161 offset:56
	s_waitcnt lgkmcnt(7)
	s_add_i32 m0, s8, 0x0
	v_lshl_add_u32 v8, v0, 8, v10
	global_load_lds_dwordx4 v8, s[16:17]
	s_waitcnt lgkmcnt(6)
	s_add_i32 m0, s8, 0x400
	v_lshl_add_u32 v9, v1, 8, v11
	global_load_lds_dwordx4 v9, s[16:17]
	s_waitcnt lgkmcnt(5)
	s_add_i32 m0, s8, 0x800
	v_lshl_add_u32 v8, v2, 8, v12
	global_load_lds_dwordx4 v8, s[16:17]
	s_waitcnt lgkmcnt(4)
	s_add_i32 m0, s8, 0xc00
	v_lshl_add_u32 v9, v3, 8, v13
	global_load_lds_dwordx4 v9, s[16:17]
	s_waitcnt lgkmcnt(3)
	s_add_i32 m0, s8, 0x1000
	v_lshl_add_u32 v8, v4, 8, v10
	global_load_lds_dwordx4 v8, s[16:17]
	s_waitcnt lgkmcnt(2)
	s_add_i32 m0, s8, 0x1400
	v_lshl_add_u32 v9, v5, 8, v11
	global_load_lds_dwordx4 v9, s[16:17]
	s_waitcnt lgkmcnt(1)
	s_add_i32 m0, s8, 0x1800
	v_lshl_add_u32 v8, v6, 8, v12
	global_load_lds_dwordx4 v8, s[16:17]
	s_waitcnt lgkmcnt(0)
	s_add_i32 m0, s8, 0x1c00
	v_lshl_add_u32 v9, v7, 8, v13
	global_load_lds_dwordx4 v9, s[16:17]
	s_waitcnt vmcnt(8)
	ds_read_b64_tr_b16 v[104:105], v148 offset:8192
	ds_read_b64_tr_b16 v[106:107], v148 offset:12288
	ds_read_b64_tr_b16 v[108:109], v149 offset:8192
	ds_read_b64_tr_b16 v[110:111], v149 offset:12288
	ds_read_b64_tr_b16 v[112:113], v150 offset:8192
	ds_read_b64_tr_b16 v[114:115], v150 offset:12288
	ds_read_b64_tr_b16 v[116:117], v151 offset:8192
	ds_read_b64_tr_b16 v[118:119], v151 offset:12288
	ds_read_b64_tr_b16 v[120:121], v152 offset:8192
	ds_read_b64_tr_b16 v[122:123], v152 offset:12288
	ds_read_b64_tr_b16 v[124:125], v153 offset:8192
	ds_read_b64_tr_b16 v[126:127], v153 offset:12288
	ds_read_b64_tr_b16 v[128:129], v154 offset:8192
	ds_read_b64_tr_b16 v[130:131], v154 offset:12288
	s_waitcnt lgkmcnt(12)
	v_mfma_f32_16x16x32_bf16 v[176:179], v[32:35], v[104:107], v[176:179]
	ds_read_b64_tr_b16 v[132:133], v155 offset:8192
	ds_read_b64_tr_b16 v[134:135], v155 offset:12288
	s_waitcnt lgkmcnt(12)
	v_mfma_f32_16x16x32_bf16 v[180:183], v[32:35], v[108:111], v[180:183]
	s_waitcnt lgkmcnt(10)
	v_mfma_f32_16x16x32_bf16 v[184:187], v[32:35], v[112:115], v[184:187]
	s_waitcnt lgkmcnt(8)
	v_mfma_f32_16x16x32_bf16 v[188:191], v[32:35], v[116:119], v[188:191]
	s_waitcnt lgkmcnt(6)
	v_mfma_f32_16x16x32_bf16 v[192:195], v[32:35], v[120:123], v[192:195]
	s_waitcnt lgkmcnt(4)
	v_mfma_f32_16x16x32_bf16 v[196:199], v[32:35], v[124:127], v[196:199]
	s_waitcnt lgkmcnt(2)
	v_mfma_f32_16x16x32_bf16 v[200:203], v[32:35], v[128:131], v[200:203]
	s_waitcnt lgkmcnt(0)
	v_mfma_f32_16x16x32_bf16 v[204:207], v[32:35], v[132:135], v[204:207]
	s_add_i32 s18, s14, 192
	s_mov_b64 s[16:17], s[4:5]
	v_add_u32_e32 v161, s18, v156
	ds_read_u16 v0, v161 offset:0
	ds_read_u16 v1, v161 offset:8
	ds_read_u16 v2, v161 offset:16
	ds_read_u16 v3, v161 offset:24
	ds_read_u16 v4, v161 offset:32
	ds_read_u16 v5, v161 offset:40
	ds_read_u16 v6, v161 offset:48
	ds_read_u16 v7, v161 offset:56
	s_waitcnt lgkmcnt(7)
	s_add_i32 m0, s8, 0x2000
	v_lshl_add_u32 v8, v0, 8, v10
	global_load_lds_dwordx4 v8, s[16:17]
	s_waitcnt lgkmcnt(6)
	s_add_i32 m0, s8, 0x2400
	v_lshl_add_u32 v9, v1, 8, v11
	global_load_lds_dwordx4 v9, s[16:17]
	s_waitcnt lgkmcnt(5)
	s_add_i32 m0, s8, 0x2800
	v_lshl_add_u32 v8, v2, 8, v12
	global_load_lds_dwordx4 v8, s[16:17]
	s_waitcnt lgkmcnt(4)
	s_add_i32 m0, s8, 0x2c00
	v_lshl_add_u32 v9, v3, 8, v13
	global_load_lds_dwordx4 v9, s[16:17]
	s_waitcnt lgkmcnt(3)
	s_add_i32 m0, s8, 0x3000
	v_lshl_add_u32 v8, v4, 8, v10
	global_load_lds_dwordx4 v8, s[16:17]
	s_waitcnt lgkmcnt(2)
	s_add_i32 m0, s8, 0x3400
	v_lshl_add_u32 v9, v5, 8, v11
	global_load_lds_dwordx4 v9, s[16:17]
	s_waitcnt lgkmcnt(1)
	s_add_i32 m0, s8, 0x3800
	v_lshl_add_u32 v8, v6, 8, v12
	global_load_lds_dwordx4 v8, s[16:17]
	s_waitcnt lgkmcnt(0)
	s_add_i32 m0, s8, 0x3c00
	v_lshl_add_u32 v9, v7, 8, v13
	global_load_lds_dwordx4 v9, s[16:17]
	s_waitcnt vmcnt(8)
	ds_read_b64_tr_b16 v[104:105], v148 offset:0
	ds_read_b64_tr_b16 v[106:107], v148 offset:4096
	ds_read_b64_tr_b16 v[108:109], v149 offset:0
	ds_read_b64_tr_b16 v[110:111], v149 offset:4096
	ds_read_b64_tr_b16 v[112:113], v150 offset:0
	ds_read_b64_tr_b16 v[114:115], v150 offset:4096
	ds_read_b64_tr_b16 v[116:117], v151 offset:0
	ds_read_b64_tr_b16 v[118:119], v151 offset:4096
	ds_read_b64_tr_b16 v[120:121], v152 offset:0
	ds_read_b64_tr_b16 v[122:123], v152 offset:4096
	ds_read_b64_tr_b16 v[124:125], v153 offset:0
	ds_read_b64_tr_b16 v[126:127], v153 offset:4096
	ds_read_b64_tr_b16 v[128:129], v154 offset:0
	ds_read_b64_tr_b16 v[130:131], v154 offset:4096
	s_waitcnt lgkmcnt(12)
	v_mfma_f32_16x16x32_bf16 v[176:179], v[40:43], v[104:107], v[176:179]
	ds_read_b64_tr_b16 v[132:133], v155 offset:0
	ds_read_b64_tr_b16 v[134:135], v155 offset:4096
	s_waitcnt lgkmcnt(12)
	v_mfma_f32_16x16x32_bf16 v[180:183], v[40:43], v[108:111], v[180:183]
	s_waitcnt lgkmcnt(10)
	v_mfma_f32_16x16x32_bf16 v[184:187], v[40:43], v[112:115], v[184:187]
	s_waitcnt lgkmcnt(8)
	v_mfma_f32_16x16x32_bf16 v[188:191], v[40:43], v[116:119], v[188:191]
	s_waitcnt lgkmcnt(6)
	v_mfma_f32_16x16x32_bf16 v[192:195], v[40:43], v[120:123], v[192:195]
	s_waitcnt lgkmcnt(4)
	v_mfma_f32_16x16x32_bf16 v[196:199], v[40:43], v[124:127], v[196:199]
	s_waitcnt lgkmcnt(2)
	v_mfma_f32_16x16x32_bf16 v[200:203], v[40:43], v[128:131], v[200:203]
	s_waitcnt lgkmcnt(0)
	v_mfma_f32_16x16x32_bf16 v[204:207], v[40:43], v[132:135], v[204:207]
	s_add_i32 s18, s14, 256
	s_mov_b64 s[16:17], s[4:5]
	v_add_u32_e32 v161, s18, v156
	ds_read_u16 v0, v161 offset:0
	ds_read_u16 v1, v161 offset:8
	ds_read_u16 v2, v161 offset:16
	ds_read_u16 v3, v161 offset:24
	ds_read_u16 v4, v161 offset:32
	ds_read_u16 v5, v161 offset:40
	ds_read_u16 v6, v161 offset:48
	ds_read_u16 v7, v161 offset:56
	s_waitcnt lgkmcnt(7)
	s_add_i32 m0, s8, 0x0
	v_lshl_add_u32 v8, v0, 8, v10
	global_load_lds_dwordx4 v8, s[16:17]
	s_waitcnt lgkmcnt(6)
	s_add_i32 m0, s8, 0x400
	v_lshl_add_u32 v9, v1, 8, v11
	global_load_lds_dwordx4 v9, s[16:17]
	s_waitcnt lgkmcnt(5)
	s_add_i32 m0, s8, 0x800
	v_lshl_add_u32 v8, v2, 8, v12
	global_load_lds_dwordx4 v8, s[16:17]
	s_waitcnt lgkmcnt(4)
	s_add_i32 m0, s8, 0xc00
	v_lshl_add_u32 v9, v3, 8, v13
	global_load_lds_dwordx4 v9, s[16:17]
	s_waitcnt lgkmcnt(3)
	s_add_i32 m0, s8, 0x1000
	v_lshl_add_u32 v8, v4, 8, v10
	global_load_lds_dwordx4 v8, s[16:17]
	s_waitcnt lgkmcnt(2)
	s_add_i32 m0, s8, 0x1400
	v_lshl_add_u32 v9, v5, 8, v11
	global_load_lds_dwordx4 v9, s[16:17]
	s_waitcnt lgkmcnt(1)
	s_add_i32 m0, s8, 0x1800
	v_lshl_add_u32 v8, v6, 8, v12
	global_load_lds_dwordx4 v8, s[16:17]
	s_waitcnt lgkmcnt(0)
	s_add_i32 m0, s8, 0x1c00
	v_lshl_add_u32 v9, v7, 8, v13
	global_load_lds_dwordx4 v9, s[16:17]
	s_waitcnt vmcnt(8)
	ds_read_b64_tr_b16 v[104:105], v148 offset:8192
	ds_read_b64_tr_b16 v[106:107], v148 offset:12288
	ds_read_b64_tr_b16 v[108:109], v149 offset:8192
	ds_read_b64_tr_b16 v[110:111], v149 offset:12288
	ds_read_b64_tr_b16 v[112:113], v150 offset:8192
	ds_read_b64_tr_b16 v[114:115], v150 offset:12288
	ds_read_b64_tr_b16 v[116:117], v151 offset:8192
	ds_read_b64_tr_b16 v[118:119], v151 offset:12288
	ds_read_b64_tr_b16 v[120:121], v152 offset:8192
	ds_read_b64_tr_b16 v[122:123], v152 offset:12288
	ds_read_b64_tr_b16 v[124:125], v153 offset:8192
	ds_read_b64_tr_b16 v[126:127], v153 offset:12288
	ds_read_b64_tr_b16 v[128:129], v154 offset:8192
	ds_read_b64_tr_b16 v[130:131], v154 offset:12288
	s_waitcnt lgkmcnt(12)
	v_mfma_f32_16x16x32_bf16 v[176:179], v[48:51], v[104:107], v[176:179]
	ds_read_b64_tr_b16 v[132:133], v155 offset:8192
	ds_read_b64_tr_b16 v[134:135], v155 offset:12288
	s_waitcnt lgkmcnt(12)
	v_mfma_f32_16x16x32_bf16 v[180:183], v[48:51], v[108:111], v[180:183]
	s_waitcnt lgkmcnt(10)
	v_mfma_f32_16x16x32_bf16 v[184:187], v[48:51], v[112:115], v[184:187]
	s_waitcnt lgkmcnt(8)
	v_mfma_f32_16x16x32_bf16 v[188:191], v[48:51], v[116:119], v[188:191]
	s_waitcnt lgkmcnt(6)
	v_mfma_f32_16x16x32_bf16 v[192:195], v[48:51], v[120:123], v[192:195]
	s_waitcnt lgkmcnt(4)
	v_mfma_f32_16x16x32_bf16 v[196:199], v[48:51], v[124:127], v[196:199]
	s_waitcnt lgkmcnt(2)
	v_mfma_f32_16x16x32_bf16 v[200:203], v[48:51], v[128:131], v[200:203]
	s_waitcnt lgkmcnt(0)
	v_mfma_f32_16x16x32_bf16 v[204:207], v[48:51], v[132:135], v[204:207]
	s_add_i32 s18, s14, 320
	s_mov_b64 s[16:17], s[4:5]
	v_add_u32_e32 v161, s18, v156
	ds_read_u16 v0, v161 offset:0
	ds_read_u16 v1, v161 offset:8
	ds_read_u16 v2, v161 offset:16
	ds_read_u16 v3, v161 offset:24
	ds_read_u16 v4, v161 offset:32
	ds_read_u16 v5, v161 offset:40
	ds_read_u16 v6, v161 offset:48
	ds_read_u16 v7, v161 offset:56
	s_waitcnt lgkmcnt(7)
	s_add_i32 m0, s8, 0x2000
	v_lshl_add_u32 v8, v0, 8, v10
	global_load_lds_dwordx4 v8, s[16:17]
	s_waitcnt lgkmcnt(6)
	s_add_i32 m0, s8, 0x2400
	v_lshl_add_u32 v9, v1, 8, v11
	global_load_lds_dwordx4 v9, s[16:17]
	s_waitcnt lgkmcnt(5)
	s_add_i32 m0, s8, 0x2800
	v_lshl_add_u32 v8, v2, 8, v12
	global_load_lds_dwordx4 v8, s[16:17]
	s_waitcnt lgkmcnt(4)
	s_add_i32 m0, s8, 0x2c00
	v_lshl_add_u32 v9, v3, 8, v13
	global_load_lds_dwordx4 v9, s[16:17]
	s_waitcnt lgkmcnt(3)
	s_add_i32 m0, s8, 0x3000
	v_lshl_add_u32 v8, v4, 8, v10
	global_load_lds_dwordx4 v8, s[16:17]
	s_waitcnt lgkmcnt(2)
	s_add_i32 m0, s8, 0x3400
	v_lshl_add_u32 v9, v5, 8, v11
	global_load_lds_dwordx4 v9, s[16:17]
	s_waitcnt lgkmcnt(1)
	s_add_i32 m0, s8, 0x3800
	v_lshl_add_u32 v8, v6, 8, v12
	global_load_lds_dwordx4 v8, s[16:17]
	s_waitcnt lgkmcnt(0)
	s_add_i32 m0, s8, 0x3c00
	v_lshl_add_u32 v9, v7, 8, v13
	global_load_lds_dwordx4 v9, s[16:17]
	s_waitcnt vmcnt(8)
	ds_read_b64_tr_b16 v[104:105], v148 offset:0
	ds_read_b64_tr_b16 v[106:107], v148 offset:4096
	ds_read_b64_tr_b16 v[108:109], v149 offset:0
	ds_read_b64_tr_b16 v[110:111], v149 offset:4096
	ds_read_b64_tr_b16 v[112:113], v150 offset:0
	ds_read_b64_tr_b16 v[114:115], v150 offset:4096
	ds_read_b64_tr_b16 v[116:117], v151 offset:0
	ds_read_b64_tr_b16 v[118:119], v151 offset:4096
	ds_read_b64_tr_b16 v[120:121], v152 offset:0
	ds_read_b64_tr_b16 v[122:123], v152 offset:4096
	ds_read_b64_tr_b16 v[124:125], v153 offset:0
	ds_read_b64_tr_b16 v[126:127], v153 offset:4096
	ds_read_b64_tr_b16 v[128:129], v154 offset:0
	ds_read_b64_tr_b16 v[130:131], v154 offset:4096
	s_waitcnt lgkmcnt(12)
	v_mfma_f32_16x16x32_bf16 v[176:179], v[56:59], v[104:107], v[176:179]
	ds_read_b64_tr_b16 v[132:133], v155 offset:0
	ds_read_b64_tr_b16 v[134:135], v155 offset:4096
	s_waitcnt lgkmcnt(12)
	v_mfma_f32_16x16x32_bf16 v[180:183], v[56:59], v[108:111], v[180:183]
	s_waitcnt lgkmcnt(10)
	v_mfma_f32_16x16x32_bf16 v[184:187], v[56:59], v[112:115], v[184:187]
	s_waitcnt lgkmcnt(8)
	v_mfma_f32_16x16x32_bf16 v[188:191], v[56:59], v[116:119], v[188:191]
	s_waitcnt lgkmcnt(6)
	v_mfma_f32_16x16x32_bf16 v[192:195], v[56:59], v[120:123], v[192:195]
	s_waitcnt lgkmcnt(4)
	v_mfma_f32_16x16x32_bf16 v[196:199], v[56:59], v[124:127], v[196:199]
	s_waitcnt lgkmcnt(2)
	v_mfma_f32_16x16x32_bf16 v[200:203], v[56:59], v[128:131], v[200:203]
	s_waitcnt lgkmcnt(0)
	v_mfma_f32_16x16x32_bf16 v[204:207], v[56:59], v[132:135], v[204:207]
	s_cmp_eq_u32 s11, 0
	s_cselect_b32 s18, 512, 0
	s_add_i32 s18, s18, s14
	s_mov_b64 s[16:17], s[2:3]
	v_add_u32_e32 v161, s18, v156
	ds_read_u16 v0, v161 offset:0
	ds_read_u16 v1, v161 offset:8
	ds_read_u16 v2, v161 offset:16
	ds_read_u16 v3, v161 offset:24
	ds_read_u16 v4, v161 offset:32
	ds_read_u16 v5, v161 offset:40
	ds_read_u16 v6, v161 offset:48
	ds_read_u16 v7, v161 offset:56
	s_waitcnt lgkmcnt(7)
	s_add_i32 m0, s8, 0x0
	v_lshl_add_u32 v8, v0, 8, v10
	global_load_lds_dwordx4 v8, s[16:17]
	s_waitcnt lgkmcnt(6)
	s_add_i32 m0, s8, 0x400
	v_lshl_add_u32 v9, v1, 8, v11
	global_load_lds_dwordx4 v9, s[16:17]
	s_waitcnt lgkmcnt(5)
	s_add_i32 m0, s8, 0x800
	v_lshl_add_u32 v8, v2, 8, v12
	global_load_lds_dwordx4 v8, s[16:17]
	s_waitcnt lgkmcnt(4)
	s_add_i32 m0, s8, 0xc00
	v_lshl_add_u32 v9, v3, 8, v13
	global_load_lds_dwordx4 v9, s[16:17]
	s_waitcnt lgkmcnt(3)
	s_add_i32 m0, s8, 0x1000
	v_lshl_add_u32 v8, v4, 8, v10
	global_load_lds_dwordx4 v8, s[16:17]
	s_waitcnt lgkmcnt(2)
	s_add_i32 m0, s8, 0x1400
	v_lshl_add_u32 v9, v5, 8, v11
	global_load_lds_dwordx4 v9, s[16:17]
	s_waitcnt lgkmcnt(1)
	s_add_i32 m0, s8, 0x1800
	v_lshl_add_u32 v8, v6, 8, v12
	global_load_lds_dwordx4 v8, s[16:17]
	s_waitcnt lgkmcnt(0)
	s_add_i32 m0, s8, 0x1c00
	v_lshl_add_u32 v9, v7, 8, v13
	global_load_lds_dwordx4 v9, s[16:17]
	s_waitcnt vmcnt(8)
	ds_read_b64_tr_b16 v[104:105], v148 offset:8192
	ds_read_b64_tr_b16 v[106:107], v148 offset:12288
	ds_read_b64_tr_b16 v[108:109], v149 offset:8192
	ds_read_b64_tr_b16 v[110:111], v149 offset:12288
	ds_read_b64_tr_b16 v[112:113], v150 offset:8192
	ds_read_b64_tr_b16 v[114:115], v150 offset:12288
	ds_read_b64_tr_b16 v[116:117], v151 offset:8192
	ds_read_b64_tr_b16 v[118:119], v151 offset:12288
	ds_read_b64_tr_b16 v[120:121], v152 offset:8192
	ds_read_b64_tr_b16 v[122:123], v152 offset:12288
	ds_read_b64_tr_b16 v[124:125], v153 offset:8192
	ds_read_b64_tr_b16 v[126:127], v153 offset:12288
	ds_read_b64_tr_b16 v[128:129], v154 offset:8192
	ds_read_b64_tr_b16 v[130:131], v154 offset:12288
	s_waitcnt lgkmcnt(12)
	v_mfma_f32_16x16x32_bf16 v[176:179], v[64:67], v[104:107], v[176:179]
	ds_read_b64_tr_b16 v[132:133], v155 offset:8192
	ds_read_b64_tr_b16 v[134:135], v155 offset:12288
	s_waitcnt lgkmcnt(12)
	v_mfma_f32_16x16x32_bf16 v[180:183], v[64:67], v[108:111], v[180:183]
	s_waitcnt lgkmcnt(10)
	v_mfma_f32_16x16x32_bf16 v[184:187], v[64:67], v[112:115], v[184:187]
	s_waitcnt lgkmcnt(8)
	v_mfma_f32_16x16x32_bf16 v[188:191], v[64:67], v[116:119], v[188:191]
	s_waitcnt lgkmcnt(6)
	v_mfma_f32_16x16x32_bf16 v[192:195], v[64:67], v[120:123], v[192:195]
	s_waitcnt lgkmcnt(4)
	v_mfma_f32_16x16x32_bf16 v[196:199], v[64:67], v[124:127], v[196:199]
	s_waitcnt lgkmcnt(2)
	v_mfma_f32_16x16x32_bf16 v[200:203], v[64:67], v[128:131], v[200:203]
	s_waitcnt lgkmcnt(0)
	v_mfma_f32_16x16x32_bf16 v[204:207], v[64:67], v[132:135], v[204:207]
	s_nop 7
	s_mov_b32 exec_lo, -1
	s_mov_b32 exec_hi, 0
	v_cvt_pk_bf16_f32 v165, v176, 0
	ds_write_b16 v158, v165 offset:0
	v_cvt_pk_bf16_f32 v166, v177, 0
	ds_write_b16 v158, v166 offset:256
	v_cvt_pk_bf16_f32 v167, v178, 0
	ds_write_b16 v158, v167 offset:512
	v_cvt_pk_bf16_f32 v168, v179, 0
	ds_write_b16 v158, v168 offset:768
	v_cvt_pk_bf16_f32 v165, v180, 0
	ds_write_b16 v158, v165 offset:32
	v_cvt_pk_bf16_f32 v166, v181, 0
	ds_write_b16 v158, v166 offset:288
	v_cvt_pk_bf16_f32 v167, v182, 0
	ds_write_b16 v158, v167 offset:544
	v_cvt_pk_bf16_f32 v168, v183, 0
	ds_write_b16 v158, v168 offset:800
	v_cvt_pk_bf16_f32 v165, v184, 0
	ds_write_b16 v158, v165 offset:64
	v_cvt_pk_bf16_f32 v166, v185, 0
	ds_write_b16 v158, v166 offset:320
	v_cvt_pk_bf16_f32 v167, v186, 0
	ds_write_b16 v158, v167 offset:576
	v_cvt_pk_bf16_f32 v168, v187, 0
	ds_write_b16 v158, v168 offset:832
	v_cvt_pk_bf16_f32 v165, v188, 0
	ds_write_b16 v158, v165 offset:96
	v_cvt_pk_bf16_f32 v166, v189, 0
	ds_write_b16 v158, v166 offset:352
	v_cvt_pk_bf16_f32 v167, v190, 0
	ds_write_b16 v158, v167 offset:608
	v_cvt_pk_bf16_f32 v168, v191, 0
	ds_write_b16 v158, v168 offset:864
	v_cvt_pk_bf16_f32 v165, v192, 0
	ds_write_b16 v158, v165 offset:128
	v_cvt_pk_bf16_f32 v166, v193, 0
	ds_write_b16 v158, v166 offset:384
	v_cvt_pk_bf16_f32 v167, v194, 0
	ds_write_b16 v158, v167 offset:640
	v_cvt_pk_bf16_f32 v168, v195, 0
	ds_write_b16 v158, v168 offset:896
	v_cvt_pk_bf16_f32 v165, v196, 0
	ds_write_b16 v158, v165 offset:160
	v_cvt_pk_bf16_f32 v166, v197, 0
	ds_write_b16 v158, v166 offset:416
	v_cvt_pk_bf16_f32 v167, v198, 0
	ds_write_b16 v158, v167 offset:672
	v_cvt_pk_bf16_f32 v168, v199, 0
	ds_write_b16 v158, v168 offset:928
	v_cvt_pk_bf16_f32 v165, v200, 0
	ds_write_b16 v158, v165 offset:192
	v_cvt_pk_bf16_f32 v166, v201, 0
	ds_write_b16 v158, v166 offset:448
	v_cvt_pk_bf16_f32 v167, v202, 0
	ds_write_b16 v158, v167 offset:704
	v_cvt_pk_bf16_f32 v168, v203, 0
	ds_write_b16 v158, v168 offset:960
	v_cvt_pk_bf16_f32 v165, v204, 0
	ds_write_b16 v158, v165 offset:224
	v_cvt_pk_bf16_f32 v166, v205, 0
	ds_write_b16 v158, v166 offset:480
	v_cvt_pk_bf16_f32 v167, v206, 0
	ds_write_b16 v158, v167 offset:736
	v_cvt_pk_bf16_f32 v168, v207, 0
	ds_write_b16 v158, v168 offset:992
	s_mov_b64 exec, -1
	s_waitcnt lgkmcnt(0)
	ds_read_b128 v[104:107], v159
	ds_read_b128 v[108:111], v159 offset:1024
	s_lshl_b32 s13, s12, 12
	v_add_u32_e32 v162, s13, v160
	s_waitcnt lgkmcnt(1)
	global_store_dwordx4 v162, v[104:107], s[6:7]
	s_waitcnt lgkmcnt(0)
	global_store_dwordx4 v162, v[108:111], s[6:7] offset:1024
	s_add_i32 s11, s11, 1
	s_add_i32 s12, s12, 1
	s_addk_i32 s14, 0x200
	s_cmp_lt_u32 s11, 2
	s_cbranch_scc1 .Lattn_q6
	s_branch .Lattn_done
.Lattn_q4:
	s_add_i32 s18, s14, 64
	s_mov_b64 s[16:17], s[2:3]
	v_add_u32_e32 v161, s18, v156
	ds_read_u16 v0, v161 offset:0
	ds_read_u16 v1, v161 offset:8
	ds_read_u16 v2, v161 offset:16
	ds_read_u16 v3, v161 offset:24
	ds_read_u16 v4, v161 offset:32
	ds_read_u16 v5, v161 offset:40
	ds_read_u16 v6, v161 offset:48
	ds_read_u16 v7, v161 offset:56
	s_waitcnt lgkmcnt(7)
	s_add_i32 m0, s8, 0x2000
	v_lshl_add_u32 v8, v0, 8, v10
	global_load_lds_dwordx4 v8, s[16:17]
	s_waitcnt lgkmcnt(6)
	s_add_i32 m0, s8, 0x2400
	v_lshl_add_u32 v9, v1, 8, v11
	global_load_lds_dwordx4 v9, s[16:17]
	s_waitcnt lgkmcnt(5)
	s_add_i32 m0, s8, 0x2800
	v_lshl_add_u32 v8, v2, 8, v12
	global_load_lds_dwordx4 v8, s[16:17]
	s_waitcnt lgkmcnt(4)
	s_add_i32 m0, s8, 0x2c00
	v_lshl_add_u32 v9, v3, 8, v13
	global_load_lds_dwordx4 v9, s[16:17]
	s_waitcnt lgkmcnt(3)
	s_add_i32 m0, s8, 0x3000
	v_lshl_add_u32 v8, v4, 8, v10
	global_load_lds_dwordx4 v8, s[16:17]
	s_waitcnt lgkmcnt(2)
	s_add_i32 m0, s8, 0x3400
	v_lshl_add_u32 v9, v5, 8, v11
	global_load_lds_dwordx4 v9, s[16:17]
	s_waitcnt lgkmcnt(1)
	s_add_i32 m0, s8, 0x3800
	v_lshl_add_u32 v8, v6, 8, v12
	global_load_lds_dwordx4 v8, s[16:17]
	s_waitcnt lgkmcnt(0)
	s_add_i32 m0, s8, 0x3c00
	v_lshl_add_u32 v9, v7, 8, v13
	global_load_lds_dwordx4 v9, s[16:17]
	s_waitcnt vmcnt(8)
	ds_read_b128 v[104:107], v18 offset:0
	ds_read_b128 v[108:111], v19 offset:0
	ds_read_b128 v[112:115], v20 offset:0
	ds_read_b128 v[116:119], v21 offset:0
	ds_read_b128 v[120:123], v18 offset:4096
	ds_read_b128 v[124:127], v19 offset:4096
	ds_read_b128 v[128:131], v20 offset:4096
	ds_read_b128 v[132:135], v21 offset:4096
	s_waitcnt lgkmcnt(7)
	v_mfma_f32_16x16x32_bf16 v[136:139], v[104:107], v[88:91], 0
	s_waitcnt lgkmcnt(6)
	v_mfma_f32_16x16x32_bf16 v[136:139], v[108:111], v[92:95], v[136:139]
	s_waitcnt lgkmcnt(5)
	v_mfma_f32_16x16x32_bf16 v[136:139], v[112:115], v[96:99], v[136:139]
	s_waitcnt lgkmcnt(4)
	v_mfma_f32_16x16x32_bf16 v[136:139], v[116:119], v[100:103], v[136:139]
	s_waitcnt lgkmcnt(3)
	v_mfma_f32_16x16x32_bf16 v[140:143], v[120:123], v[88:91], 0
	s_waitcnt lgkmcnt(2)
	v_mfma_f32_16x16x32_bf16 v[140:143], v[124:127], v[92:95], v[140:143]
	s_waitcnt lgkmcnt(1)
	v_mfma_f32_16x16x32_bf16 v[140:143], v[128:131], v[96:99], v[140:143]
	s_waitcnt lgkmcnt(0)
	v_mfma_f32_16x16x32_bf16 v[140:143], v[132:135], v[100:103], v[140:143]
	v_mul_f32_e32 v24, 0x3db504f3, v136
	v_mul_f32_e32 v25, 0x3db504f3, v137
	v_mul_f32_e32 v26, 0x3db504f3, v138
	v_mul_f32_e32 v27, 0x3db504f3, v139
	s_nop 3
	v_mul_f32_e32 v28, 0x3db504f3, v140
	v_mul_f32_e32 v29, 0x3db504f3, v141
	v_mul_f32_e32 v30, 0x3db504f3, v142
	v_mul_f32_e32 v31, 0x3db504f3, v143
	s_add_i32 s18, s14, 128
	s_mov_b64 s[16:17], s[2:3]
	v_add_u32_e32 v161, s18, v156
	ds_read_u16 v0, v161 offset:0
	ds_read_u16 v1, v161 offset:8
	ds_read_u16 v2, v161 offset:16
	ds_read_u16 v3, v161 offset:24
	ds_read_u16 v4, v161 offset:32
	ds_read_u16 v5, v161 offset:40
	ds_read_u16 v6, v161 offset:48
	ds_read_u16 v7, v161 offset:56
	s_waitcnt lgkmcnt(7)
	s_add_i32 m0, s8, 0x0
	v_lshl_add_u32 v8, v0, 8, v10
	global_load_lds_dwordx4 v8, s[16:17]
	s_waitcnt lgkmcnt(6)
	s_add_i32 m0, s8, 0x400
	v_lshl_add_u32 v9, v1, 8, v11
	global_load_lds_dwordx4 v9, s[16:17]
	s_waitcnt lgkmcnt(5)
	s_add_i32 m0, s8, 0x800
	v_lshl_add_u32 v8, v2, 8, v12
	global_load_lds_dwordx4 v8, s[16:17]
	s_waitcnt lgkmcnt(4)
	s_add_i32 m0, s8, 0xc00
	v_lshl_add_u32 v9, v3, 8, v13
	global_load_lds_dwordx4 v9, s[16:17]
	s_waitcnt lgkmcnt(3)
	s_add_i32 m0, s8, 0x1000
	v_lshl_add_u32 v8, v4, 8, v10
	global_load_lds_dwordx4 v8, s[16:17]
	s_waitcnt lgkmcnt(2)
	s_add_i32 m0, s8, 0x1400
	v_lshl_add_u32 v9, v5, 8, v11
	global_load_lds_dwordx4 v9, s[16:17]
	s_waitcnt lgkmcnt(1)
	s_add_i32 m0, s8, 0x1800
	v_lshl_add_u32 v8, v6, 8, v12
	global_load_lds_dwordx4 v8, s[16:17]
	s_waitcnt lgkmcnt(0)
	s_add_i32 m0, s8, 0x1c00
	v_lshl_add_u32 v9, v7, 8, v13
	global_load_lds_dwordx4 v9, s[16:17]
	s_waitcnt vmcnt(8)
	ds_read_b128 v[104:107], v18 offset:8192
	ds_read_b128 v[108:111], v19 offset:8192
	ds_read_b128 v[112:115], v20 offset:8192
	ds_read_b128 v[116:119], v21 offset:8192
	ds_read_b128 v[120:123], v18 offset:12288
	ds_read_b128 v[124:127], v19 offset:12288
	ds_read_b128 v[128:131], v20 offset:12288
	ds_read_b128 v[132:135], v21 offset:12288
	s_waitcnt lgkmcnt(7)
	v_mfma_f32_16x16x32_bf16 v[136:139], v[104:107], v[88:91], 0
	s_waitcnt lgkmcnt(6)
	v_mfma_f32_16x16x32_bf16 v[136:139], v[108:111], v[92:95], v[136:139]
	s_waitcnt lgkmcnt(5)
	v_mfma_f32_16x16x32_bf16 v[136:139], v[112:115], v[96:99], v[136:139]
	s_waitcnt lgkmcnt(4)
	v_mfma_f32_16x16x32_bf16 v[136:139], v[116:119], v[100:103], v[136:139]
	s_waitcnt lgkmcnt(3)
	v_mfma_f32_16x16x32_bf16 v[140:143], v[120:123], v[88:91], 0
	s_waitcnt lgkmcnt(2)
	v_mfma_f32_16x16x32_bf16 v[140:143], v[124:127], v[92:95], v[140:143]
	s_waitcnt lgkmcnt(1)
	v_mfma_f32_16x16x32_bf16 v[140:143], v[128:131], v[96:99], v[140:143]
	s_waitcnt lgkmcnt(0)
	v_mfma_f32_16x16x32_bf16 v[140:143], v[132:135], v[100:103], v[140:143]
	v_mul_f32_e32 v32, 0x3db504f3, v136
	v_mul_f32_e32 v33, 0x3db504f3, v137
	v_mul_f32_e32 v34, 0x3db504f3, v138
	v_mul_f32_e32 v35, 0x3db504f3, v139
	s_nop 3
	v_mul_f32_e32 v36, 0x3db504f3, v140
	v_mul_f32_e32 v37, 0x3db504f3, v141
	v_mul_f32_e32 v38, 0x3db504f3, v142
	v_mul_f32_e32 v39, 0x3db504f3, v143
	s_add_i32 s18, s14, 192
	s_mov_b64 s[16:17], s[2:3]
	v_add_u32_e32 v161, s18, v156
	ds_read_u16 v0, v161 offset:0
	ds_read_u16 v1, v161 offset:8
	ds_read_u16 v2, v161 offset:16
	ds_read_u16 v3, v161 offset:24
	ds_read_u16 v4, v161 offset:32
	ds_read_u16 v5, v161 offset:40
	ds_read_u16 v6, v161 offset:48
	ds_read_u16 v7, v161 offset:56
	s_waitcnt lgkmcnt(7)
	s_add_i32 m0, s8, 0x2000
	v_lshl_add_u32 v8, v0, 8, v10
	global_load_lds_dwordx4 v8, s[16:17]
	s_waitcnt lgkmcnt(6)
	s_add_i32 m0, s8, 0x2400
	v_lshl_add_u32 v9, v1, 8, v11
	global_load_lds_dwordx4 v9, s[16:17]
	s_waitcnt lgkmcnt(5)
	s_add_i32 m0, s8, 0x2800
	v_lshl_add_u32 v8, v2, 8, v12
	global_load_lds_dwordx4 v8, s[16:17]
	s_waitcnt lgkmcnt(4)
	s_add_i32 m0, s8, 0x2c00
	v_lshl_add_u32 v9, v3, 8, v13
	global_load_lds_dwordx4 v9, s[16:17]
	s_waitcnt lgkmcnt(3)
	s_add_i32 m0, s8, 0x3000
	v_lshl_add_u32 v8, v4, 8, v10
	global_load_lds_dwordx4 v8, s[16:17]
	s_waitcnt lgkmcnt(2)
	s_add_i32 m0, s8, 0x3400
	v_lshl_add_u32 v9, v5, 8, v11
	global_load_lds_dwordx4 v9, s[16:17]
	s_waitcnt lgkmcnt(1)
	s_add_i32 m0, s8, 0x3800
	v_lshl_add_u32 v8, v6, 8, v12
	global_load_lds_dwordx4 v8, s[16:17]
	s_waitcnt lgkmcnt(0)
	s_add_i32 m0, s8, 0x3c00
	v_lshl_add_u32 v9, v7, 8, v13
	global_load_lds_dwordx4 v9, s[16:17]
	s_waitcnt vmcnt(8)
	ds_read_b128 v[104:107], v18 offset:0
	ds_read_b128 v[108:111], v19 offset:0
	ds_read_b128 v[112:115], v20 offset:0
	ds_read_b128 v[116:119], v21 offset:0
	ds_read_b128 v[120:123], v18 offset:4096
	ds_read_b128 v[124:127], v19 offset:4096
	ds_read_b128 v[128:131], v20 offset:4096
	ds_read_b128 v[132:135], v21 offset:4096
	s_waitcnt lgkmcnt(7)
	v_mfma_f32_16x16x32_bf16 v[136:139], v[104:107], v[88:91], 0
	s_waitcnt lgkmcnt(6)
	v_mfma_f32_16x16x32_bf16 v[136:139], v[108:111], v[92:95], v[136:139]
	s_waitcnt lgkmcnt(5)
	v_mfma_f32_16x16x32_bf16 v[136:139], v[112:115], v[96:99], v[136:139]
	s_waitcnt lgkmcnt(4)
	v_mfma_f32_16x16x32_bf16 v[136:139], v[116:119], v[100:103], v[136:139]
	s_waitcnt lgkmcnt(3)
	v_mfma_f32_16x16x32_bf16 v[140:143], v[120:123], v[88:91], 0
	s_waitcnt lgkmcnt(2)
	v_mfma_f32_16x16x32_bf16 v[140:143], v[124:127], v[92:95], v[140:143]
	s_waitcnt lgkmcnt(1)
	v_mfma_f32_16x16x32_bf16 v[140:143], v[128:131], v[96:99], v[140:143]
	s_waitcnt lgkmcnt(0)
	v_mfma_f32_16x16x32_bf16 v[140:143], v[132:135], v[100:103], v[140:143]
	v_mul_f32_e32 v40, 0x3db504f3, v136
	v_mul_f32_e32 v41, 0x3db504f3, v137
	v_mul_f32_e32 v42, 0x3db504f3, v138
	v_mul_f32_e32 v43, 0x3db504f3, v139
	s_nop 3
	v_mul_f32_e32 v44, 0x3db504f3, v140
	v_mul_f32_e32 v45, 0x3db504f3, v141
	v_mul_f32_e32 v46, 0x3db504f3, v142
	v_mul_f32_e32 v47, 0x3db504f3, v143
	s_mov_b32 s18, s14
	s_mov_b64 s[16:17], s[4:5]
	v_add_u32_e32 v161, s18, v156
	ds_read_u16 v0, v161 offset:0
	ds_read_u16 v1, v161 offset:8
	ds_read_u16 v2, v161 offset:16
	ds_read_u16 v3, v161 offset:24
	ds_read_u16 v4, v161 offset:32
	ds_read_u16 v5, v161 offset:40
	ds_read_u16 v6, v161 offset:48
	ds_read_u16 v7, v161 offset:56
	s_waitcnt lgkmcnt(7)
	s_add_i32 m0, s8, 0x0
	v_lshl_add_u32 v8, v0, 8, v10
	global_load_lds_dwordx4 v8, s[16:17]
	s_waitcnt lgkmcnt(6)
	s_add_i32 m0, s8, 0x400
	v_lshl_add_u32 v9, v1, 8, v11
	global_load_lds_dwordx4 v9, s[16:17]
	s_waitcnt lgkmcnt(5)
	s_add_i32 m0, s8, 0x800
	v_lshl_add_u32 v8, v2, 8, v12
	global_load_lds_dwordx4 v8, s[16:17]
	s_waitcnt lgkmcnt(4)
	s_add_i32 m0, s8, 0xc00
	v_lshl_add_u32 v9, v3, 8, v13
	global_load_lds_dwordx4 v9, s[16:17]
	s_waitcnt lgkmcnt(3)
	s_add_i32 m0, s8, 0x1000
	v_lshl_add_u32 v8, v4, 8, v10
	global_load_lds_dwordx4 v8, s[16:17]
	s_waitcnt lgkmcnt(2)
	s_add_i32 m0, s8, 0x1400
	v_lshl_add_u32 v9, v5, 8, v11
	global_load_lds_dwordx4 v9, s[16:17]
	s_waitcnt lgkmcnt(1)
	s_add_i32 m0, s8, 0x1800
	v_lshl_add_u32 v8, v6, 8, v12
	global_load_lds_dwordx4 v8, s[16:17]
	s_waitcnt lgkmcnt(0)
	s_add_i32 m0, s8, 0x1c00
	v_lshl_add_u32 v9, v7, 8, v13
	global_load_lds_dwordx4 v9, s[16:17]
	s_waitcnt vmcnt(8)
	ds_read_b128 v[104:107], v18 offset:8192
	ds_read_b128 v[108:111], v19 offset:8192
	ds_read_b128 v[112:115], v20 offset:8192
	ds_read_b128 v[116:119], v21 offset:8192
	ds_read_b128 v[120:123], v18 offset:12288
	ds_read_b128 v[124:127], v19 offset:12288
	ds_read_b128 v[128:131], v20 offset:12288
	ds_read_b128 v[132:135], v21 offset:12288
	s_waitcnt lgkmcnt(7)
	v_mfma_f32_16x16x32_bf16 v[136:139], v[104:107], v[88:91], 0
	s_waitcnt lgkmcnt(6)
	v_mfma_f32_16x16x32_bf16 v[136:139], v[108:111], v[92:95], v[136:139]
	s_waitcnt lgkmcnt(5)
	v_mfma_f32_16x16x32_bf16 v[136:139], v[112:115], v[96:99], v[136:139]
	s_waitcnt lgkmcnt(4)
	v_mfma_f32_16x16x32_bf16 v[136:139], v[116:119], v[100:103], v[136:139]
	s_waitcnt lgkmcnt(3)
	v_mfma_f32_16x16x32_bf16 v[140:143], v[120:123], v[88:91], 0
	s_waitcnt lgkmcnt(2)
	v_mfma_f32_16x16x32_bf16 v[140:143], v[124:127], v[92:95], v[140:143]
	s_waitcnt lgkmcnt(1)
	v_mfma_f32_16x16x32_bf16 v[140:143], v[128:131], v[96:99], v[140:143]
	s_waitcnt lgkmcnt(0)
	v_mfma_f32_16x16x32_bf16 v[140:143], v[132:135], v[100:103], v[140:143]
	v_mul_f32_e32 v48, 0x3db504f3, v136
	v_mul_f32_e32 v49, 0x3db504f3, v137
	v_mul_f32_e32 v50, 0x3db504f3, v138
	v_mul_f32_e32 v51, 0x3db504f3, v139
	s_nop 3
	v_mul_f32_e32 v52, 0x3db504f3, v140
	v_mul_f32_e32 v53, 0x3db504f3, v141
	v_mul_f32_e32 v54, 0x3db504f3, v142
	v_mul_f32_e32 v55, 0x3db504f3, v143
	v_max3_f32 v163, v24, v25, v26
	v_max3_f32 v163, v163, v27, v28
	v_max3_f32 v163, v163, v29, v30
	v_max3_f32 v163, v163, v31, v32
	v_max3_f32 v163, v163, v33, v34
	v_max3_f32 v163, v163, v35, v36
	v_max3_f32 v163, v163, v37, v38
	v_max3_f32 v163, v163, v39, v40
	v_max3_f32 v163, v163, v41, v42
	v_max3_f32 v163, v163, v43, v44
	v_max3_f32 v163, v163, v45, v46
	v_max3_f32 v163, v163, v47, v48
	v_max3_f32 v163, v163, v49, v50
	v_max3_f32 v163, v163, v51, v52
	v_max3_f32 v163, v163, v53, v54
	v_max_f32_e32 v163, v163, v55
	s_nop 0
	ds_bpermute_b32 v165, v147, v163
	s_waitcnt lgkmcnt(0)
	v_max_f32_e32 v163, v163, v165
	s_nop 0
	ds_bpermute_b32 v165, v146, v163
	s_waitcnt lgkmcnt(0)
	v_max_f32_e32 v163, v163, v165
	v_sub_f32_e32 v165, v24, v163
	v_mul_f32_e32 v165, 0x3fb8aa3b, v165
	v_exp_f32_e32 v24, v165
	v_sub_f32_e32 v166, v25, v163
	v_mul_f32_e32 v166, 0x3fb8aa3b, v166
	v_exp_f32_e32 v25, v166
	v_sub_f32_e32 v167, v26, v163
	v_mul_f32_e32 v167, 0x3fb8aa3b, v167
	v_exp_f32_e32 v26, v167
	v_add_f32_e32 v164, 0, v24
	v_sub_f32_e32 v168, v27, v163
	v_mul_f32_e32 v168, 0x3fb8aa3b, v168
	v_exp_f32_e32 v27, v168
	v_add_f32_e32 v164, v164, v25
	v_sub_f32_e32 v165, v28, v163
	v_mul_f32_e32 v165, 0x3fb8aa3b, v165
	v_exp_f32_e32 v28, v165
	v_add_f32_e32 v164, v164, v26
	v_sub_f32_e32 v166, v29, v163
	v_mul_f32_e32 v166, 0x3fb8aa3b, v166
	v_exp_f32_e32 v29, v166
	v_add_f32_e32 v164, v164, v27
	v_sub_f32_e32 v167, v30, v163
	v_mul_f32_e32 v167, 0x3fb8aa3b, v167
	v_exp_f32_e32 v30, v167
	v_add_f32_e32 v164, v164, v28
	v_sub_f32_e32 v168, v31, v163
	v_mul_f32_e32 v168, 0x3fb8aa3b, v168
	v_exp_f32_e32 v31, v168
	v_add_f32_e32 v164, v164, v29
	v_sub_f32_e32 v165, v32, v163
	v_mul_f32_e32 v165, 0x3fb8aa3b, v165
	v_exp_f32_e32 v32, v165
	v_add_f32_e32 v164, v164, v30
	v_sub_f32_e32 v166, v33, v163
	v_mul_f32_e32 v166, 0x3fb8aa3b, v166
	v_exp_f32_e32 v33, v166
	v_add_f32_e32 v164, v164, v31
	v_sub_f32_e32 v167, v34, v163
	v_mul_f32_e32 v167, 0x3fb8aa3b, v167
	v_exp_f32_e32 v34, v167
	v_add_f32_e32 v164, v164, v32
	v_sub_f32_e32 v168, v35, v163
	v_mul_f32_e32 v168, 0x3fb8aa3b, v168
	v_exp_f32_e32 v35, v168
	v_add_f32_e32 v164, v164, v33
	v_sub_f32_e32 v165, v36, v163
	v_mul_f32_e32 v165, 0x3fb8aa3b, v165
	v_exp_f32_e32 v36, v165
	v_add_f32_e32 v164, v164, v34
	v_sub_f32_e32 v166, v37, v163
	v_mul_f32_e32 v166, 0x3fb8aa3b, v166
	v_exp_f32_e32 v37, v166
	v_add_f32_e32 v164, v164, v35
	v_sub_f32_e32 v167, v38, v163
	v_mul_f32_e32 v167, 0x3fb8aa3b, v167
	v_exp_f32_e32 v38, v167
	v_add_f32_e32 v164, v164, v36
	v_sub_f32_e32 v168, v39, v163
	v_mul_f32_e32 v168, 0x3fb8aa3b, v168
	v_exp_f32_e32 v39, v168
	v_add_f32_e32 v164, v164, v37
	v_sub_f32_e32 v165, v40, v163
	v_mul_f32_e32 v165, 0x3fb8aa3b, v165
	v_exp_f32_e32 v40, v165
	v_add_f32_e32 v164, v164, v38
	v_sub_f32_e32 v166, v41, v163
	v_mul_f32_e32 v166, 0x3fb8aa3b, v166
	v_exp_f32_e32 v41, v166
	v_add_f32_e32 v164, v164, v39
	v_sub_f32_e32 v167, v42, v163
	v_mul_f32_e32 v167, 0x3fb8aa3b, v167
	v_exp_f32_e32 v42, v167
	v_add_f32_e32 v164, v164, v40
	v_sub_f32_e32 v168, v43, v163
	v_mul_f32_e32 v168, 0x3fb8aa3b, v168
	v_exp_f32_e32 v43, v168
	v_add_f32_e32 v164, v164, v41
	v_sub_f32_e32 v165, v44, v163
	v_mul_f32_e32 v165, 0x3fb8aa3b, v165
	v_exp_f32_e32 v44, v165
	v_add_f32_e32 v164, v164, v42
	v_sub_f32_e32 v166, v45, v163
	v_mul_f32_e32 v166, 0x3fb8aa3b, v166
	v_exp_f32_e32 v45, v166
	v_add_f32_e32 v164, v164, v43
	v_sub_f32_e32 v167, v46, v163
	v_mul_f32_e32 v167, 0x3fb8aa3b, v167
	v_exp_f32_e32 v46, v167
	v_add_f32_e32 v164, v164, v44
	v_sub_f32_e32 v168, v47, v163
	v_mul_f32_e32 v168, 0x3fb8aa3b, v168
	v_exp_f32_e32 v47, v168
	v_add_f32_e32 v164, v164, v45
	v_sub_f32_e32 v165, v48, v163
	v_mul_f32_e32 v165, 0x3fb8aa3b, v165
	v_exp_f32_e32 v48, v165
	v_add_f32_e32 v164, v164, v46
	v_sub_f32_e32 v166, v49, v163
	v_mul_f32_e32 v166, 0x3fb8aa3b, v166
	v_exp_f32_e32 v49, v166
	v_add_f32_e32 v164, v164, v47
	v_sub_f32_e32 v167, v50, v163
	v_mul_f32_e32 v167, 0x3fb8aa3b, v167
	v_exp_f32_e32 v50, v167
	v_add_f32_e32 v164, v164, v48
	v_sub_f32_e32 v168, v51, v163
	v_mul_f32_e32 v168, 0x3fb8aa3b, v168
	v_exp_f32_e32 v51, v168
	v_add_f32_e32 v164, v164, v49
	v_sub_f32_e32 v165, v52, v163
	v_mul_f32_e32 v165, 0x3fb8aa3b, v165
	v_exp_f32_e32 v52, v165
	v_add_f32_e32 v164, v164, v50
	v_sub_f32_e32 v166, v53, v163
	v_mul_f32_e32 v166, 0x3fb8aa3b, v166
	v_exp_f32_e32 v53, v166
	v_add_f32_e32 v164, v164, v51
	v_sub_f32_e32 v167, v54, v163
	v_mul_f32_e32 v167, 0x3fb8aa3b, v167
	v_exp_f32_e32 v54, v167
	v_add_f32_e32 v164, v164, v52
	v_sub_f32_e32 v168, v55, v163
	v_mul_f32_e32 v168, 0x3fb8aa3b, v168
	v_exp_f32_e32 v55, v168
	v_add_f32_e32 v164, v164, v53
	s_nop 0
	v_add_f32_e32 v164, v164, v54
	v_add_f32_e32 v164, v164, v55
	s_nop 0
	ds_bpermute_b32 v165, v147, v164
	s_waitcnt lgkmcnt(0)
	v_add_f32_e32 v164, v164, v165
	s_nop 0
	ds_bpermute_b32 v165, v146, v164
	s_waitcnt lgkmcnt(0)
	v_add_f32_e32 v164, v164, v165
	v_div_scale_f32 v170, s[74:75], v164, v164, 1.0
	v_rcp_f32_e32 v171, v170
	s_nop 0
	v_fma_f32 v172, -v170, v171, 1.0
	v_fmac_f32_e32 v171, v172, v171
	v_div_scale_f32 v172, vcc, 1.0, v164, 1.0
	v_mul_f32_e32 v173, v172, v171
	v_fma_f32 v169, -v170, v173, v172
	v_fmac_f32_e32 v173, v169, v171
	v_fma_f32 v170, -v170, v173, v172
	v_div_fmas_f32 v170, v170, v171, v173
	v_div_fixup_f32 v169, v170, v164, 1.0
	v_mul_f32_e32 v165, v24, v169
	v_mul_f32_e32 v166, v25, v169
	v_cvt_pk_bf16_f32 v24, v165, v166
	v_mul_f32_e32 v167, v26, v169
	v_mul_f32_e32 v168, v27, v169
	v_cvt_pk_bf16_f32 v25, v167, v168
	v_mul_f32_e32 v165, v28, v169
	v_mul_f32_e32 v166, v29, v169
	v_cvt_pk_bf16_f32 v26, v165, v166
	v_mul_f32_e32 v167, v30, v169
	v_mul_f32_e32 v168, v31, v169
	v_cvt_pk_bf16_f32 v27, v167, v168
	v_mul_f32_e32 v165, v32, v169
	v_mul_f32_e32 v166, v33, v169
	v_cvt_pk_bf16_f32 v32, v165, v166
	v_mul_f32_e32 v167, v34, v169
	v_mul_f32_e32 v168, v35, v169
	v_cvt_pk_bf16_f32 v33, v167, v168
	v_mul_f32_e32 v165, v36, v169
	v_mul_f32_e32 v166, v37, v169
	v_cvt_pk_bf16_f32 v34, v165, v166
	v_mul_f32_e32 v167, v38, v169
	v_mul_f32_e32 v168, v39, v169
	v_cvt_pk_bf16_f32 v35, v167, v168
	v_mul_f32_e32 v165, v40, v169
	v_mul_f32_e32 v166, v41, v169
	v_cvt_pk_bf16_f32 v40, v165, v166
	v_mul_f32_e32 v167, v42, v169
	v_mul_f32_e32 v168, v43, v169
	v_cvt_pk_bf16_f32 v41, v167, v168
	v_mul_f32_e32 v165, v44, v169
	v_mul_f32_e32 v166, v45, v169
	v_cvt_pk_bf16_f32 v42, v165, v166
	v_mul_f32_e32 v167, v46, v169
	v_mul_f32_e32 v168, v47, v169
	v_cvt_pk_bf16_f32 v43, v167, v168
	v_mul_f32_e32 v165, v48, v169
	v_mul_f32_e32 v166, v49, v169
	v_cvt_pk_bf16_f32 v48, v165, v166
	v_mul_f32_e32 v167, v50, v169
	v_mul_f32_e32 v168, v51, v169
	v_cvt_pk_bf16_f32 v49, v167, v168
	v_mul_f32_e32 v165, v52, v169
	v_mul_f32_e32 v166, v53, v169
	v_cvt_pk_bf16_f32 v50, v165, v166
	v_mul_f32_e32 v167, v54, v169
	v_mul_f32_e32 v168, v55, v169
	v_cvt_pk_bf16_f32 v51, v167, v168
	s_cmp_eq_u32 s11, 0
	s_cselect_b32 s15, 1, 0
	s_add_i32 s15, s15, s12
	s_lshl_b32 s13, s15, 12
	v_add_u32_e32 v162, s13, v157
	global_load_dwordx4 v[88:91], v162, s[6:7] offset:0
	global_load_dwordx4 v[92:95], v162, s[6:7] offset:64
	global_load_dwordx4 v[96:99], v162, s[6:7] offset:128
	global_load_dwordx4 v[100:103], v162, s[6:7] offset:192
	s_add_i32 s18, s14, 64
	s_mov_b64 s[16:17], s[4:5]
	v_add_u32_e32 v161, s18, v156
	ds_read_u16 v0, v161 offset:0
	ds_read_u16 v1, v161 offset:8
	ds_read_u16 v2, v161 offset:16
	ds_read_u16 v3, v161 offset:24
	ds_read_u16 v4, v161 offset:32
	ds_read_u16 v5, v161 offset:40
	ds_read_u16 v6, v161 offset:48
	ds_read_u16 v7, v161 offset:56
	s_waitcnt lgkmcnt(7)
	s_add_i32 m0, s8, 0x2000
	v_lshl_add_u32 v8, v0, 8, v10
	global_load_lds_dwordx4 v8, s[16:17]
	s_waitcnt lgkmcnt(6)
	s_add_i32 m0, s8, 0x2400
	v_lshl_add_u32 v9, v1, 8, v11
	global_load_lds_dwordx4 v9, s[16:17]
	s_waitcnt lgkmcnt(5)
	s_add_i32 m0, s8, 0x2800
	v_lshl_add_u32 v8, v2, 8, v12
	global_load_lds_dwordx4 v8, s[16:17]
	s_waitcnt lgkmcnt(4)
	s_add_i32 m0, s8, 0x2c00
	v_lshl_add_u32 v9, v3, 8, v13
	global_load_lds_dwordx4 v9, s[16:17]
	s_waitcnt lgkmcnt(3)
	s_add_i32 m0, s8, 0x3000
	v_lshl_add_u32 v8, v4, 8, v10
	global_load_lds_dwordx4 v8, s[16:17]
	s_waitcnt lgkmcnt(2)
	s_add_i32 m0, s8, 0x3400
	v_lshl_add_u32 v9, v5, 8, v11
	global_load_lds_dwordx4 v9, s[16:17]
	s_waitcnt lgkmcnt(1)
	s_add_i32 m0, s8, 0x3800
	v_lshl_add_u32 v8, v6, 8, v12
	global_load_lds_dwordx4 v8, s[16:17]
	s_waitcnt lgkmcnt(0)
	s_add_i32 m0, s8, 0x3c00
	v_lshl_add_u32 v9, v7, 8, v13
	global_load_lds_dwordx4 v9, s[16:17]
	s_waitcnt vmcnt(8)
	ds_read_b64_tr_b16 v[104:105], v148 offset:0
	ds_read_b64_tr_b16 v[106:107], v148 offset:4096
	ds_read_b64_tr_b16 v[108:109], v149 offset:0
	ds_read_b64_tr_b16 v[110:111], v149 offset:4096
	ds_read_b64_tr_b16 v[112:113], v150 offset:0
	ds_read_b64_tr_b16 v[114:115], v150 offset:4096
	ds_read_b64_tr_b16 v[116:117], v151 offset:0
	ds_read_b64_tr_b16 v[118:119], v151 offset:4096
	ds_read_b64_tr_b16 v[120:121], v152 offset:0
	ds_read_b64_tr_b16 v[122:123], v152 offset:4096
	ds_read_b64_tr_b16 v[124:125], v153 offset:0
	ds_read_b64_tr_b16 v[126:127], v153 offset:4096
	ds_read_b64_tr_b16 v[128:129], v154 offset:0
	ds_read_b64_tr_b16 v[130:131], v154 offset:4096
	s_waitcnt lgkmcnt(12)
	v_mfma_f32_16x16x32_bf16 v[176:179], v[24:27], v[104:107], 0
	ds_read_b64_tr_b16 v[132:133], v155 offset:0
	ds_read_b64_tr_b16 v[134:135], v155 offset:4096
	s_waitcnt lgkmcnt(12)
	v_mfma_f32_16x16x32_bf16 v[180:183], v[24:27], v[108:111], 0
	s_waitcnt lgkmcnt(10)
	v_mfma_f32_16x16x32_bf16 v[184:187], v[24:27], v[112:115], 0
	s_waitcnt lgkmcnt(8)
	v_mfma_f32_16x16x32_bf16 v[188:191], v[24:27], v[116:119], 0
	s_waitcnt lgkmcnt(6)
	v_mfma_f32_16x16x32_bf16 v[192:195], v[24:27], v[120:123], 0
	s_waitcnt lgkmcnt(4)
	v_mfma_f32_16x16x32_bf16 v[196:199], v[24:27], v[124:127], 0
	s_waitcnt lgkmcnt(2)
	v_mfma_f32_16x16x32_bf16 v[200:203], v[24:27], v[128:131], 0
	s_waitcnt lgkmcnt(0)
	v_mfma_f32_16x16x32_bf16 v[204:207], v[24:27], v[132:135], 0
	s_add_i32 s18, s14, 128
	s_mov_b64 s[16:17], s[4:5]
	v_add_u32_e32 v161, s18, v156
	ds_read_u16 v0, v161 offset:0
	ds_read_u16 v1, v161 offset:8
	ds_read_u16 v2, v161 offset:16
	ds_read_u16 v3, v161 offset:24
	ds_read_u16 v4, v161 offset:32
	ds_read_u16 v5, v161 offset:40
	ds_read_u16 v6, v161 offset:48
	ds_read_u16 v7, v161 offset:56
	s_waitcnt lgkmcnt(7)
	s_add_i32 m0, s8, 0x0
	v_lshl_add_u32 v8, v0, 8, v10
	global_load_lds_dwordx4 v8, s[16:17]
	s_waitcnt lgkmcnt(6)
	s_add_i32 m0, s8, 0x400
	v_lshl_add_u32 v9, v1, 8, v11
	global_load_lds_dwordx4 v9, s[16:17]
	s_waitcnt lgkmcnt(5)
	s_add_i32 m0, s8, 0x800
	v_lshl_add_u32 v8, v2, 8, v12
	global_load_lds_dwordx4 v8, s[16:17]
	s_waitcnt lgkmcnt(4)
	s_add_i32 m0, s8, 0xc00
	v_lshl_add_u32 v9, v3, 8, v13
	global_load_lds_dwordx4 v9, s[16:17]
	s_waitcnt lgkmcnt(3)
	s_add_i32 m0, s8, 0x1000
	v_lshl_add_u32 v8, v4, 8, v10
	global_load_lds_dwordx4 v8, s[16:17]
	s_waitcnt lgkmcnt(2)
	s_add_i32 m0, s8, 0x1400
	v_lshl_add_u32 v9, v5, 8, v11
	global_load_lds_dwordx4 v9, s[16:17]
	s_waitcnt lgkmcnt(1)
	s_add_i32 m0, s8, 0x1800
	v_lshl_add_u32 v8, v6, 8, v12
	global_load_lds_dwordx4 v8, s[16:17]
	s_waitcnt lgkmcnt(0)
	s_add_i32 m0, s8, 0x1c00
	v_lshl_add_u32 v9, v7, 8, v13
	global_load_lds_dwordx4 v9, s[16:17]
	s_waitcnt vmcnt(8)
	ds_read_b64_tr_b16 v[104:105], v148 offset:8192
	ds_read_b64_tr_b16 v[106:107], v148 offset:12288
	ds_read_b64_tr_b16 v[108:109], v149 offset:8192
	ds_read_b64_tr_b16 v[110:111], v149 offset:12288
	ds_read_b64_tr_b16 v[112:113], v150 offset:8192
	ds_read_b64_tr_b16 v[114:115], v150 offset:12288
	ds_read_b64_tr_b16 v[116:117], v151 offset:8192
	ds_read_b64_tr_b16 v[118:119], v151 offset:12288
	ds_read_b64_tr_b16 v[120:121], v152 offset:8192
	ds_read_b64_tr_b16 v[122:123], v152 offset:12288
	ds_read_b64_tr_b16 v[124:125], v153 offset:8192
	ds_read_b64_tr_b16 v[126:127], v153 offset:12288
	ds_read_b64_tr_b16 v[128:129], v154 offset:8192
	ds_read_b64_tr_b16 v[130:131], v154 offset:12288
	s_waitcnt lgkmcnt(12)
	v_mfma_f32_16x16x32_bf16 v[176:179], v[32:35], v[104:107], v[176:179]
	ds_read_b64_tr_b16 v[132:133], v155 offset:8192
	ds_read_b64_tr_b16 v[134:135], v155 offset:12288
	s_waitcnt lgkmcnt(12)
	v_mfma_f32_16x16x32_bf16 v[180:183], v[32:35], v[108:111], v[180:183]
	s_waitcnt lgkmcnt(10)
	v_mfma_f32_16x16x32_bf16 v[184:187], v[32:35], v[112:115], v[184:187]
	s_waitcnt lgkmcnt(8)
	v_mfma_f32_16x16x32_bf16 v[188:191], v[32:35], v[116:119], v[188:191]
	s_waitcnt lgkmcnt(6)
	v_mfma_f32_16x16x32_bf16 v[192:195], v[32:35], v[120:123], v[192:195]
	s_waitcnt lgkmcnt(4)
	v_mfma_f32_16x16x32_bf16 v[196:199], v[32:35], v[124:127], v[196:199]
	s_waitcnt lgkmcnt(2)
	v_mfma_f32_16x16x32_bf16 v[200:203], v[32:35], v[128:131], v[200:203]
	s_waitcnt lgkmcnt(0)
	v_mfma_f32_16x16x32_bf16 v[204:207], v[32:35], v[132:135], v[204:207]
	s_add_i32 s18, s14, 192
	s_mov_b64 s[16:17], s[4:5]
	v_add_u32_e32 v161, s18, v156
	ds_read_u16 v0, v161 offset:0
	ds_read_u16 v1, v161 offset:8
	ds_read_u16 v2, v161 offset:16
	ds_read_u16 v3, v161 offset:24
	ds_read_u16 v4, v161 offset:32
	ds_read_u16 v5, v161 offset:40
	ds_read_u16 v6, v161 offset:48
	ds_read_u16 v7, v161 offset:56
	s_waitcnt lgkmcnt(7)
	s_add_i32 m0, s8, 0x2000
	v_lshl_add_u32 v8, v0, 8, v10
	global_load_lds_dwordx4 v8, s[16:17]
	s_waitcnt lgkmcnt(6)
	s_add_i32 m0, s8, 0x2400
	v_lshl_add_u32 v9, v1, 8, v11
	global_load_lds_dwordx4 v9, s[16:17]
	s_waitcnt lgkmcnt(5)
	s_add_i32 m0, s8, 0x2800
	v_lshl_add_u32 v8, v2, 8, v12
	global_load_lds_dwordx4 v8, s[16:17]
	s_waitcnt lgkmcnt(4)
	s_add_i32 m0, s8, 0x2c00
	v_lshl_add_u32 v9, v3, 8, v13
	global_load_lds_dwordx4 v9, s[16:17]
	s_waitcnt lgkmcnt(3)
	s_add_i32 m0, s8, 0x3000
	v_lshl_add_u32 v8, v4, 8, v10
	global_load_lds_dwordx4 v8, s[16:17]
	s_waitcnt lgkmcnt(2)
	s_add_i32 m0, s8, 0x3400
	v_lshl_add_u32 v9, v5, 8, v11
	global_load_lds_dwordx4 v9, s[16:17]
	s_waitcnt lgkmcnt(1)
	s_add_i32 m0, s8, 0x3800
	v_lshl_add_u32 v8, v6, 8, v12
	global_load_lds_dwordx4 v8, s[16:17]
	s_waitcnt lgkmcnt(0)
	s_add_i32 m0, s8, 0x3c00
	v_lshl_add_u32 v9, v7, 8, v13
	global_load_lds_dwordx4 v9, s[16:17]
	s_waitcnt vmcnt(8)
	ds_read_b64_tr_b16 v[104:105], v148 offset:0
	ds_read_b64_tr_b16 v[106:107], v148 offset:4096
	ds_read_b64_tr_b16 v[108:109], v149 offset:0
	ds_read_b64_tr_b16 v[110:111], v149 offset:4096
	ds_read_b64_tr_b16 v[112:113], v150 offset:0
	ds_read_b64_tr_b16 v[114:115], v150 offset:4096
	ds_read_b64_tr_b16 v[116:117], v151 offset:0
	ds_read_b64_tr_b16 v[118:119], v151 offset:4096
	ds_read_b64_tr_b16 v[120:121], v152 offset:0
	ds_read_b64_tr_b16 v[122:123], v152 offset:4096
	ds_read_b64_tr_b16 v[124:125], v153 offset:0
	ds_read_b64_tr_b16 v[126:127], v153 offset:4096
	ds_read_b64_tr_b16 v[128:129], v154 offset:0
	ds_read_b64_tr_b16 v[130:131], v154 offset:4096
	s_waitcnt lgkmcnt(12)
	v_mfma_f32_16x16x32_bf16 v[176:179], v[40:43], v[104:107], v[176:179]
	ds_read_b64_tr_b16 v[132:133], v155 offset:0
	ds_read_b64_tr_b16 v[134:135], v155 offset:4096
	s_waitcnt lgkmcnt(12)
	v_mfma_f32_16x16x32_bf16 v[180:183], v[40:43], v[108:111], v[180:183]
	s_waitcnt lgkmcnt(10)
	v_mfma_f32_16x16x32_bf16 v[184:187], v[40:43], v[112:115], v[184:187]
	s_waitcnt lgkmcnt(8)
	v_mfma_f32_16x16x32_bf16 v[188:191], v[40:43], v[116:119], v[188:191]
	s_waitcnt lgkmcnt(6)
	v_mfma_f32_16x16x32_bf16 v[192:195], v[40:43], v[120:123], v[192:195]
	s_waitcnt lgkmcnt(4)
	v_mfma_f32_16x16x32_bf16 v[196:199], v[40:43], v[124:127], v[196:199]
	s_waitcnt lgkmcnt(2)
	v_mfma_f32_16x16x32_bf16 v[200:203], v[40:43], v[128:131], v[200:203]
	s_waitcnt lgkmcnt(0)
	v_mfma_f32_16x16x32_bf16 v[204:207], v[40:43], v[132:135], v[204:207]
	s_cmp_eq_u32 s11, 0
	s_cselect_b32 s18, 512, 0
	s_add_i32 s18, s18, s14
	s_mov_b64 s[16:17], s[2:3]
	v_add_u32_e32 v161, s18, v156
	ds_read_u16 v0, v161 offset:0
	ds_read_u16 v1, v161 offset:8
	ds_read_u16 v2, v161 offset:16
	ds_read_u16 v3, v161 offset:24
	ds_read_u16 v4, v161 offset:32
	ds_read_u16 v5, v161 offset:40
	ds_read_u16 v6, v161 offset:48
	ds_read_u16 v7, v161 offset:56
	s_waitcnt lgkmcnt(7)
	s_add_i32 m0, s8, 0x0
	v_lshl_add_u32 v8, v0, 8, v10
	global_load_lds_dwordx4 v8, s[16:17]
	s_waitcnt lgkmcnt(6)
	s_add_i32 m0, s8, 0x400
	v_lshl_add_u32 v9, v1, 8, v11
	global_load_lds_dwordx4 v9, s[16:17]
	s_waitcnt lgkmcnt(5)
	s_add_i32 m0, s8, 0x800
	v_lshl_add_u32 v8, v2, 8, v12
	global_load_lds_dwordx4 v8, s[16:17]
	s_waitcnt lgkmcnt(4)
	s_add_i32 m0, s8, 0xc00
	v_lshl_add_u32 v9, v3, 8, v13
	global_load_lds_dwordx4 v9, s[16:17]
	s_waitcnt lgkmcnt(3)
	s_add_i32 m0, s8, 0x1000
	v_lshl_add_u32 v8, v4, 8, v10
	global_load_lds_dwordx4 v8, s[16:17]
	s_waitcnt lgkmcnt(2)
	s_add_i32 m0, s8, 0x1400
	v_lshl_add_u32 v9, v5, 8, v11
	global_load_lds_dwordx4 v9, s[16:17]
	s_waitcnt lgkmcnt(1)
	s_add_i32 m0, s8, 0x1800
	v_lshl_add_u32 v8, v6, 8, v12
	global_load_lds_dwordx4 v8, s[16:17]
	s_waitcnt lgkmcnt(0)
	s_add_i32 m0, s8, 0x1c00
	v_lshl_add_u32 v9, v7, 8, v13
	global_load_lds_dwordx4 v9, s[16:17]
	s_waitcnt vmcnt(8)
	ds_read_b64_tr_b16 v[104:105], v148 offset:8192
	ds_read_b64_tr_b16 v[106:107], v148 offset:12288
	ds_read_b64_tr_b16 v[108:109], v149 offset:8192
	ds_read_b64_tr_b16 v[110:111], v149 offset:12288
	ds_read_b64_tr_b16 v[112:113], v150 offset:8192
	ds_read_b64_tr_b16 v[114:115], v150 offset:12288
	ds_read_b64_tr_b16 v[116:117], v151 offset:8192
	ds_read_b64_tr_b16 v[118:119], v151 offset:12288
	ds_read_b64_tr_b16 v[120:121], v152 offset:8192
	ds_read_b64_tr_b16 v[122:123], v152 offset:12288
	ds_read_b64_tr_b16 v[124:125], v153 offset:8192
	ds_read_b64_tr_b16 v[126:127], v153 offset:12288
	ds_read_b64_tr_b16 v[128:129], v154 offset:8192
	ds_read_b64_tr_b16 v[130:131], v154 offset:12288
	s_waitcnt lgkmcnt(12)
	v_mfma_f32_16x16x32_bf16 v[176:179], v[48:51], v[104:107], v[176:179]
	ds_read_b64_tr_b16 v[132:133], v155 offset:8192
	ds_read_b64_tr_b16 v[134:135], v155 offset:12288
	s_waitcnt lgkmcnt(12)
	v_mfma_f32_16x16x32_bf16 v[180:183], v[48:51], v[108:111], v[180:183]
	s_waitcnt lgkmcnt(10)
	v_mfma_f32_16x16x32_bf16 v[184:187], v[48:51], v[112:115], v[184:187]
	s_waitcnt lgkmcnt(8)
	v_mfma_f32_16x16x32_bf16 v[188:191], v[48:51], v[116:119], v[188:191]
	s_waitcnt lgkmcnt(6)
	v_mfma_f32_16x16x32_bf16 v[192:195], v[48:51], v[120:123], v[192:195]
	s_waitcnt lgkmcnt(4)
	v_mfma_f32_16x16x32_bf16 v[196:199], v[48:51], v[124:127], v[196:199]
	s_waitcnt lgkmcnt(2)
	v_mfma_f32_16x16x32_bf16 v[200:203], v[48:51], v[128:131], v[200:203]
	s_waitcnt lgkmcnt(0)
	v_mfma_f32_16x16x32_bf16 v[204:207], v[48:51], v[132:135], v[204:207]
	s_nop 7
	s_mov_b32 exec_lo, -1
	s_mov_b32 exec_hi, 0
	v_cvt_pk_bf16_f32 v165, v176, 0
	ds_write_b16 v158, v165 offset:0
	v_cvt_pk_bf16_f32 v166, v177, 0
	ds_write_b16 v158, v166 offset:256
	v_cvt_pk_bf16_f32 v167, v178, 0
	ds_write_b16 v158, v167 offset:512
	v_cvt_pk_bf16_f32 v168, v179, 0
	ds_write_b16 v158, v168 offset:768
	v_cvt_pk_bf16_f32 v165, v180, 0
	ds_write_b16 v158, v165 offset:32
	v_cvt_pk_bf16_f32 v166, v181, 0
	ds_write_b16 v158, v166 offset:288
	v_cvt_pk_bf16_f32 v167, v182, 0
	ds_write_b16 v158, v167 offset:544
	v_cvt_pk_bf16_f32 v168, v183, 0
	ds_write_b16 v158, v168 offset:800
	v_cvt_pk_bf16_f32 v165, v184, 0
	ds_write_b16 v158, v165 offset:64
	v_cvt_pk_bf16_f32 v166, v185, 0
	ds_write_b16 v158, v166 offset:320
	v_cvt_pk_bf16_f32 v167, v186, 0
	ds_write_b16 v158, v167 offset:576
	v_cvt_pk_bf16_f32 v168, v187, 0
	ds_write_b16 v158, v168 offset:832
	v_cvt_pk_bf16_f32 v165, v188, 0
	ds_write_b16 v158, v165 offset:96
	v_cvt_pk_bf16_f32 v166, v189, 0
	ds_write_b16 v158, v166 offset:352
	v_cvt_pk_bf16_f32 v167, v190, 0
	ds_write_b16 v158, v167 offset:608
	v_cvt_pk_bf16_f32 v168, v191, 0
	ds_write_b16 v158, v168 offset:864
	v_cvt_pk_bf16_f32 v165, v192, 0
	ds_write_b16 v158, v165 offset:128
	v_cvt_pk_bf16_f32 v166, v193, 0
	ds_write_b16 v158, v166 offset:384
	v_cvt_pk_bf16_f32 v167, v194, 0
	ds_write_b16 v158, v167 offset:640
	v_cvt_pk_bf16_f32 v168, v195, 0
	ds_write_b16 v158, v168 offset:896
	v_cvt_pk_bf16_f32 v165, v196, 0
	ds_write_b16 v158, v165 offset:160
	v_cvt_pk_bf16_f32 v166, v197, 0
	ds_write_b16 v158, v166 offset:416
	v_cvt_pk_bf16_f32 v167, v198, 0
	ds_write_b16 v158, v167 offset:672
	v_cvt_pk_bf16_f32 v168, v199, 0
	ds_write_b16 v158, v168 offset:928
	v_cvt_pk_bf16_f32 v165, v200, 0
	ds_write_b16 v158, v165 offset:192
	v_cvt_pk_bf16_f32 v166, v201, 0
	ds_write_b16 v158, v166 offset:448
	v_cvt_pk_bf16_f32 v167, v202, 0
	ds_write_b16 v158, v167 offset:704
	v_cvt_pk_bf16_f32 v168, v203, 0
	ds_write_b16 v158, v168 offset:960
	v_cvt_pk_bf16_f32 v165, v204, 0
	ds_write_b16 v158, v165 offset:224
	v_cvt_pk_bf16_f32 v166, v205, 0
	ds_write_b16 v158, v166 offset:480
	v_cvt_pk_bf16_f32 v167, v206, 0
	ds_write_b16 v158, v167 offset:736
	v_cvt_pk_bf16_f32 v168, v207, 0
	ds_write_b16 v158, v168 offset:992
	s_mov_b64 exec, -1
	s_waitcnt lgkmcnt(0)
	ds_read_b128 v[104:107], v159
	ds_read_b128 v[108:111], v159 offset:1024
	s_lshl_b32 s13, s12, 12
	v_add_u32_e32 v162, s13, v160
	s_waitcnt lgkmcnt(1)
	global_store_dwordx4 v162, v[104:107], s[6:7]
	s_waitcnt lgkmcnt(0)
	global_store_dwordx4 v162, v[108:111], s[6:7] offset:1024
	s_add_i32 s11, s11, 1
	s_add_i32 s12, s12, 1
	s_addk_i32 s14, 0x200
	s_cmp_lt_u32 s11, 2
	s_cbranch_scc1 .Lattn_q4
	s_branch .Lattn_done
.Lattn_q2:
	s_add_i32 s18, s14, 64
	s_mov_b64 s[16:17], s[2:3]
	v_add_u32_e32 v161, s18, v156
	ds_read_u16 v0, v161 offset:0
	ds_read_u16 v1, v161 offset:8
	ds_read_u16 v2, v161 offset:16
	ds_read_u16 v3, v161 offset:24
	ds_read_u16 v4, v161 offset:32
	ds_read_u16 v5, v161 offset:40
	ds_read_u16 v6, v161 offset:48
	ds_read_u16 v7, v161 offset:56
	s_waitcnt lgkmcnt(7)
	s_add_i32 m0, s8, 0x2000
	v_lshl_add_u32 v8, v0, 8, v10
	global_load_lds_dwordx4 v8, s[16:17]
	s_waitcnt lgkmcnt(6)
	s_add_i32 m0, s8, 0x2400
	v_lshl_add_u32 v9, v1, 8, v11
	global_load_lds_dwordx4 v9, s[16:17]
	s_waitcnt lgkmcnt(5)
	s_add_i32 m0, s8, 0x2800
	v_lshl_add_u32 v8, v2, 8, v12
	global_load_lds_dwordx4 v8, s[16:17]
	s_waitcnt lgkmcnt(4)
	s_add_i32 m0, s8, 0x2c00
	v_lshl_add_u32 v9, v3, 8, v13
	global_load_lds_dwordx4 v9, s[16:17]
	s_waitcnt lgkmcnt(3)
	s_add_i32 m0, s8, 0x3000
	v_lshl_add_u32 v8, v4, 8, v10
	global_load_lds_dwordx4 v8, s[16:17]
	s_waitcnt lgkmcnt(2)
	s_add_i32 m0, s8, 0x3400
	v_lshl_add_u32 v9, v5, 8, v11
	global_load_lds_dwordx4 v9, s[16:17]
	s_waitcnt lgkmcnt(1)
	s_add_i32 m0, s8, 0x3800
	v_lshl_add_u32 v8, v6, 8, v12
	global_load_lds_dwordx4 v8, s[16:17]
	s_waitcnt lgkmcnt(0)
	s_add_i32 m0, s8, 0x3c00
	v_lshl_add_u32 v9, v7, 8, v13
	global_load_lds_dwordx4 v9, s[16:17]
	s_waitcnt vmcnt(8)
	ds_read_b128 v[104:107], v18 offset:0
	ds_read_b128 v[108:111], v19 offset:0
	ds_read_b128 v[112:115], v20 offset:0
	ds_read_b128 v[116:119], v21 offset:0
	ds_read_b128 v[120:123], v18 offset:4096
	ds_read_b128 v[124:127], v19 offset:4096
	ds_read_b128 v[128:131], v20 offset:4096
	ds_read_b128 v[132:135], v21 offset:4096
	s_waitcnt lgkmcnt(7)
	v_mfma_f32_16x16x32_bf16 v[136:139], v[104:107], v[88:91], 0
	s_waitcnt lgkmcnt(6)
	v_mfma_f32_16x16x32_bf16 v[136:139], v[108:111], v[92:95], v[136:139]
	s_waitcnt lgkmcnt(5)
	v_mfma_f32_16x16x32_bf16 v[136:139], v[112:115], v[96:99], v[136:139]
	s_waitcnt lgkmcnt(4)
	v_mfma_f32_16x16x32_bf16 v[136:139], v[116:119], v[100:103], v[136:139]
	s_waitcnt lgkmcnt(3)
	v_mfma_f32_16x16x32_bf16 v[140:143], v[120:123], v[88:91], 0
	s_waitcnt lgkmcnt(2)
	v_mfma_f32_16x16x32_bf16 v[140:143], v[124:127], v[92:95], v[140:143]
	s_waitcnt lgkmcnt(1)
	v_mfma_f32_16x16x32_bf16 v[140:143], v[128:131], v[96:99], v[140:143]
	s_waitcnt lgkmcnt(0)
	v_mfma_f32_16x16x32_bf16 v[140:143], v[132:135], v[100:103], v[140:143]
	v_mul_f32_e32 v24, 0x3db504f3, v136
	v_mul_f32_e32 v25, 0x3db504f3, v137
	v_mul_f32_e32 v26, 0x3db504f3, v138
	v_mul_f32_e32 v27, 0x3db504f3, v139
	s_nop 3
	v_mul_f32_e32 v28, 0x3db504f3, v140
	v_mul_f32_e32 v29, 0x3db504f3, v141
	v_mul_f32_e32 v30, 0x3db504f3, v142
	v_mul_f32_e32 v31, 0x3db504f3, v143
	s_mov_b32 s18, s14
	s_mov_b64 s[16:17], s[4:5]
	v_add_u32_e32 v161, s18, v156
	ds_read_u16 v0, v161 offset:0
	ds_read_u16 v1, v161 offset:8
	ds_read_u16 v2, v161 offset:16
	ds_read_u16 v3, v161 offset:24
	ds_read_u16 v4, v161 offset:32
	ds_read_u16 v5, v161 offset:40
	ds_read_u16 v6, v161 offset:48
	ds_read_u16 v7, v161 offset:56
	s_waitcnt lgkmcnt(7)
	s_add_i32 m0, s8, 0x0
	v_lshl_add_u32 v8, v0, 8, v10
	global_load_lds_dwordx4 v8, s[16:17]
	s_waitcnt lgkmcnt(6)
	s_add_i32 m0, s8, 0x400
	v_lshl_add_u32 v9, v1, 8, v11
	global_load_lds_dwordx4 v9, s[16:17]
	s_waitcnt lgkmcnt(5)
	s_add_i32 m0, s8, 0x800
	v_lshl_add_u32 v8, v2, 8, v12
	global_load_lds_dwordx4 v8, s[16:17]
	s_waitcnt lgkmcnt(4)
	s_add_i32 m0, s8, 0xc00
	v_lshl_add_u32 v9, v3, 8, v13
	global_load_lds_dwordx4 v9, s[16:17]
	s_waitcnt lgkmcnt(3)
	s_add_i32 m0, s8, 0x1000
	v_lshl_add_u32 v8, v4, 8, v10
	global_load_lds_dwordx4 v8, s[16:17]
	s_waitcnt lgkmcnt(2)
	s_add_i32 m0, s8, 0x1400
	v_lshl_add_u32 v9, v5, 8, v11
	global_load_lds_dwordx4 v9, s[16:17]
	s_waitcnt lgkmcnt(1)
	s_add_i32 m0, s8, 0x1800
	v_lshl_add_u32 v8, v6, 8, v12
	global_load_lds_dwordx4 v8, s[16:17]
	s_waitcnt lgkmcnt(0)
	s_add_i32 m0, s8, 0x1c00
	v_lshl_add_u32 v9, v7, 8, v13
	global_load_lds_dwordx4 v9, s[16:17]
	s_waitcnt vmcnt(8)
	ds_read_b128 v[104:107], v18 offset:8192
	ds_read_b128 v[108:111], v19 offset:8192
	ds_read_b128 v[112:115], v20 offset:8192
	ds_read_b128 v[116:119], v21 offset:8192
	ds_read_b128 v[120:123], v18 offset:12288
	ds_read_b128 v[124:127], v19 offset:12288
	ds_read_b128 v[128:131], v20 offset:12288
	ds_read_b128 v[132:135], v21 offset:12288
	s_waitcnt lgkmcnt(7)
	v_mfma_f32_16x16x32_bf16 v[136:139], v[104:107], v[88:91], 0
	s_waitcnt lgkmcnt(6)
	v_mfma_f32_16x16x32_bf16 v[136:139], v[108:111], v[92:95], v[136:139]
	s_waitcnt lgkmcnt(5)
	v_mfma_f32_16x16x32_bf16 v[136:139], v[112:115], v[96:99], v[136:139]
	s_waitcnt lgkmcnt(4)
	v_mfma_f32_16x16x32_bf16 v[136:139], v[116:119], v[100:103], v[136:139]
	s_waitcnt lgkmcnt(3)
	v_mfma_f32_16x16x32_bf16 v[140:143], v[120:123], v[88:91], 0
	s_waitcnt lgkmcnt(2)
	v_mfma_f32_16x16x32_bf16 v[140:143], v[124:127], v[92:95], v[140:143]
	s_waitcnt lgkmcnt(1)
	v_mfma_f32_16x16x32_bf16 v[140:143], v[128:131], v[96:99], v[140:143]
	s_waitcnt lgkmcnt(0)
	v_mfma_f32_16x16x32_bf16 v[140:143], v[132:135], v[100:103], v[140:143]
	v_mul_f32_e32 v32, 0x3db504f3, v136
	v_mul_f32_e32 v33, 0x3db504f3, v137
	v_mul_f32_e32 v34, 0x3db504f3, v138
	v_mul_f32_e32 v35, 0x3db504f3, v139
	s_nop 3
	v_mul_f32_e32 v36, 0x3db504f3, v140
	v_mul_f32_e32 v37, 0x3db504f3, v141
	v_mul_f32_e32 v38, 0x3db504f3, v142
	v_mul_f32_e32 v39, 0x3db504f3, v143
	v_max3_f32 v163, v24, v25, v26
	v_max3_f32 v163, v163, v27, v28
	v_max3_f32 v163, v163, v29, v30
	v_max3_f32 v163, v163, v31, v32
	v_max3_f32 v163, v163, v33, v34
	v_max3_f32 v163, v163, v35, v36
	v_max3_f32 v163, v163, v37, v38
	v_max_f32_e32 v163, v163, v39
	s_nop 0
	ds_bpermute_b32 v165, v147, v163
	s_waitcnt lgkmcnt(0)
	v_max_f32_e32 v163, v163, v165
	s_nop 0
	ds_bpermute_b32 v165, v146, v163
	s_waitcnt lgkmcnt(0)
	v_max_f32_e32 v163, v163, v165
	v_sub_f32_e32 v165, v24, v163
	v_mul_f32_e32 v165, 0x3fb8aa3b, v165
	v_exp_f32_e32 v24, v165
	v_sub_f32_e32 v166, v25, v163
	v_mul_f32_e32 v166, 0x3fb8aa3b, v166
	v_exp_f32_e32 v25, v166
	v_sub_f32_e32 v167, v26, v163
	v_mul_f32_e32 v167, 0x3fb8aa3b, v167
	v_exp_f32_e32 v26, v167
	v_add_f32_e32 v164, 0, v24
	v_sub_f32_e32 v168, v27, v163
	v_mul_f32_e32 v168, 0x3fb8aa3b, v168
	v_exp_f32_e32 v27, v168
	v_add_f32_e32 v164, v164, v25
	v_sub_f32_e32 v165, v28, v163
	v_mul_f32_e32 v165, 0x3fb8aa3b, v165
	v_exp_f32_e32 v28, v165
	v_add_f32_e32 v164, v164, v26
	v_sub_f32_e32 v166, v29, v163
	v_mul_f32_e32 v166, 0x3fb8aa3b, v166
	v_exp_f32_e32 v29, v166
	v_add_f32_e32 v164, v164, v27
	v_sub_f32_e32 v167, v30, v163
	v_mul_f32_e32 v167, 0x3fb8aa3b, v167
	v_exp_f32_e32 v30, v167
	v_add_f32_e32 v164, v164, v28
	v_sub_f32_e32 v168, v31, v163
	v_mul_f32_e32 v168, 0x3fb8aa3b, v168
	v_exp_f32_e32 v31, v168
	v_add_f32_e32 v164, v164, v29
	v_sub_f32_e32 v165, v32, v163
	v_mul_f32_e32 v165, 0x3fb8aa3b, v165
	v_exp_f32_e32 v32, v165
	v_add_f32_e32 v164, v164, v30
	v_sub_f32_e32 v166, v33, v163
	v_mul_f32_e32 v166, 0x3fb8aa3b, v166
	v_exp_f32_e32 v33, v166
	v_add_f32_e32 v164, v164, v31
	v_sub_f32_e32 v167, v34, v163
	v_mul_f32_e32 v167, 0x3fb8aa3b, v167
	v_exp_f32_e32 v34, v167
	v_add_f32_e32 v164, v164, v32
	v_sub_f32_e32 v168, v35, v163
	v_mul_f32_e32 v168, 0x3fb8aa3b, v168
	v_exp_f32_e32 v35, v168
	v_add_f32_e32 v164, v164, v33
	v_sub_f32_e32 v165, v36, v163
	v_mul_f32_e32 v165, 0x3fb8aa3b, v165
	v_exp_f32_e32 v36, v165
	v_add_f32_e32 v164, v164, v34
	v_sub_f32_e32 v166, v37, v163
	v_mul_f32_e32 v166, 0x3fb8aa3b, v166
	v_exp_f32_e32 v37, v166
	v_add_f32_e32 v164, v164, v35
	v_sub_f32_e32 v167, v38, v163
	v_mul_f32_e32 v167, 0x3fb8aa3b, v167
	v_exp_f32_e32 v38, v167
	v_add_f32_e32 v164, v164, v36
	v_sub_f32_e32 v168, v39, v163
	v_mul_f32_e32 v168, 0x3fb8aa3b, v168
	v_exp_f32_e32 v39, v168
	v_add_f32_e32 v164, v164, v37
	s_nop 0
	v_add_f32_e32 v164, v164, v38
	v_add_f32_e32 v164, v164, v39
	s_nop 0
	ds_bpermute_b32 v165, v147, v164
	s_waitcnt lgkmcnt(0)
	v_add_f32_e32 v164, v164, v165
	s_nop 0
	ds_bpermute_b32 v165, v146, v164
	s_waitcnt lgkmcnt(0)
	v_add_f32_e32 v164, v164, v165
	v_div_scale_f32 v170, s[74:75], v164, v164, 1.0
	v_rcp_f32_e32 v171, v170
	s_nop 0
	v_fma_f32 v172, -v170, v171, 1.0
	v_fmac_f32_e32 v171, v172, v171
	v_div_scale_f32 v172, vcc, 1.0, v164, 1.0
	v_mul_f32_e32 v173, v172, v171
	v_fma_f32 v169, -v170, v173, v172
	v_fmac_f32_e32 v173, v169, v171
	v_fma_f32 v170, -v170, v173, v172
	v_div_fmas_f32 v170, v170, v171, v173
	v_div_fixup_f32 v169, v170, v164, 1.0
	v_mul_f32_e32 v165, v24, v169
	v_mul_f32_e32 v166, v25, v169
	v_cvt_pk_bf16_f32 v24, v165, v166
	v_mul_f32_e32 v167, v26, v169
	v_mul_f32_e32 v168, v27, v169
	v_cvt_pk_bf16_f32 v25, v167, v168
	v_mul_f32_e32 v165, v28, v169
	v_mul_f32_e32 v166, v29, v169
	v_cvt_pk_bf16_f32 v26, v165, v166
	v_mul_f32_e32 v167, v30, v169
	v_mul_f32_e32 v168, v31, v169
	v_cvt_pk_bf16_f32 v27, v167, v168
	v_mul_f32_e32 v165, v32, v169
	v_mul_f32_e32 v166, v33, v169
	v_cvt_pk_bf16_f32 v32, v165, v166
	v_mul_f32_e32 v167, v34, v169
	v_mul_f32_e32 v168, v35, v169
	v_cvt_pk_bf16_f32 v33, v167, v168
	v_mul_f32_e32 v165, v36, v169
	v_mul_f32_e32 v166, v37, v169
	v_cvt_pk_bf16_f32 v34, v165, v166
	v_mul_f32_e32 v167, v38, v169
	v_mul_f32_e32 v168, v39, v169
	v_cvt_pk_bf16_f32 v35, v167, v168
	s_cmp_eq_u32 s11, 0
	s_cselect_b32 s15, 1, 0
	s_add_i32 s15, s15, s12
	s_lshl_b32 s13, s15, 12
	v_add_u32_e32 v162, s13, v157
	global_load_dwordx4 v[88:91], v162, s[6:7] offset:0
	global_load_dwordx4 v[92:95], v162, s[6:7] offset:64
	global_load_dwordx4 v[96:99], v162, s[6:7] offset:128
	global_load_dwordx4 v[100:103], v162, s[6:7] offset:192
	s_add_i32 s18, s14, 64
	s_mov_b64 s[16:17], s[4:5]
	v_add_u32_e32 v161, s18, v156
	ds_read_u16 v0, v161 offset:0
	ds_read_u16 v1, v161 offset:8
	ds_read_u16 v2, v161 offset:16
	ds_read_u16 v3, v161 offset:24
	ds_read_u16 v4, v161 offset:32
	ds_read_u16 v5, v161 offset:40
	ds_read_u16 v6, v161 offset:48
	ds_read_u16 v7, v161 offset:56
	s_waitcnt lgkmcnt(7)
	s_add_i32 m0, s8, 0x2000
	v_lshl_add_u32 v8, v0, 8, v10
	global_load_lds_dwordx4 v8, s[16:17]
	s_waitcnt lgkmcnt(6)
	s_add_i32 m0, s8, 0x2400
	v_lshl_add_u32 v9, v1, 8, v11
	global_load_lds_dwordx4 v9, s[16:17]
	s_waitcnt lgkmcnt(5)
	s_add_i32 m0, s8, 0x2800
	v_lshl_add_u32 v8, v2, 8, v12
	global_load_lds_dwordx4 v8, s[16:17]
	s_waitcnt lgkmcnt(4)
	s_add_i32 m0, s8, 0x2c00
	v_lshl_add_u32 v9, v3, 8, v13
	global_load_lds_dwordx4 v9, s[16:17]
	s_waitcnt lgkmcnt(3)
	s_add_i32 m0, s8, 0x3000
	v_lshl_add_u32 v8, v4, 8, v10
	global_load_lds_dwordx4 v8, s[16:17]
	s_waitcnt lgkmcnt(2)
	s_add_i32 m0, s8, 0x3400
	v_lshl_add_u32 v9, v5, 8, v11
	global_load_lds_dwordx4 v9, s[16:17]
	s_waitcnt lgkmcnt(1)
	s_add_i32 m0, s8, 0x3800
	v_lshl_add_u32 v8, v6, 8, v12
	global_load_lds_dwordx4 v8, s[16:17]
	s_waitcnt lgkmcnt(0)
	s_add_i32 m0, s8, 0x3c00
	v_lshl_add_u32 v9, v7, 8, v13
	global_load_lds_dwordx4 v9, s[16:17]
	s_waitcnt vmcnt(8)
	ds_read_b64_tr_b16 v[104:105], v148 offset:0
	ds_read_b64_tr_b16 v[106:107], v148 offset:4096
	ds_read_b64_tr_b16 v[108:109], v149 offset:0
	ds_read_b64_tr_b16 v[110:111], v149 offset:4096
	ds_read_b64_tr_b16 v[112:113], v150 offset:0
	ds_read_b64_tr_b16 v[114:115], v150 offset:4096
	ds_read_b64_tr_b16 v[116:117], v151 offset:0
	ds_read_b64_tr_b16 v[118:119], v151 offset:4096
	ds_read_b64_tr_b16 v[120:121], v152 offset:0
	ds_read_b64_tr_b16 v[122:123], v152 offset:4096
	ds_read_b64_tr_b16 v[124:125], v153 offset:0
	ds_read_b64_tr_b16 v[126:127], v153 offset:4096
	ds_read_b64_tr_b16 v[128:129], v154 offset:0
	ds_read_b64_tr_b16 v[130:131], v154 offset:4096
	s_waitcnt lgkmcnt(12)
	v_mfma_f32_16x16x32_bf16 v[176:179], v[24:27], v[104:107], 0
	ds_read_b64_tr_b16 v[132:133], v155 offset:0
	ds_read_b64_tr_b16 v[134:135], v155 offset:4096
	s_waitcnt lgkmcnt(12)
	v_mfma_f32_16x16x32_bf16 v[180:183], v[24:27], v[108:111], 0
	s_waitcnt lgkmcnt(10)
	v_mfma_f32_16x16x32_bf16 v[184:187], v[24:27], v[112:115], 0
	s_waitcnt lgkmcnt(8)
	v_mfma_f32_16x16x32_bf16 v[188:191], v[24:27], v[116:119], 0
	s_waitcnt lgkmcnt(6)
	v_mfma_f32_16x16x32_bf16 v[192:195], v[24:27], v[120:123], 0
	s_waitcnt lgkmcnt(4)
	v_mfma_f32_16x16x32_bf16 v[196:199], v[24:27], v[124:127], 0
	s_waitcnt lgkmcnt(2)
	v_mfma_f32_16x16x32_bf16 v[200:203], v[24:27], v[128:131], 0
	s_waitcnt lgkmcnt(0)
	v_mfma_f32_16x16x32_bf16 v[204:207], v[24:27], v[132:135], 0
	s_cmp_eq_u32 s11, 0
	s_cselect_b32 s18, 512, 0
	s_add_i32 s18, s18, s14
	s_mov_b64 s[16:17], s[2:3]
	v_add_u32_e32 v161, s18, v156
	ds_read_u16 v0, v161 offset:0
	ds_read_u16 v1, v161 offset:8
	ds_read_u16 v2, v161 offset:16
	ds_read_u16 v3, v161 offset:24
	ds_read_u16 v4, v161 offset:32
	ds_read_u16 v5, v161 offset:40
	ds_read_u16 v6, v161 offset:48
	ds_read_u16 v7, v161 offset:56
	s_waitcnt lgkmcnt(7)
	s_add_i32 m0, s8, 0x0
	v_lshl_add_u32 v8, v0, 8, v10
	global_load_lds_dwordx4 v8, s[16:17]
	s_waitcnt lgkmcnt(6)
	s_add_i32 m0, s8, 0x400
	v_lshl_add_u32 v9, v1, 8, v11
	global_load_lds_dwordx4 v9, s[16:17]
	s_waitcnt lgkmcnt(5)
	s_add_i32 m0, s8, 0x800
	v_lshl_add_u32 v8, v2, 8, v12
	global_load_lds_dwordx4 v8, s[16:17]
	s_waitcnt lgkmcnt(4)
	s_add_i32 m0, s8, 0xc00
	v_lshl_add_u32 v9, v3, 8, v13
	global_load_lds_dwordx4 v9, s[16:17]
	s_waitcnt lgkmcnt(3)
	s_add_i32 m0, s8, 0x1000
	v_lshl_add_u32 v8, v4, 8, v10
	global_load_lds_dwordx4 v8, s[16:17]
	s_waitcnt lgkmcnt(2)
	s_add_i32 m0, s8, 0x1400
	v_lshl_add_u32 v9, v5, 8, v11
	global_load_lds_dwordx4 v9, s[16:17]
	s_waitcnt lgkmcnt(1)
	s_add_i32 m0, s8, 0x1800
	v_lshl_add_u32 v8, v6, 8, v12
	global_load_lds_dwordx4 v8, s[16:17]
	s_waitcnt lgkmcnt(0)
	s_add_i32 m0, s8, 0x1c00
	v_lshl_add_u32 v9, v7, 8, v13
	global_load_lds_dwordx4 v9, s[16:17]
	s_waitcnt vmcnt(8)
	ds_read_b64_tr_b16 v[104:105], v148 offset:8192
	ds_read_b64_tr_b16 v[106:107], v148 offset:12288
	ds_read_b64_tr_b16 v[108:109], v149 offset:8192
	ds_read_b64_tr_b16 v[110:111], v149 offset:12288
	ds_read_b64_tr_b16 v[112:113], v150 offset:8192
	ds_read_b64_tr_b16 v[114:115], v150 offset:12288
	ds_read_b64_tr_b16 v[116:117], v151 offset:8192
	ds_read_b64_tr_b16 v[118:119], v151 offset:12288
	ds_read_b64_tr_b16 v[120:121], v152 offset:8192
	ds_read_b64_tr_b16 v[122:123], v152 offset:12288
	ds_read_b64_tr_b16 v[124:125], v153 offset:8192
	ds_read_b64_tr_b16 v[126:127], v153 offset:12288
	ds_read_b64_tr_b16 v[128:129], v154 offset:8192
	ds_read_b64_tr_b16 v[130:131], v154 offset:12288
	s_waitcnt lgkmcnt(12)
	v_mfma_f32_16x16x32_bf16 v[176:179], v[32:35], v[104:107], v[176:179]
	ds_read_b64_tr_b16 v[132:133], v155 offset:8192
	ds_read_b64_tr_b16 v[134:135], v155 offset:12288
	s_waitcnt lgkmcnt(12)
	v_mfma_f32_16x16x32_bf16 v[180:183], v[32:35], v[108:111], v[180:183]
	s_waitcnt lgkmcnt(10)
	v_mfma_f32_16x16x32_bf16 v[184:187], v[32:35], v[112:115], v[184:187]
	s_waitcnt lgkmcnt(8)
	v_mfma_f32_16x16x32_bf16 v[188:191], v[32:35], v[116:119], v[188:191]
	s_waitcnt lgkmcnt(6)
	v_mfma_f32_16x16x32_bf16 v[192:195], v[32:35], v[120:123], v[192:195]
	s_waitcnt lgkmcnt(4)
	v_mfma_f32_16x16x32_bf16 v[196:199], v[32:35], v[124:127], v[196:199]
	s_waitcnt lgkmcnt(2)
	v_mfma_f32_16x16x32_bf16 v[200:203], v[32:35], v[128:131], v[200:203]
	s_waitcnt lgkmcnt(0)
	v_mfma_f32_16x16x32_bf16 v[204:207], v[32:35], v[132:135], v[204:207]
	s_nop 7
	s_mov_b32 exec_lo, -1
	s_mov_b32 exec_hi, 0
	v_cvt_pk_bf16_f32 v165, v176, 0
	ds_write_b16 v158, v165 offset:0
	v_cvt_pk_bf16_f32 v166, v177, 0
	ds_write_b16 v158, v166 offset:256
	v_cvt_pk_bf16_f32 v167, v178, 0
	ds_write_b16 v158, v167 offset:512
	v_cvt_pk_bf16_f32 v168, v179, 0
	ds_write_b16 v158, v168 offset:768
	v_cvt_pk_bf16_f32 v165, v180, 0
	ds_write_b16 v158, v165 offset:32
	v_cvt_pk_bf16_f32 v166, v181, 0
	ds_write_b16 v158, v166 offset:288
	v_cvt_pk_bf16_f32 v167, v182, 0
	ds_write_b16 v158, v167 offset:544
	v_cvt_pk_bf16_f32 v168, v183, 0
	ds_write_b16 v158, v168 offset:800
	v_cvt_pk_bf16_f32 v165, v184, 0
	ds_write_b16 v158, v165 offset:64
	v_cvt_pk_bf16_f32 v166, v185, 0
	ds_write_b16 v158, v166 offset:320
	v_cvt_pk_bf16_f32 v167, v186, 0
	ds_write_b16 v158, v167 offset:576
	v_cvt_pk_bf16_f32 v168, v187, 0
	ds_write_b16 v158, v168 offset:832
	v_cvt_pk_bf16_f32 v165, v188, 0
	ds_write_b16 v158, v165 offset:96
	v_cvt_pk_bf16_f32 v166, v189, 0
	ds_write_b16 v158, v166 offset:352
	v_cvt_pk_bf16_f32 v167, v190, 0
	ds_write_b16 v158, v167 offset:608
	v_cvt_pk_bf16_f32 v168, v191, 0
	ds_write_b16 v158, v168 offset:864
	v_cvt_pk_bf16_f32 v165, v192, 0
	ds_write_b16 v158, v165 offset:128
	v_cvt_pk_bf16_f32 v166, v193, 0
	ds_write_b16 v158, v166 offset:384
	v_cvt_pk_bf16_f32 v167, v194, 0
	ds_write_b16 v158, v167 offset:640
	v_cvt_pk_bf16_f32 v168, v195, 0
	ds_write_b16 v158, v168 offset:896
	v_cvt_pk_bf16_f32 v165, v196, 0
	ds_write_b16 v158, v165 offset:160
	v_cvt_pk_bf16_f32 v166, v197, 0
	ds_write_b16 v158, v166 offset:416
	v_cvt_pk_bf16_f32 v167, v198, 0
	ds_write_b16 v158, v167 offset:672
	v_cvt_pk_bf16_f32 v168, v199, 0
	ds_write_b16 v158, v168 offset:928
	v_cvt_pk_bf16_f32 v165, v200, 0
	ds_write_b16 v158, v165 offset:192
	v_cvt_pk_bf16_f32 v166, v201, 0
	ds_write_b16 v158, v166 offset:448
	v_cvt_pk_bf16_f32 v167, v202, 0
	ds_write_b16 v158, v167 offset:704
	v_cvt_pk_bf16_f32 v168, v203, 0
	ds_write_b16 v158, v168 offset:960
	v_cvt_pk_bf16_f32 v165, v204, 0
	ds_write_b16 v158, v165 offset:224
	v_cvt_pk_bf16_f32 v166, v205, 0
	ds_write_b16 v158, v166 offset:480
	v_cvt_pk_bf16_f32 v167, v206, 0
	ds_write_b16 v158, v167 offset:736
	v_cvt_pk_bf16_f32 v168, v207, 0
	ds_write_b16 v158, v168 offset:992
	s_mov_b64 exec, -1
	s_waitcnt lgkmcnt(0)
	ds_read_b128 v[104:107], v159
	ds_read_b128 v[108:111], v159 offset:1024
	s_lshl_b32 s13, s12, 12
	v_add_u32_e32 v162, s13, v160
	s_waitcnt lgkmcnt(1)
	global_store_dwordx4 v162, v[104:107], s[6:7]
	s_waitcnt lgkmcnt(0)
	global_store_dwordx4 v162, v[108:111], s[6:7] offset:1024
	s_add_i32 s11, s11, 1
	s_add_i32 s12, s12, 1
	s_addk_i32 s14, 0x200
	s_cmp_lt_u32 s11, 2
	s_cbranch_scc1 .Lattn_q2
	s_branch .Lattn_done
.Lattn_done:
	s_waitcnt vmcnt(0)
	s_branch .LBB0_185
